# MFMA order O9: each super-phase's 32 MFMAs merged, same-accumulator k0/k1 back-to-back, pairs grouped by A fragment (src1 re-read by 4 consecutive pairs); middle setprio pair dropped
# speedup vs baseline: 1.0157x; 1.0069x over previous
.LBB0_170:
	ds_read_b128 v[136:139], v191
	ds_read_b128 v[158:161], v191 offset:1024
	ds_read_b128 v[162:165], v191 offset:2048
	ds_read_b128 v[166:169], v191 offset:3072
	ds_read_b128 v[170:173], v192
	ds_read_b128 v[174:177], v192 offset:1024
	ds_read_b128 v[178:181], v192 offset:2048
	ds_read_b128 v[194:197], v192 offset:3072
	s_add_u32 s0, s42, 0xfff00080
	s_addc_u32 s50, s43, -1
	s_cmp_eq_u32 s70, 60
	s_cselect_b32 s53, s23, s50
	s_cselect_b32 s52, s41, s0
	s_cselect_b32 s51, s21, s68
	s_cselect_b32 s50, s66, s67
	s_add_i32 m0, s31, 0xc000
	ds_read_b128 v[198:201], v193
	ds_read_b128 v[202:205], v193 offset:1024
	ds_read_b128 v[206:209], v193 offset:2048
	ds_read_b128 v[210:213], v193 offset:3072
	ds_read_b128 v[214:217], v193 offset:4096
	ds_read_b128 v[218:221], v193 offset:5120
	ds_read_b128 v[222:225], v193 offset:6144
	ds_read_b128 v[226:229], v193 offset:7168
	global_load_lds_dwordx4 v152, s[42:43]
	s_add_i32 m0, s31, 0xe000
	s_nop 0
	global_load_lds_dwordx4 v154, s[42:43]
	s_waitcnt vmcnt(8)
	s_waitcnt lgkmcnt(0)
	s_setprio 1
	s_barrier
	v_mfma_f32_16x16x32_bf16 v[132:135], v[136:139], v[198:201], v[132:135]
	v_mfma_f32_16x16x32_bf16 v[132:135], v[158:161], v[202:205], v[132:135]
	v_mfma_f32_16x16x32_bf16 v[128:131], v[162:165], v[198:201], v[128:131]
	v_mfma_f32_16x16x32_bf16 v[128:131], v[166:169], v[202:205], v[128:131]
	v_mfma_f32_16x16x32_bf16 v[124:127], v[170:173], v[198:201], v[124:127]
	v_mfma_f32_16x16x32_bf16 v[124:127], v[174:177], v[202:205], v[124:127]
	v_mfma_f32_16x16x32_bf16 v[120:123], v[178:181], v[198:201], v[120:123]
	v_mfma_f32_16x16x32_bf16 v[120:123], v[194:197], v[202:205], v[120:123]
	v_mfma_f32_16x16x32_bf16 v[116:119], v[136:139], v[206:209], v[116:119]
	v_mfma_f32_16x16x32_bf16 v[116:119], v[158:161], v[210:213], v[116:119]
	v_mfma_f32_16x16x32_bf16 v[112:115], v[162:165], v[206:209], v[112:115]
	v_mfma_f32_16x16x32_bf16 v[112:115], v[166:169], v[210:213], v[112:115]
	v_mfma_f32_16x16x32_bf16 v[108:111], v[170:173], v[206:209], v[108:111]
	v_mfma_f32_16x16x32_bf16 v[108:111], v[174:177], v[210:213], v[108:111]
	v_mfma_f32_16x16x32_bf16 v[104:107], v[178:181], v[206:209], v[104:107]
	v_mfma_f32_16x16x32_bf16 v[104:107], v[194:197], v[210:213], v[104:107]
	v_mfma_f32_16x16x32_bf16 v[100:103], v[136:139], v[214:217], v[100:103]
	v_mfma_f32_16x16x32_bf16 v[100:103], v[158:161], v[218:221], v[100:103]
	v_mfma_f32_16x16x32_bf16 v[96:99], v[162:165], v[214:217], v[96:99]
	v_mfma_f32_16x16x32_bf16 v[96:99], v[166:169], v[218:221], v[96:99]
	v_mfma_f32_16x16x32_bf16 v[92:95], v[170:173], v[214:217], v[92:95]
	v_mfma_f32_16x16x32_bf16 v[92:95], v[174:177], v[218:221], v[92:95]
	v_mfma_f32_16x16x32_bf16 v[88:91], v[178:181], v[214:217], v[88:91]
	v_mfma_f32_16x16x32_bf16 v[88:91], v[194:197], v[218:221], v[88:91]
	v_mfma_f32_16x16x32_bf16 v[84:87], v[136:139], v[222:225], v[84:87]
	v_mfma_f32_16x16x32_bf16 v[84:87], v[158:161], v[226:229], v[84:87]
	v_mfma_f32_16x16x32_bf16 v[80:83], v[162:165], v[222:225], v[80:83]
	v_mfma_f32_16x16x32_bf16 v[80:83], v[166:169], v[226:229], v[80:83]
	v_mfma_f32_16x16x32_bf16 v[76:79], v[170:173], v[222:225], v[76:79]
	v_mfma_f32_16x16x32_bf16 v[76:79], v[174:177], v[226:229], v[76:79]
	v_mfma_f32_16x16x32_bf16 v[72:75], v[178:181], v[222:225], v[72:75]
	v_mfma_f32_16x16x32_bf16 v[72:75], v[194:197], v[226:229], v[72:75]
	s_setprio 0
	s_barrier
	s_add_i32 s0, s61, s19
	s_mov_b32 m0, s0
	ds_read_b128 v[198:201], v193 offset:16384
	ds_read_b128 v[202:205], v193 offset:17408
	ds_read_b128 v[206:209], v193 offset:18432
	ds_read_b128 v[210:213], v193 offset:19456
	ds_read_b128 v[214:217], v193 offset:20480
	ds_read_b128 v[218:221], v193 offset:21504
	ds_read_b128 v[222:225], v193 offset:22528
	ds_read_b128 v[226:229], v193 offset:23552
	global_load_lds_dwordx4 v142, s[50:51]
	s_add_i32 m0, s0, 0x2000
	s_add_u32 s72, s50, 0x100000
	s_addc_u32 s73, s51, 0
	s_add_i32 s0, s62, s19
	global_load_lds_dwordx4 v146, s[50:51]
	s_mov_b32 m0, s0
	s_nop 0
	global_load_lds_dwordx4 v142, s[72:73]
	s_add_i32 m0, s0, 0x2000
	s_nop 0
	global_load_lds_dwordx4 v146, s[72:73]
	s_mov_b32 m0, s31
	s_nop 0
	global_load_lds_dwordx4 v140, s[52:53]
	s_mov_b32 m0, s35
	s_nop 0
	global_load_lds_dwordx4 v144, s[52:53]
	s_waitcnt vmcnt(8)
	s_waitcnt lgkmcnt(0)
	s_setprio 1
	s_barrier
	v_mfma_f32_16x16x32_bf16 v[68:71], v[136:139], v[198:201], v[68:71]
	v_mfma_f32_16x16x32_bf16 v[68:71], v[158:161], v[202:205], v[68:71]
	v_mfma_f32_16x16x32_bf16 v[64:67], v[162:165], v[198:201], v[64:67]
	v_mfma_f32_16x16x32_bf16 v[64:67], v[166:169], v[202:205], v[64:67]
	v_mfma_f32_16x16x32_bf16 v[60:63], v[170:173], v[198:201], v[60:63]
	v_mfma_f32_16x16x32_bf16 v[60:63], v[174:177], v[202:205], v[60:63]
	v_mfma_f32_16x16x32_bf16 v[56:59], v[178:181], v[198:201], v[56:59]
	v_mfma_f32_16x16x32_bf16 v[56:59], v[194:197], v[202:205], v[56:59]
	v_mfma_f32_16x16x32_bf16 v[52:55], v[136:139], v[206:209], v[52:55]
	v_mfma_f32_16x16x32_bf16 v[52:55], v[158:161], v[210:213], v[52:55]
	v_mfma_f32_16x16x32_bf16 v[48:51], v[162:165], v[206:209], v[48:51]
	v_mfma_f32_16x16x32_bf16 v[48:51], v[166:169], v[210:213], v[48:51]
	v_mfma_f32_16x16x32_bf16 v[44:47], v[170:173], v[206:209], v[44:47]
	v_mfma_f32_16x16x32_bf16 v[44:47], v[174:177], v[210:213], v[44:47]
	v_mfma_f32_16x16x32_bf16 v[40:43], v[178:181], v[206:209], v[40:43]
	v_mfma_f32_16x16x32_bf16 v[40:43], v[194:197], v[210:213], v[40:43]
	v_mfma_f32_16x16x32_bf16 v[36:39], v[136:139], v[214:217], v[36:39]
	v_mfma_f32_16x16x32_bf16 v[36:39], v[158:161], v[218:221], v[36:39]
	v_mfma_f32_16x16x32_bf16 v[32:35], v[162:165], v[214:217], v[32:35]
	v_mfma_f32_16x16x32_bf16 v[32:35], v[166:169], v[218:221], v[32:35]
	v_mfma_f32_16x16x32_bf16 v[28:31], v[170:173], v[214:217], v[28:31]
	v_mfma_f32_16x16x32_bf16 v[28:31], v[174:177], v[218:221], v[28:31]
	v_mfma_f32_16x16x32_bf16 v[24:27], v[178:181], v[214:217], v[24:27]
	v_mfma_f32_16x16x32_bf16 v[24:27], v[194:197], v[218:221], v[24:27]
	v_mfma_f32_16x16x32_bf16 v[20:23], v[136:139], v[222:225], v[20:23]
	v_mfma_f32_16x16x32_bf16 v[20:23], v[158:161], v[226:229], v[20:23]
	v_mfma_f32_16x16x32_bf16 v[16:19], v[162:165], v[222:225], v[16:19]
	v_mfma_f32_16x16x32_bf16 v[16:19], v[166:169], v[226:229], v[16:19]
	v_mfma_f32_16x16x32_bf16 v[12:15], v[170:173], v[222:225], v[12:15]
	v_mfma_f32_16x16x32_bf16 v[12:15], v[174:177], v[226:229], v[12:15]
	v_mfma_f32_16x16x32_bf16 v[6:9], v[178:181], v[222:225], v[8:11]
	v_mfma_f32_16x16x32_bf16 v[6:9], v[194:197], v[226:229], v[6:9]
	s_setprio 0
	s_barrier
	s_add_i32 s0, 0, 0x18000
	v_add_u32_e32 v5, s0, v1
	s_add_i32 s71, 0, 0x1c000
	ds_read_b128 v[136:139], v5
	ds_read_b128 v[158:161], v5 offset:1024
	ds_read_b128 v[162:165], v5 offset:2048
	ds_read_b128 v[166:169], v5 offset:3072
	v_add_u32_e32 v5, s71, v1
	ds_read_b128 v[170:173], v5
	ds_read_b128 v[174:177], v5 offset:1024
	ds_read_b128 v[178:181], v5 offset:2048
	ds_read_b128 v[194:197], v5 offset:3072
	s_add_u32 s98, s52, 0x100000
	s_addc_u32 s99, s53, 0
	s_mov_b32 m0, s45
	ds_read_b128 v[198:201], v193 offset:32768
	ds_read_b128 v[202:205], v193 offset:33792
	ds_read_b128 v[206:209], v193 offset:34816
	ds_read_b128 v[210:213], v193 offset:35840
	ds_read_b128 v[214:217], v193 offset:36864
	ds_read_b128 v[218:221], v193 offset:37888
	ds_read_b128 v[222:225], v193 offset:38912
	ds_read_b128 v[226:229], v193 offset:39936
	global_load_lds_dwordx4 v140, s[98:99]
	s_mov_b32 m0, s46
	s_nop 0
	global_load_lds_dwordx4 v144, s[98:99]
	s_waitcnt vmcnt(8)
	s_waitcnt lgkmcnt(0)
	s_setprio 1
	s_barrier
	v_mfma_f32_16x16x32_bf16 v[132:135], v[136:139], v[198:201], v[132:135]
	v_mfma_f32_16x16x32_bf16 v[132:135], v[158:161], v[202:205], v[132:135]
	v_mfma_f32_16x16x32_bf16 v[128:131], v[162:165], v[198:201], v[128:131]
	v_mfma_f32_16x16x32_bf16 v[128:131], v[166:169], v[202:205], v[128:131]
	v_mfma_f32_16x16x32_bf16 v[124:127], v[170:173], v[198:201], v[124:127]
	v_mfma_f32_16x16x32_bf16 v[124:127], v[174:177], v[202:205], v[124:127]
	v_mfma_f32_16x16x32_bf16 v[120:123], v[178:181], v[198:201], v[120:123]
	v_mfma_f32_16x16x32_bf16 v[120:123], v[194:197], v[202:205], v[120:123]
	v_mfma_f32_16x16x32_bf16 v[116:119], v[136:139], v[206:209], v[116:119]
	v_mfma_f32_16x16x32_bf16 v[116:119], v[158:161], v[210:213], v[116:119]
	v_mfma_f32_16x16x32_bf16 v[112:115], v[162:165], v[206:209], v[112:115]
	v_mfma_f32_16x16x32_bf16 v[112:115], v[166:169], v[210:213], v[112:115]
	v_mfma_f32_16x16x32_bf16 v[108:111], v[170:173], v[206:209], v[108:111]
	v_mfma_f32_16x16x32_bf16 v[108:111], v[174:177], v[210:213], v[108:111]
	v_mfma_f32_16x16x32_bf16 v[104:107], v[178:181], v[206:209], v[104:107]
	v_mfma_f32_16x16x32_bf16 v[104:107], v[194:197], v[210:213], v[104:107]
	v_mfma_f32_16x16x32_bf16 v[100:103], v[136:139], v[214:217], v[100:103]
	v_mfma_f32_16x16x32_bf16 v[100:103], v[158:161], v[218:221], v[100:103]
	v_mfma_f32_16x16x32_bf16 v[96:99], v[162:165], v[214:217], v[96:99]
	v_mfma_f32_16x16x32_bf16 v[96:99], v[166:169], v[218:221], v[96:99]
	v_mfma_f32_16x16x32_bf16 v[92:95], v[170:173], v[214:217], v[92:95]
	v_mfma_f32_16x16x32_bf16 v[92:95], v[174:177], v[218:221], v[92:95]
	v_mfma_f32_16x16x32_bf16 v[88:91], v[178:181], v[214:217], v[88:91]
	v_mfma_f32_16x16x32_bf16 v[88:91], v[194:197], v[218:221], v[88:91]
	v_mfma_f32_16x16x32_bf16 v[84:87], v[136:139], v[222:225], v[84:87]
	v_mfma_f32_16x16x32_bf16 v[84:87], v[158:161], v[226:229], v[84:87]
	v_mfma_f32_16x16x32_bf16 v[80:83], v[162:165], v[222:225], v[80:83]
	v_mfma_f32_16x16x32_bf16 v[80:83], v[166:169], v[226:229], v[80:83]
	v_mfma_f32_16x16x32_bf16 v[76:79], v[170:173], v[222:225], v[76:79]
	v_mfma_f32_16x16x32_bf16 v[76:79], v[174:177], v[226:229], v[76:79]
	v_mfma_f32_16x16x32_bf16 v[72:75], v[178:181], v[222:225], v[72:75]
	v_mfma_f32_16x16x32_bf16 v[72:75], v[194:197], v[226:229], v[72:75]
	s_setprio 0
	s_barrier
	s_add_i32 s0, s0, s19
	s_add_i32 m0, s0, 0xffffff80
	ds_read_b128 v[198:201], v193 offset:49152
	ds_read_b128 v[202:205], v193 offset:50176
	ds_read_b128 v[206:209], v193 offset:51200
	ds_read_b128 v[210:213], v193 offset:52224
	ds_read_b128 v[214:217], v193 offset:53248
	ds_read_b128 v[218:221], v193 offset:54272
	ds_read_b128 v[222:225], v193 offset:55296
	ds_read_b128 v[226:229], v193 offset:56320
	global_load_lds_dwordx4 v142, s[50:51] offset:128
	s_add_i32 m0, s0, 0x1f80
	s_add_i32 s0, s71, s19
	global_load_lds_dwordx4 v146, s[50:51] offset:128
	s_add_u32 s50, s50, 0x100080
	s_addc_u32 s51, s51, 0
	s_mov_b32 m0, s0
	s_nop 0
	global_load_lds_dwordx4 v142, s[50:51]
	s_add_i32 m0, s0, 0x2000
	s_nop 0
	global_load_lds_dwordx4 v146, s[50:51]
	s_add_i32 m0, s56, 0xffffff80
	s_nop 0
	global_load_lds_dwordx4 v140, s[52:53] offset:128
	s_add_i32 m0, s57, 0xffffff80
	s_nop 0
	global_load_lds_dwordx4 v144, s[52:53] offset:128
	s_waitcnt vmcnt(8)
	s_waitcnt lgkmcnt(0)
	s_setprio 1
	s_barrier
	v_mfma_f32_16x16x32_bf16 v[68:71], v[136:139], v[198:201], v[68:71]
	v_mfma_f32_16x16x32_bf16 v[68:71], v[158:161], v[202:205], v[68:71]
	v_mfma_f32_16x16x32_bf16 v[64:67], v[162:165], v[198:201], v[64:67]
	v_mfma_f32_16x16x32_bf16 v[64:67], v[166:169], v[202:205], v[64:67]
	v_mfma_f32_16x16x32_bf16 v[60:63], v[170:173], v[198:201], v[60:63]
	v_mfma_f32_16x16x32_bf16 v[60:63], v[174:177], v[202:205], v[60:63]
	v_mfma_f32_16x16x32_bf16 v[56:59], v[178:181], v[198:201], v[56:59]
	v_mfma_f32_16x16x32_bf16 v[56:59], v[194:197], v[202:205], v[56:59]
	v_mfma_f32_16x16x32_bf16 v[52:55], v[136:139], v[206:209], v[52:55]
	v_mfma_f32_16x16x32_bf16 v[52:55], v[158:161], v[210:213], v[52:55]
	v_mfma_f32_16x16x32_bf16 v[48:51], v[162:165], v[206:209], v[48:51]
	v_mfma_f32_16x16x32_bf16 v[48:51], v[166:169], v[210:213], v[48:51]
	v_mfma_f32_16x16x32_bf16 v[44:47], v[170:173], v[206:209], v[44:47]
	v_mfma_f32_16x16x32_bf16 v[44:47], v[174:177], v[210:213], v[44:47]
	v_mfma_f32_16x16x32_bf16 v[40:43], v[178:181], v[206:209], v[40:43]
	v_mfma_f32_16x16x32_bf16 v[40:43], v[194:197], v[210:213], v[40:43]
	v_mfma_f32_16x16x32_bf16 v[36:39], v[136:139], v[214:217], v[36:39]
	v_mfma_f32_16x16x32_bf16 v[36:39], v[158:161], v[218:221], v[36:39]
	v_mfma_f32_16x16x32_bf16 v[32:35], v[162:165], v[214:217], v[32:35]
	v_mfma_f32_16x16x32_bf16 v[32:35], v[166:169], v[218:221], v[32:35]
	v_mfma_f32_16x16x32_bf16 v[28:31], v[170:173], v[214:217], v[28:31]
	v_mfma_f32_16x16x32_bf16 v[28:31], v[174:177], v[218:221], v[28:31]
	v_mfma_f32_16x16x32_bf16 v[24:27], v[178:181], v[214:217], v[24:27]
	v_mfma_f32_16x16x32_bf16 v[24:27], v[194:197], v[218:221], v[24:27]
	v_mfma_f32_16x16x32_bf16 v[20:23], v[136:139], v[222:225], v[20:23]
	v_mfma_f32_16x16x32_bf16 v[20:23], v[158:161], v[226:229], v[20:23]
	v_mfma_f32_16x16x32_bf16 v[16:19], v[162:165], v[222:225], v[16:19]
	v_mfma_f32_16x16x32_bf16 v[16:19], v[166:169], v[226:229], v[16:19]
	v_mfma_f32_16x16x32_bf16 v[10:13], v[170:173], v[222:225], v[12:15]
	v_mfma_f32_16x16x32_bf16 v[12:15], v[174:177], v[226:229], v[10:13]
	v_mfma_f32_16x16x32_bf16 v[6:9], v[178:181], v[222:225], v[6:9]
	v_mfma_f32_16x16x32_bf16 v[8:11], v[194:197], v[226:229], v[6:9]
	s_setprio 0
	s_barrier
	s_add_i32 s70, s70, 2
	s_add_u32 s42, s42, 0x100
	s_addc_u32 s43, s43, 0
	s_add_u32 s67, s67, 0x100
	s_addc_u32 s68, s68, 0
	s_cmp_gt_u32 s70, 61
	s_cbranch_scc0 .LBB0_170
	s_and_b64 vcc, exec, s[16:17]
	s_cbranch_vccz .LBB0_173
	s_barrier

.LBB0_342:
	ds_read_b128 v[132:135], v209
	ds_read_b128 v[136:139], v209 offset:1024
	ds_read_b128 v[140:143], v209 offset:2048
	ds_read_b128 v[144:147], v209 offset:3072
	ds_read_b128 v[148:151], v210
	ds_read_b128 v[152:155], v210 offset:1024
	ds_read_b128 v[156:159], v210 offset:2048
	ds_read_b128 v[160:163], v210 offset:3072
	s_add_u32 s0, s26, 0xffd50080
	s_addc_u32 s28, s27, -1
	s_cmpk_eq_i32 s62, 0xa8
	s_cselect_b32 s31, s7, s28
	s_cselect_b32 s30, s6, s0
	s_cselect_b32 s29, s25, s61
	s_cselect_b32 s28, s24, s60
	s_add_i32 m0, s43, 0xc000
	ds_read_b128 v[164:167], v211
	ds_read_b128 v[168:171], v211 offset:1024
	ds_read_b128 v[172:175], v211 offset:2048
	ds_read_b128 v[176:179], v211 offset:3072
	ds_read_b128 v[196:199], v211 offset:4096
	ds_read_b128 v[200:203], v211 offset:5120
	ds_read_b128 v[204:207], v211 offset:6144
	ds_read_b128 v[214:217], v211 offset:7168
	global_load_lds_dwordx4 v188, s[26:27]
	s_add_i32 m0, s43, 0xe000
	s_nop 0
	global_load_lds_dwordx4 v190, s[26:27]
	s_waitcnt vmcnt(8)
	s_waitcnt lgkmcnt(0)
	s_setprio 1
	s_barrier
	v_mfma_f32_16x16x32_bf16 v[128:131], v[132:135], v[164:167], v[128:131]
	v_mfma_f32_16x16x32_bf16 v[128:131], v[136:139], v[168:171], v[128:131]
	v_mfma_f32_16x16x32_bf16 v[124:127], v[140:143], v[164:167], v[124:127]
	v_mfma_f32_16x16x32_bf16 v[124:127], v[144:147], v[168:171], v[124:127]
	v_mfma_f32_16x16x32_bf16 v[120:123], v[148:151], v[164:167], v[120:123]
	v_mfma_f32_16x16x32_bf16 v[120:123], v[152:155], v[168:171], v[120:123]
	v_mfma_f32_16x16x32_bf16 v[116:119], v[156:159], v[164:167], v[116:119]
	v_mfma_f32_16x16x32_bf16 v[116:119], v[160:163], v[168:171], v[116:119]
	v_mfma_f32_16x16x32_bf16 v[112:115], v[132:135], v[172:175], v[112:115]
	v_mfma_f32_16x16x32_bf16 v[112:115], v[136:139], v[176:179], v[112:115]
	v_mfma_f32_16x16x32_bf16 v[108:111], v[140:143], v[172:175], v[108:111]
	v_mfma_f32_16x16x32_bf16 v[108:111], v[144:147], v[176:179], v[108:111]
	v_mfma_f32_16x16x32_bf16 v[104:107], v[148:151], v[172:175], v[104:107]
	v_mfma_f32_16x16x32_bf16 v[104:107], v[152:155], v[176:179], v[104:107]
	v_mfma_f32_16x16x32_bf16 v[100:103], v[156:159], v[172:175], v[100:103]
	v_mfma_f32_16x16x32_bf16 v[100:103], v[160:163], v[176:179], v[100:103]
	v_mfma_f32_16x16x32_bf16 v[96:99], v[132:135], v[196:199], v[96:99]
	v_mfma_f32_16x16x32_bf16 v[96:99], v[136:139], v[200:203], v[96:99]
	v_mfma_f32_16x16x32_bf16 v[92:95], v[140:143], v[196:199], v[92:95]
	v_mfma_f32_16x16x32_bf16 v[92:95], v[144:147], v[200:203], v[92:95]
	v_mfma_f32_16x16x32_bf16 v[88:91], v[148:151], v[196:199], v[88:91]
	v_mfma_f32_16x16x32_bf16 v[88:91], v[152:155], v[200:203], v[88:91]
	v_mfma_f32_16x16x32_bf16 v[84:87], v[156:159], v[196:199], v[84:87]
	v_mfma_f32_16x16x32_bf16 v[84:87], v[160:163], v[200:203], v[84:87]
	v_mfma_f32_16x16x32_bf16 v[80:83], v[132:135], v[204:207], v[80:83]
	v_mfma_f32_16x16x32_bf16 v[80:83], v[136:139], v[214:217], v[80:83]
	v_mfma_f32_16x16x32_bf16 v[76:79], v[140:143], v[204:207], v[76:79]
	v_mfma_f32_16x16x32_bf16 v[76:79], v[144:147], v[214:217], v[76:79]
	v_mfma_f32_16x16x32_bf16 v[72:75], v[148:151], v[204:207], v[72:75]
	v_mfma_f32_16x16x32_bf16 v[72:75], v[152:155], v[214:217], v[72:75]
	v_mfma_f32_16x16x32_bf16 v[68:71], v[156:159], v[204:207], v[68:71]
	v_mfma_f32_16x16x32_bf16 v[68:71], v[160:163], v[214:217], v[68:71]
	s_setprio 0
	s_barrier
	s_add_i32 s0, s53, s42
	s_mov_b32 m0, s0
	ds_read_b128 v[164:167], v211 offset:16384
	ds_read_b128 v[168:171], v211 offset:17408
	ds_read_b128 v[172:175], v211 offset:18432
	ds_read_b128 v[176:179], v211 offset:19456
	ds_read_b128 v[196:199], v211 offset:20480
	ds_read_b128 v[200:203], v211 offset:21504
	ds_read_b128 v[204:207], v211 offset:22528
	ds_read_b128 v[214:217], v211 offset:23552
	global_load_lds_dwordx4 v182, s[28:29]
	s_add_i32 m0, s0, 0x2000
	s_add_u32 s64, s28, 0x2b0000
	s_addc_u32 s65, s29, 0
	s_add_i32 s0, s54, s42
	global_load_lds_dwordx4 v186, s[28:29]
	s_mov_b32 m0, s0
	s_nop 0
	global_load_lds_dwordx4 v182, s[64:65]
	s_add_i32 m0, s0, 0x2000
	s_nop 0
	global_load_lds_dwordx4 v186, s[64:65]
	s_mov_b32 m0, s43
	s_nop 0
	global_load_lds_dwordx4 v180, s[30:31]
	s_mov_b32 m0, s45
	s_nop 0
	global_load_lds_dwordx4 v184, s[30:31]
	s_waitcnt vmcnt(8)
	s_waitcnt lgkmcnt(0)
	s_setprio 1
	s_barrier
	v_mfma_f32_16x16x32_bf16 v[64:67], v[132:135], v[164:167], v[64:67]
	v_mfma_f32_16x16x32_bf16 v[64:67], v[136:139], v[168:171], v[64:67]
	v_mfma_f32_16x16x32_bf16 v[60:63], v[140:143], v[164:167], v[60:63]
	v_mfma_f32_16x16x32_bf16 v[60:63], v[144:147], v[168:171], v[60:63]
	v_mfma_f32_16x16x32_bf16 v[56:59], v[148:151], v[164:167], v[56:59]
	v_mfma_f32_16x16x32_bf16 v[56:59], v[152:155], v[168:171], v[56:59]
	v_mfma_f32_16x16x32_bf16 v[52:55], v[156:159], v[164:167], v[52:55]
	v_mfma_f32_16x16x32_bf16 v[52:55], v[160:163], v[168:171], v[52:55]
	v_mfma_f32_16x16x32_bf16 v[48:51], v[132:135], v[172:175], v[48:51]
	v_mfma_f32_16x16x32_bf16 v[48:51], v[136:139], v[176:179], v[48:51]
	v_mfma_f32_16x16x32_bf16 v[44:47], v[140:143], v[172:175], v[44:47]
	v_mfma_f32_16x16x32_bf16 v[44:47], v[144:147], v[176:179], v[44:47]
	v_mfma_f32_16x16x32_bf16 v[40:43], v[148:151], v[172:175], v[40:43]
	v_mfma_f32_16x16x32_bf16 v[40:43], v[152:155], v[176:179], v[40:43]
	v_mfma_f32_16x16x32_bf16 v[36:39], v[156:159], v[172:175], v[36:39]
	v_mfma_f32_16x16x32_bf16 v[36:39], v[160:163], v[176:179], v[36:39]
	v_mfma_f32_16x16x32_bf16 v[32:35], v[132:135], v[196:199], v[32:35]
	v_mfma_f32_16x16x32_bf16 v[32:35], v[136:139], v[200:203], v[32:35]
	v_mfma_f32_16x16x32_bf16 v[28:31], v[140:143], v[196:199], v[28:31]
	v_mfma_f32_16x16x32_bf16 v[28:31], v[144:147], v[200:203], v[28:31]
	v_mfma_f32_16x16x32_bf16 v[24:27], v[148:151], v[196:199], v[24:27]
	v_mfma_f32_16x16x32_bf16 v[24:27], v[152:155], v[200:203], v[24:27]
	v_mfma_f32_16x16x32_bf16 v[20:23], v[156:159], v[196:199], v[20:23]
	v_mfma_f32_16x16x32_bf16 v[20:23], v[160:163], v[200:203], v[20:23]
	v_mfma_f32_16x16x32_bf16 v[16:19], v[132:135], v[204:207], v[16:19]
	v_mfma_f32_16x16x32_bf16 v[16:19], v[136:139], v[214:217], v[16:19]
	v_mfma_f32_16x16x32_bf16 v[12:15], v[140:143], v[204:207], v[12:15]
	v_mfma_f32_16x16x32_bf16 v[12:15], v[144:147], v[214:217], v[12:15]
	v_mfma_f32_16x16x32_bf16 v[8:11], v[148:151], v[204:207], v[8:11]
	v_mfma_f32_16x16x32_bf16 v[8:11], v[152:155], v[214:217], v[8:11]
	v_mfma_f32_16x16x32_bf16 v[4:7], v[156:159], v[204:207], v[4:7]
	v_mfma_f32_16x16x32_bf16 v[4:7], v[160:163], v[214:217], v[4:7]
	s_setprio 0
	s_barrier
	s_add_i32 s0, 0, 0x18000
	s_add_i32 s63, 0, 0x1c000
	v_add_u32_e32 v144, s0, v3
	v_add_u32_e32 v160, s63, v3
	ds_read_b128 v[132:135], v144
	ds_read_b128 v[136:139], v144 offset:1024
	ds_read_b128 v[140:143], v144 offset:2048
	ds_read_b128 v[144:147], v144 offset:3072
	ds_read_b128 v[148:151], v160
	ds_read_b128 v[152:155], v160 offset:1024
	ds_read_b128 v[156:159], v160 offset:2048
	ds_read_b128 v[160:163], v160 offset:3072
	s_add_u32 s98, s30, 0x2b0000
	s_addc_u32 s99, s31, 0
	s_mov_b32 m0, s46
	ds_read_b128 v[164:167], v211 offset:32768
	ds_read_b128 v[168:171], v211 offset:33792
	ds_read_b128 v[172:175], v211 offset:34816
	ds_read_b128 v[176:179], v211 offset:35840
	ds_read_b128 v[196:199], v211 offset:36864
	ds_read_b128 v[200:203], v211 offset:37888
	ds_read_b128 v[204:207], v211 offset:38912
	ds_read_b128 v[214:217], v211 offset:39936
	global_load_lds_dwordx4 v180, s[98:99]
	s_mov_b32 m0, s47
	s_nop 0
	global_load_lds_dwordx4 v184, s[98:99]
	s_waitcnt vmcnt(8)
	s_waitcnt lgkmcnt(0)
	s_setprio 1
	s_barrier
	v_mfma_f32_16x16x32_bf16 v[128:131], v[132:135], v[164:167], v[128:131]
	v_mfma_f32_16x16x32_bf16 v[128:131], v[136:139], v[168:171], v[128:131]
	v_mfma_f32_16x16x32_bf16 v[124:127], v[140:143], v[164:167], v[124:127]
	v_mfma_f32_16x16x32_bf16 v[124:127], v[144:147], v[168:171], v[124:127]
	v_mfma_f32_16x16x32_bf16 v[120:123], v[148:151], v[164:167], v[120:123]
	v_mfma_f32_16x16x32_bf16 v[120:123], v[152:155], v[168:171], v[120:123]
	v_mfma_f32_16x16x32_bf16 v[116:119], v[156:159], v[164:167], v[116:119]
	v_mfma_f32_16x16x32_bf16 v[116:119], v[160:163], v[168:171], v[116:119]
	v_mfma_f32_16x16x32_bf16 v[112:115], v[132:135], v[172:175], v[112:115]
	v_mfma_f32_16x16x32_bf16 v[112:115], v[136:139], v[176:179], v[112:115]
	v_mfma_f32_16x16x32_bf16 v[108:111], v[140:143], v[172:175], v[108:111]
	v_mfma_f32_16x16x32_bf16 v[108:111], v[144:147], v[176:179], v[108:111]
	v_mfma_f32_16x16x32_bf16 v[104:107], v[148:151], v[172:175], v[104:107]
	v_mfma_f32_16x16x32_bf16 v[104:107], v[152:155], v[176:179], v[104:107]
	v_mfma_f32_16x16x32_bf16 v[100:103], v[156:159], v[172:175], v[100:103]
	v_mfma_f32_16x16x32_bf16 v[100:103], v[160:163], v[176:179], v[100:103]
	v_mfma_f32_16x16x32_bf16 v[96:99], v[132:135], v[196:199], v[96:99]
	v_mfma_f32_16x16x32_bf16 v[96:99], v[136:139], v[200:203], v[96:99]
	v_mfma_f32_16x16x32_bf16 v[92:95], v[140:143], v[196:199], v[92:95]
	v_mfma_f32_16x16x32_bf16 v[92:95], v[144:147], v[200:203], v[92:95]
	v_mfma_f32_16x16x32_bf16 v[88:91], v[148:151], v[196:199], v[88:91]
	v_mfma_f32_16x16x32_bf16 v[88:91], v[152:155], v[200:203], v[88:91]
	v_mfma_f32_16x16x32_bf16 v[84:87], v[156:159], v[196:199], v[84:87]
	v_mfma_f32_16x16x32_bf16 v[84:87], v[160:163], v[200:203], v[84:87]
	v_mfma_f32_16x16x32_bf16 v[80:83], v[132:135], v[204:207], v[80:83]
	v_mfma_f32_16x16x32_bf16 v[80:83], v[136:139], v[214:217], v[80:83]
	v_mfma_f32_16x16x32_bf16 v[76:79], v[140:143], v[204:207], v[76:79]
	v_mfma_f32_16x16x32_bf16 v[76:79], v[144:147], v[214:217], v[76:79]
	v_mfma_f32_16x16x32_bf16 v[72:75], v[148:151], v[204:207], v[72:75]
	v_mfma_f32_16x16x32_bf16 v[72:75], v[152:155], v[214:217], v[72:75]
	v_mfma_f32_16x16x32_bf16 v[68:71], v[156:159], v[204:207], v[68:71]
	v_mfma_f32_16x16x32_bf16 v[68:71], v[160:163], v[214:217], v[68:71]
	s_setprio 0
	s_barrier
	s_add_i32 s0, s0, s42
	s_add_i32 m0, s0, 0xffffff80
	ds_read_b128 v[164:167], v211 offset:49152
	ds_read_b128 v[168:171], v211 offset:50176
	ds_read_b128 v[172:175], v211 offset:51200
	ds_read_b128 v[176:179], v211 offset:52224
	ds_read_b128 v[196:199], v211 offset:53248
	ds_read_b128 v[200:203], v211 offset:54272
	ds_read_b128 v[204:207], v211 offset:55296
	ds_read_b128 v[214:217], v211 offset:56320
	global_load_lds_dwordx4 v182, s[28:29] offset:128
	s_add_i32 m0, s0, 0x1f80
	s_add_i32 s0, s63, s42
	global_load_lds_dwordx4 v186, s[28:29] offset:128
	s_add_u32 s28, s28, 0x2b0080
	s_addc_u32 s29, s29, 0
	s_mov_b32 m0, s0
	s_nop 0
	global_load_lds_dwordx4 v182, s[28:29]
	s_add_i32 m0, s0, 0x2000
	s_nop 0
	global_load_lds_dwordx4 v186, s[28:29]
	s_add_i32 m0, s51, 0xffffff80
	s_nop 0
	global_load_lds_dwordx4 v180, s[30:31] offset:128
	s_add_i32 m0, s52, 0xffffff80
	s_nop 0
	global_load_lds_dwordx4 v184, s[30:31] offset:128
	s_waitcnt vmcnt(8)
	s_waitcnt lgkmcnt(0)
	s_setprio 1
	s_barrier
	v_mfma_f32_16x16x32_bf16 v[64:67], v[132:135], v[164:167], v[64:67]
	v_mfma_f32_16x16x32_bf16 v[64:67], v[136:139], v[168:171], v[64:67]
	v_mfma_f32_16x16x32_bf16 v[60:63], v[140:143], v[164:167], v[60:63]
	v_mfma_f32_16x16x32_bf16 v[60:63], v[144:147], v[168:171], v[60:63]
	v_mfma_f32_16x16x32_bf16 v[56:59], v[148:151], v[164:167], v[56:59]
	v_mfma_f32_16x16x32_bf16 v[56:59], v[152:155], v[168:171], v[56:59]
	v_mfma_f32_16x16x32_bf16 v[52:55], v[156:159], v[164:167], v[52:55]
	v_mfma_f32_16x16x32_bf16 v[52:55], v[160:163], v[168:171], v[52:55]
	v_mfma_f32_16x16x32_bf16 v[48:51], v[132:135], v[172:175], v[48:51]
	v_mfma_f32_16x16x32_bf16 v[48:51], v[136:139], v[176:179], v[48:51]
	v_mfma_f32_16x16x32_bf16 v[44:47], v[140:143], v[172:175], v[44:47]
	v_mfma_f32_16x16x32_bf16 v[44:47], v[144:147], v[176:179], v[44:47]
	v_mfma_f32_16x16x32_bf16 v[40:43], v[148:151], v[172:175], v[40:43]
	v_mfma_f32_16x16x32_bf16 v[40:43], v[152:155], v[176:179], v[40:43]
	v_mfma_f32_16x16x32_bf16 v[36:39], v[156:159], v[172:175], v[36:39]
	v_mfma_f32_16x16x32_bf16 v[36:39], v[160:163], v[176:179], v[36:39]
	v_mfma_f32_16x16x32_bf16 v[32:35], v[132:135], v[196:199], v[32:35]
	v_mfma_f32_16x16x32_bf16 v[32:35], v[136:139], v[200:203], v[32:35]
	v_mfma_f32_16x16x32_bf16 v[28:31], v[140:143], v[196:199], v[28:31]
	v_mfma_f32_16x16x32_bf16 v[28:31], v[144:147], v[200:203], v[28:31]
	v_mfma_f32_16x16x32_bf16 v[24:27], v[148:151], v[196:199], v[24:27]
	v_mfma_f32_16x16x32_bf16 v[24:27], v[152:155], v[200:203], v[24:27]
	v_mfma_f32_16x16x32_bf16 v[20:23], v[156:159], v[196:199], v[20:23]
	v_mfma_f32_16x16x32_bf16 v[20:23], v[160:163], v[200:203], v[20:23]
	v_mfma_f32_16x16x32_bf16 v[16:19], v[132:135], v[204:207], v[16:19]
	v_mfma_f32_16x16x32_bf16 v[16:19], v[136:139], v[214:217], v[16:19]
	v_mfma_f32_16x16x32_bf16 v[12:15], v[140:143], v[204:207], v[12:15]
	v_mfma_f32_16x16x32_bf16 v[12:15], v[144:147], v[214:217], v[12:15]
	v_mfma_f32_16x16x32_bf16 v[8:11], v[148:151], v[204:207], v[8:11]
	v_mfma_f32_16x16x32_bf16 v[8:11], v[152:155], v[214:217], v[8:11]
	v_mfma_f32_16x16x32_bf16 v[4:7], v[156:159], v[204:207], v[4:7]
	v_mfma_f32_16x16x32_bf16 v[4:7], v[160:163], v[214:217], v[4:7]
	s_setprio 0
	s_barrier
	s_add_i32 s62, s62, 2
	s_add_u32 s26, s26, 0x100
	s_addc_u32 s27, s27, 0
	s_add_u32 s60, s60, 0x100
	s_addc_u32 s61, s61, 0
	s_cmpk_gt_u32 s62, 0xa9
	s_cbranch_scc0 .LBB0_342
	s_and_b64 vcc, exec, s[22:23]
	s_cbranch_vccz .LBB0_345
	s_barrier

.LBB0_429:
	ds_read_b128 v[150:153], v156
	ds_read_b128 v[162:165], v156 offset:1024
	ds_read_b128 v[166:169], v156 offset:2048
	ds_read_b128 v[170:173], v156 offset:3072
	ds_read_b128 v[174:177], v157
	ds_read_b128 v[178:181], v157 offset:1024
	ds_read_b128 v[182:185], v157 offset:2048
	ds_read_b128 v[186:189], v157 offset:3072
	s_add_u32 s0, s50, 0xfff00080
	s_addc_u32 s52, s51, -1
	s_cmp_eq_u32 s72, 60
	s_cselect_b32 s55, s27, s52
	s_cselect_b32 s54, s67, s0
	s_cselect_b32 s53, s25, s71
	s_cselect_b32 s52, s68, s70
	s_add_i32 m0, s43, 0xc000
	ds_read_b128 v[190:193], v158
	ds_read_b128 v[194:197], v158 offset:1024
	ds_read_b128 v[198:201], v158 offset:2048
	ds_read_b128 v[202:205], v158 offset:3072
	ds_read_b128 v[206:209], v158 offset:4096
	ds_read_b128 v[210:213], v158 offset:5120
	ds_read_b128 v[214:217], v158 offset:6144
	ds_read_b128 v[218:221], v158 offset:7168
	global_load_lds_dwordx4 v142, s[50:51]
	s_add_i32 m0, s43, 0xe000
	s_nop 0
	global_load_lds_dwordx4 v144, s[50:51]
	s_waitcnt vmcnt(8)
	s_waitcnt lgkmcnt(0)
	s_setprio 1
	s_barrier
	v_mfma_f32_16x16x32_bf16 v[128:131], v[150:153], v[190:193], v[128:131]
	v_mfma_f32_16x16x32_bf16 v[128:131], v[162:165], v[194:197], v[128:131]
	v_mfma_f32_16x16x32_bf16 v[124:127], v[166:169], v[190:193], v[124:127]
	v_mfma_f32_16x16x32_bf16 v[124:127], v[170:173], v[194:197], v[124:127]
	v_mfma_f32_16x16x32_bf16 v[120:123], v[174:177], v[190:193], v[120:123]
	v_mfma_f32_16x16x32_bf16 v[120:123], v[178:181], v[194:197], v[120:123]
	v_mfma_f32_16x16x32_bf16 v[116:119], v[182:185], v[190:193], v[116:119]
	v_mfma_f32_16x16x32_bf16 v[116:119], v[186:189], v[194:197], v[116:119]
	v_mfma_f32_16x16x32_bf16 v[112:115], v[150:153], v[198:201], v[112:115]
	v_mfma_f32_16x16x32_bf16 v[112:115], v[162:165], v[202:205], v[112:115]
	v_mfma_f32_16x16x32_bf16 v[108:111], v[166:169], v[198:201], v[108:111]
	v_mfma_f32_16x16x32_bf16 v[108:111], v[170:173], v[202:205], v[108:111]
	v_mfma_f32_16x16x32_bf16 v[104:107], v[174:177], v[198:201], v[104:107]
	v_mfma_f32_16x16x32_bf16 v[104:107], v[178:181], v[202:205], v[104:107]
	v_mfma_f32_16x16x32_bf16 v[100:103], v[182:185], v[198:201], v[100:103]
	v_mfma_f32_16x16x32_bf16 v[100:103], v[186:189], v[202:205], v[100:103]
	v_mfma_f32_16x16x32_bf16 v[96:99], v[150:153], v[206:209], v[96:99]
	v_mfma_f32_16x16x32_bf16 v[96:99], v[162:165], v[210:213], v[96:99]
	v_mfma_f32_16x16x32_bf16 v[92:95], v[166:169], v[206:209], v[92:95]
	v_mfma_f32_16x16x32_bf16 v[92:95], v[170:173], v[210:213], v[92:95]
	v_mfma_f32_16x16x32_bf16 v[88:91], v[174:177], v[206:209], v[88:91]
	v_mfma_f32_16x16x32_bf16 v[88:91], v[178:181], v[210:213], v[88:91]
	v_mfma_f32_16x16x32_bf16 v[84:87], v[182:185], v[206:209], v[84:87]
	v_mfma_f32_16x16x32_bf16 v[84:87], v[186:189], v[210:213], v[84:87]
	v_mfma_f32_16x16x32_bf16 v[80:83], v[150:153], v[214:217], v[80:83]
	v_mfma_f32_16x16x32_bf16 v[80:83], v[162:165], v[218:221], v[80:83]
	v_mfma_f32_16x16x32_bf16 v[76:79], v[166:169], v[214:217], v[76:79]
	v_mfma_f32_16x16x32_bf16 v[76:79], v[170:173], v[218:221], v[76:79]
	v_mfma_f32_16x16x32_bf16 v[72:75], v[174:177], v[214:217], v[72:75]
	v_mfma_f32_16x16x32_bf16 v[72:75], v[178:181], v[218:221], v[72:75]
	v_mfma_f32_16x16x32_bf16 v[68:71], v[182:185], v[214:217], v[68:71]
	v_mfma_f32_16x16x32_bf16 v[68:71], v[186:189], v[218:221], v[68:71]
	s_setprio 0
	s_barrier
	s_add_i32 s0, s62, s41
	s_mov_b32 m0, s0
	ds_read_b128 v[190:193], v158 offset:16384
	ds_read_b128 v[194:197], v158 offset:17408
	ds_read_b128 v[198:201], v158 offset:18432
	ds_read_b128 v[202:205], v158 offset:19456
	ds_read_b128 v[206:209], v158 offset:20480
	ds_read_b128 v[210:213], v158 offset:21504
	ds_read_b128 v[214:217], v158 offset:22528
	ds_read_b128 v[218:221], v158 offset:23552
	global_load_lds_dwordx4 v136, s[52:53]
	s_add_i32 m0, s0, 0x2000
	s_add_u32 s74, s52, 0x100000
	s_addc_u32 s75, s53, 0
	s_add_i32 s0, s63, s41
	global_load_lds_dwordx4 v140, s[52:53]
	s_mov_b32 m0, s0
	s_nop 0
	global_load_lds_dwordx4 v136, s[74:75]
	s_add_i32 m0, s0, 0x2000
	s_nop 0
	global_load_lds_dwordx4 v140, s[74:75]
	s_mov_b32 m0, s43
	s_nop 0
	global_load_lds_dwordx4 v134, s[54:55]
	s_mov_b32 m0, s48
	s_nop 0
	global_load_lds_dwordx4 v138, s[54:55]
	s_waitcnt vmcnt(8)
	s_waitcnt lgkmcnt(0)
	s_setprio 1
	s_barrier
	v_mfma_f32_16x16x32_bf16 v[64:67], v[150:153], v[190:193], v[64:67]
	v_mfma_f32_16x16x32_bf16 v[64:67], v[162:165], v[194:197], v[64:67]
	v_mfma_f32_16x16x32_bf16 v[60:63], v[166:169], v[190:193], v[60:63]
	v_mfma_f32_16x16x32_bf16 v[60:63], v[170:173], v[194:197], v[60:63]
	v_mfma_f32_16x16x32_bf16 v[56:59], v[174:177], v[190:193], v[56:59]
	v_mfma_f32_16x16x32_bf16 v[56:59], v[178:181], v[194:197], v[56:59]
	v_mfma_f32_16x16x32_bf16 v[52:55], v[182:185], v[190:193], v[52:55]
	v_mfma_f32_16x16x32_bf16 v[52:55], v[186:189], v[194:197], v[52:55]
	v_mfma_f32_16x16x32_bf16 v[48:51], v[150:153], v[198:201], v[48:51]
	v_mfma_f32_16x16x32_bf16 v[48:51], v[162:165], v[202:205], v[48:51]
	v_mfma_f32_16x16x32_bf16 v[44:47], v[166:169], v[198:201], v[44:47]
	v_mfma_f32_16x16x32_bf16 v[44:47], v[170:173], v[202:205], v[44:47]
	v_mfma_f32_16x16x32_bf16 v[40:43], v[174:177], v[198:201], v[40:43]
	v_mfma_f32_16x16x32_bf16 v[40:43], v[178:181], v[202:205], v[40:43]
	v_mfma_f32_16x16x32_bf16 v[36:39], v[182:185], v[198:201], v[36:39]
	v_mfma_f32_16x16x32_bf16 v[36:39], v[186:189], v[202:205], v[36:39]
	v_mfma_f32_16x16x32_bf16 v[32:35], v[150:153], v[206:209], v[32:35]
	v_mfma_f32_16x16x32_bf16 v[32:35], v[162:165], v[210:213], v[32:35]
	v_mfma_f32_16x16x32_bf16 v[28:31], v[166:169], v[206:209], v[28:31]
	v_mfma_f32_16x16x32_bf16 v[28:31], v[170:173], v[210:213], v[28:31]
	v_mfma_f32_16x16x32_bf16 v[24:27], v[174:177], v[206:209], v[24:27]
	v_mfma_f32_16x16x32_bf16 v[24:27], v[178:181], v[210:213], v[24:27]
	v_mfma_f32_16x16x32_bf16 v[20:23], v[182:185], v[206:209], v[20:23]
	v_mfma_f32_16x16x32_bf16 v[20:23], v[186:189], v[210:213], v[20:23]
	v_mfma_f32_16x16x32_bf16 v[16:19], v[150:153], v[214:217], v[16:19]
	v_mfma_f32_16x16x32_bf16 v[16:19], v[162:165], v[218:221], v[16:19]
	v_mfma_f32_16x16x32_bf16 v[12:15], v[166:169], v[214:217], v[12:15]
	v_mfma_f32_16x16x32_bf16 v[12:15], v[170:173], v[218:221], v[12:15]
	v_mfma_f32_16x16x32_bf16 v[8:11], v[174:177], v[214:217], v[8:11]
	v_mfma_f32_16x16x32_bf16 v[8:11], v[178:181], v[218:221], v[8:11]
	v_mfma_f32_16x16x32_bf16 v[4:7], v[182:185], v[214:217], v[4:7]
	v_mfma_f32_16x16x32_bf16 v[4:7], v[186:189], v[218:221], v[4:7]
	s_setprio 0
	s_barrier
	s_add_i32 s0, 0, 0x18000
	v_add_u32_e32 v161, s0, v133
	s_add_i32 s73, 0, 0x1c000
	ds_read_b128 v[150:153], v161
	ds_read_b128 v[162:165], v161 offset:1024
	ds_read_b128 v[166:169], v161 offset:2048
	ds_read_b128 v[170:173], v161 offset:3072
	v_add_u32_e32 v161, s73, v133
	ds_read_b128 v[174:177], v161
	ds_read_b128 v[178:181], v161 offset:1024
	ds_read_b128 v[182:185], v161 offset:2048
	ds_read_b128 v[186:189], v161 offset:3072
	s_add_u32 s98, s54, 0x100000
	s_addc_u32 s99, s55, 0
	s_mov_b32 m0, s49
	ds_read_b128 v[190:193], v158 offset:32768
	ds_read_b128 v[194:197], v158 offset:33792
	ds_read_b128 v[198:201], v158 offset:34816
	ds_read_b128 v[202:205], v158 offset:35840
	ds_read_b128 v[206:209], v158 offset:36864
	ds_read_b128 v[210:213], v158 offset:37888
	ds_read_b128 v[214:217], v158 offset:38912
	ds_read_b128 v[218:221], v158 offset:39936
	global_load_lds_dwordx4 v134, s[98:99]
	s_mov_b32 m0, s56
	s_nop 0
	global_load_lds_dwordx4 v138, s[98:99]
	s_waitcnt vmcnt(8)
	s_waitcnt lgkmcnt(0)
	s_setprio 1
	s_barrier
	v_mfma_f32_16x16x32_bf16 v[128:131], v[150:153], v[190:193], v[128:131]
	v_mfma_f32_16x16x32_bf16 v[128:131], v[162:165], v[194:197], v[128:131]
	v_mfma_f32_16x16x32_bf16 v[124:127], v[166:169], v[190:193], v[124:127]
	v_mfma_f32_16x16x32_bf16 v[124:127], v[170:173], v[194:197], v[124:127]
	v_mfma_f32_16x16x32_bf16 v[120:123], v[174:177], v[190:193], v[120:123]
	v_mfma_f32_16x16x32_bf16 v[120:123], v[178:181], v[194:197], v[120:123]
	v_mfma_f32_16x16x32_bf16 v[116:119], v[182:185], v[190:193], v[116:119]
	v_mfma_f32_16x16x32_bf16 v[116:119], v[186:189], v[194:197], v[116:119]
	v_mfma_f32_16x16x32_bf16 v[112:115], v[150:153], v[198:201], v[112:115]
	v_mfma_f32_16x16x32_bf16 v[112:115], v[162:165], v[202:205], v[112:115]
	v_mfma_f32_16x16x32_bf16 v[108:111], v[166:169], v[198:201], v[108:111]
	v_mfma_f32_16x16x32_bf16 v[108:111], v[170:173], v[202:205], v[108:111]
	v_mfma_f32_16x16x32_bf16 v[104:107], v[174:177], v[198:201], v[104:107]
	v_mfma_f32_16x16x32_bf16 v[104:107], v[178:181], v[202:205], v[104:107]
	v_mfma_f32_16x16x32_bf16 v[100:103], v[182:185], v[198:201], v[100:103]
	v_mfma_f32_16x16x32_bf16 v[100:103], v[186:189], v[202:205], v[100:103]
	v_mfma_f32_16x16x32_bf16 v[96:99], v[150:153], v[206:209], v[96:99]
	v_mfma_f32_16x16x32_bf16 v[96:99], v[162:165], v[210:213], v[96:99]
	v_mfma_f32_16x16x32_bf16 v[92:95], v[166:169], v[206:209], v[92:95]
	v_mfma_f32_16x16x32_bf16 v[92:95], v[170:173], v[210:213], v[92:95]
	v_mfma_f32_16x16x32_bf16 v[88:91], v[174:177], v[206:209], v[88:91]
	v_mfma_f32_16x16x32_bf16 v[88:91], v[178:181], v[210:213], v[88:91]
	v_mfma_f32_16x16x32_bf16 v[84:87], v[182:185], v[206:209], v[84:87]
	v_mfma_f32_16x16x32_bf16 v[84:87], v[186:189], v[210:213], v[84:87]
	v_mfma_f32_16x16x32_bf16 v[80:83], v[150:153], v[214:217], v[80:83]
	v_mfma_f32_16x16x32_bf16 v[80:83], v[162:165], v[218:221], v[80:83]
	v_mfma_f32_16x16x32_bf16 v[76:79], v[166:169], v[214:217], v[76:79]
	v_mfma_f32_16x16x32_bf16 v[76:79], v[170:173], v[218:221], v[76:79]
	v_mfma_f32_16x16x32_bf16 v[72:75], v[174:177], v[214:217], v[72:75]
	v_mfma_f32_16x16x32_bf16 v[72:75], v[178:181], v[218:221], v[72:75]
	v_mfma_f32_16x16x32_bf16 v[68:71], v[182:185], v[214:217], v[68:71]
	v_mfma_f32_16x16x32_bf16 v[68:71], v[186:189], v[218:221], v[68:71]
	s_setprio 0
	s_barrier
	s_add_i32 s0, s0, s41
	s_add_i32 m0, s0, 0xffffff80
	ds_read_b128 v[190:193], v158 offset:49152
	ds_read_b128 v[194:197], v158 offset:50176
	ds_read_b128 v[198:201], v158 offset:51200
	ds_read_b128 v[202:205], v158 offset:52224
	ds_read_b128 v[206:209], v158 offset:53248
	ds_read_b128 v[210:213], v158 offset:54272
	ds_read_b128 v[214:217], v158 offset:55296
	ds_read_b128 v[218:221], v158 offset:56320
	global_load_lds_dwordx4 v136, s[52:53] offset:128
	s_add_i32 m0, s0, 0x1f80
	s_add_i32 s0, s73, s41
	global_load_lds_dwordx4 v140, s[52:53] offset:128
	s_add_u32 s52, s52, 0x100080
	s_addc_u32 s53, s53, 0
	s_mov_b32 m0, s0
	s_nop 0
	global_load_lds_dwordx4 v136, s[52:53]
	s_add_i32 m0, s0, 0x2000
	s_nop 0
	global_load_lds_dwordx4 v140, s[52:53]
	s_add_i32 m0, s59, 0xffffff80
	s_nop 0
	global_load_lds_dwordx4 v134, s[54:55] offset:128
	s_add_i32 m0, s60, 0xffffff80
	s_nop 0
	global_load_lds_dwordx4 v138, s[54:55] offset:128
	s_waitcnt vmcnt(8)
	s_waitcnt lgkmcnt(0)
	s_setprio 1
	s_barrier
	v_mfma_f32_16x16x32_bf16 v[64:67], v[150:153], v[190:193], v[64:67]
	v_mfma_f32_16x16x32_bf16 v[64:67], v[162:165], v[194:197], v[64:67]
	v_mfma_f32_16x16x32_bf16 v[60:63], v[166:169], v[190:193], v[60:63]
	v_mfma_f32_16x16x32_bf16 v[60:63], v[170:173], v[194:197], v[60:63]
	v_mfma_f32_16x16x32_bf16 v[56:59], v[174:177], v[190:193], v[56:59]
	v_mfma_f32_16x16x32_bf16 v[56:59], v[178:181], v[194:197], v[56:59]
	v_mfma_f32_16x16x32_bf16 v[52:55], v[182:185], v[190:193], v[52:55]
	v_mfma_f32_16x16x32_bf16 v[52:55], v[186:189], v[194:197], v[52:55]
	v_mfma_f32_16x16x32_bf16 v[48:51], v[150:153], v[198:201], v[48:51]
	v_mfma_f32_16x16x32_bf16 v[48:51], v[162:165], v[202:205], v[48:51]
	v_mfma_f32_16x16x32_bf16 v[44:47], v[166:169], v[198:201], v[44:47]
	v_mfma_f32_16x16x32_bf16 v[44:47], v[170:173], v[202:205], v[44:47]
	v_mfma_f32_16x16x32_bf16 v[40:43], v[174:177], v[198:201], v[40:43]
	v_mfma_f32_16x16x32_bf16 v[40:43], v[178:181], v[202:205], v[40:43]
	v_mfma_f32_16x16x32_bf16 v[36:39], v[182:185], v[198:201], v[36:39]
	v_mfma_f32_16x16x32_bf16 v[36:39], v[186:189], v[202:205], v[36:39]
	v_mfma_f32_16x16x32_bf16 v[32:35], v[150:153], v[206:209], v[32:35]
	v_mfma_f32_16x16x32_bf16 v[32:35], v[162:165], v[210:213], v[32:35]
	v_mfma_f32_16x16x32_bf16 v[28:31], v[166:169], v[206:209], v[28:31]
	v_mfma_f32_16x16x32_bf16 v[28:31], v[170:173], v[210:213], v[28:31]
	v_mfma_f32_16x16x32_bf16 v[24:27], v[174:177], v[206:209], v[24:27]
	v_mfma_f32_16x16x32_bf16 v[24:27], v[178:181], v[210:213], v[24:27]
	v_mfma_f32_16x16x32_bf16 v[20:23], v[182:185], v[206:209], v[20:23]
	v_mfma_f32_16x16x32_bf16 v[20:23], v[186:189], v[210:213], v[20:23]
	v_mfma_f32_16x16x32_bf16 v[16:19], v[150:153], v[214:217], v[16:19]
	v_mfma_f32_16x16x32_bf16 v[16:19], v[162:165], v[218:221], v[16:19]
	v_mfma_f32_16x16x32_bf16 v[12:15], v[166:169], v[214:217], v[12:15]
	v_mfma_f32_16x16x32_bf16 v[12:15], v[170:173], v[218:221], v[12:15]
	v_mfma_f32_16x16x32_bf16 v[8:11], v[174:177], v[214:217], v[8:11]
	v_mfma_f32_16x16x32_bf16 v[8:11], v[178:181], v[218:221], v[8:11]
	v_mfma_f32_16x16x32_bf16 v[4:7], v[182:185], v[214:217], v[4:7]
	v_mfma_f32_16x16x32_bf16 v[4:7], v[186:189], v[218:221], v[4:7]
	s_setprio 0
	s_barrier
	s_add_i32 s72, s72, 2
	s_add_u32 s50, s50, 0x100
	s_addc_u32 s51, s51, 0
	s_add_u32 s70, s70, 0x100
	s_addc_u32 s71, s71, 0
	s_cmp_gt_u32 s72, 61
	s_cbranch_scc0 .LBB0_429
	s_and_b64 vcc, exec, s[22:23]
	s_cbranch_vccz .LBB0_432
	s_barrier

.LBB0_1032:
	v_add_u32_e32 v5, s60, v3
	ds_read_b128 v[140:143], v5
	ds_read_b128 v[144:147], v5 offset:1024
	ds_read_b128 v[148:151], v5 offset:2048
	ds_read_b128 v[152:155], v5 offset:3072
	v_add_u32_e32 v5, s61, v3
	ds_read_b128 v[156:159], v5
	ds_read_b128 v[160:163], v5 offset:1024
	ds_read_b128 v[164:167], v5 offset:2048
	ds_read_b128 v[168:171], v5 offset:3072
	s_add_u32 s42, s40, 0xfff80080
	s_addc_u32 s43, s41, -1
	s_cmp_eq_u32 s67, 28
	s_cselect_b32 s51, s5, s43
	s_cselect_b32 s50, s7, s42
	s_cselect_b32 s43, s25, s66
	s_cselect_b32 s42, s27, s65
	s_add_i32 m0, s47, 0xc000
	ds_read_b128 v[172:175], v246
	ds_read_b128 v[176:179], v246 offset:1024
	ds_read_b128 v[180:183], v246 offset:2048
	ds_read_b128 v[184:187], v246 offset:3072
	ds_read_b128 v[188:191], v246 offset:4096
	ds_read_b128 v[192:195], v246 offset:5120
	ds_read_b128 v[196:199], v246 offset:6144
	ds_read_b128 v[200:203], v246 offset:7168
	global_load_lds_dwordx4 v216, s[40:41]
	s_add_i32 m0, s47, 0xe000
	s_nop 0
	global_load_lds_dwordx4 v218, s[40:41]
	s_waitcnt vmcnt(8)
	s_waitcnt lgkmcnt(0)
	s_setprio 1
	s_barrier
	v_mfma_f32_16x16x32_bf16 v[136:139], v[140:143], v[172:175], v[136:139]
	v_mfma_f32_16x16x32_bf16 v[136:139], v[144:147], v[176:179], v[136:139]
	v_mfma_f32_16x16x32_bf16 v[132:135], v[148:151], v[172:175], v[132:135]
	v_mfma_f32_16x16x32_bf16 v[132:135], v[152:155], v[176:179], v[132:135]
	v_mfma_f32_16x16x32_bf16 v[104:107], v[156:159], v[172:175], v[104:107]
	v_mfma_f32_16x16x32_bf16 v[104:107], v[160:163], v[176:179], v[104:107]
	v_mfma_f32_16x16x32_bf16 v[100:103], v[164:167], v[172:175], v[100:103]
	v_mfma_f32_16x16x32_bf16 v[100:103], v[168:171], v[176:179], v[100:103]
	v_mfma_f32_16x16x32_bf16 v[128:131], v[140:143], v[180:183], v[128:131]
	v_mfma_f32_16x16x32_bf16 v[128:131], v[144:147], v[184:187], v[128:131]
	v_mfma_f32_16x16x32_bf16 v[124:127], v[148:151], v[180:183], v[124:127]
	v_mfma_f32_16x16x32_bf16 v[124:127], v[152:155], v[184:187], v[124:127]
	v_mfma_f32_16x16x32_bf16 v[96:99], v[156:159], v[180:183], v[96:99]
	v_mfma_f32_16x16x32_bf16 v[96:99], v[160:163], v[184:187], v[96:99]
	v_mfma_f32_16x16x32_bf16 v[92:95], v[164:167], v[180:183], v[92:95]
	v_mfma_f32_16x16x32_bf16 v[92:95], v[168:171], v[184:187], v[92:95]
	v_mfma_f32_16x16x32_bf16 v[120:123], v[140:143], v[188:191], v[120:123]
	v_mfma_f32_16x16x32_bf16 v[120:123], v[144:147], v[192:195], v[120:123]
	v_mfma_f32_16x16x32_bf16 v[116:119], v[148:151], v[188:191], v[116:119]
	v_mfma_f32_16x16x32_bf16 v[116:119], v[152:155], v[192:195], v[116:119]
	v_mfma_f32_16x16x32_bf16 v[88:91], v[156:159], v[188:191], v[88:91]
	v_mfma_f32_16x16x32_bf16 v[88:91], v[160:163], v[192:195], v[88:91]
	v_mfma_f32_16x16x32_bf16 v[84:87], v[164:167], v[188:191], v[84:87]
	v_mfma_f32_16x16x32_bf16 v[84:87], v[168:171], v[192:195], v[84:87]
	v_mfma_f32_16x16x32_bf16 v[112:115], v[140:143], v[196:199], v[112:115]
	v_mfma_f32_16x16x32_bf16 v[112:115], v[144:147], v[200:203], v[112:115]
	v_mfma_f32_16x16x32_bf16 v[108:111], v[148:151], v[196:199], v[108:111]
	v_mfma_f32_16x16x32_bf16 v[108:111], v[152:155], v[200:203], v[108:111]
	v_mfma_f32_16x16x32_bf16 v[80:83], v[156:159], v[196:199], v[80:83]
	v_mfma_f32_16x16x32_bf16 v[80:83], v[160:163], v[200:203], v[80:83]
	v_mfma_f32_16x16x32_bf16 v[76:79], v[164:167], v[196:199], v[76:79]
	v_mfma_f32_16x16x32_bf16 v[76:79], v[168:171], v[200:203], v[76:79]
	s_setprio 0
	s_barrier
	s_add_i32 s68, s60, s46
	s_mov_b32 m0, s68
	ds_read_b128 v[172:175], v246 offset:16384
	ds_read_b128 v[176:179], v246 offset:17408
	ds_read_b128 v[180:183], v246 offset:18432
	ds_read_b128 v[184:187], v246 offset:19456
	ds_read_b128 v[188:191], v246 offset:20480
	ds_read_b128 v[192:195], v246 offset:21504
	ds_read_b128 v[196:199], v246 offset:22528
	ds_read_b128 v[200:203], v246 offset:23552
	global_load_lds_dwordx4 v210, s[42:43]
	s_add_i32 m0, s68, 0x2000
	s_add_u32 s70, s42, 0x80000
	s_addc_u32 s71, s43, 0
	s_add_i32 s68, s61, s46
	global_load_lds_dwordx4 v214, s[42:43]
	s_mov_b32 m0, s68
	s_nop 0
	global_load_lds_dwordx4 v210, s[70:71]
	s_add_i32 m0, s68, 0x2000
	s_nop 0
	global_load_lds_dwordx4 v214, s[70:71]
	s_mov_b32 m0, s47
	s_nop 0
	global_load_lds_dwordx4 v208, s[50:51]
	s_mov_b32 m0, s48
	s_nop 0
	global_load_lds_dwordx4 v212, s[50:51]
	s_waitcnt vmcnt(8)
	s_waitcnt lgkmcnt(0)
	s_setprio 1
	s_barrier
	v_mfma_f32_16x16x32_bf16 v[72:75], v[140:143], v[172:175], v[72:75]
	v_mfma_f32_16x16x32_bf16 v[72:75], v[144:147], v[176:179], v[72:75]
	v_mfma_f32_16x16x32_bf16 v[68:71], v[148:151], v[172:175], v[68:71]
	v_mfma_f32_16x16x32_bf16 v[68:71], v[152:155], v[176:179], v[68:71]
	v_mfma_f32_16x16x32_bf16 v[40:43], v[156:159], v[172:175], v[40:43]
	v_mfma_f32_16x16x32_bf16 v[40:43], v[160:163], v[176:179], v[40:43]
	v_mfma_f32_16x16x32_bf16 v[36:39], v[164:167], v[172:175], v[36:39]
	v_mfma_f32_16x16x32_bf16 v[36:39], v[168:171], v[176:179], v[36:39]
	v_mfma_f32_16x16x32_bf16 v[64:67], v[140:143], v[180:183], v[64:67]
	v_mfma_f32_16x16x32_bf16 v[64:67], v[144:147], v[184:187], v[64:67]
	v_mfma_f32_16x16x32_bf16 v[60:63], v[148:151], v[180:183], v[60:63]
	v_mfma_f32_16x16x32_bf16 v[60:63], v[152:155], v[184:187], v[60:63]
	v_mfma_f32_16x16x32_bf16 v[32:35], v[156:159], v[180:183], v[32:35]
	v_mfma_f32_16x16x32_bf16 v[32:35], v[160:163], v[184:187], v[32:35]
	v_mfma_f32_16x16x32_bf16 v[28:31], v[164:167], v[180:183], v[28:31]
	v_mfma_f32_16x16x32_bf16 v[28:31], v[168:171], v[184:187], v[28:31]
	v_mfma_f32_16x16x32_bf16 v[56:59], v[140:143], v[188:191], v[56:59]
	v_mfma_f32_16x16x32_bf16 v[56:59], v[144:147], v[192:195], v[56:59]
	v_mfma_f32_16x16x32_bf16 v[52:55], v[148:151], v[188:191], v[52:55]
	v_mfma_f32_16x16x32_bf16 v[52:55], v[152:155], v[192:195], v[52:55]
	v_mfma_f32_16x16x32_bf16 v[24:27], v[156:159], v[188:191], v[24:27]
	v_mfma_f32_16x16x32_bf16 v[24:27], v[160:163], v[192:195], v[24:27]
	v_mfma_f32_16x16x32_bf16 v[20:23], v[164:167], v[188:191], v[20:23]
	v_mfma_f32_16x16x32_bf16 v[20:23], v[168:171], v[192:195], v[20:23]
	v_mfma_f32_16x16x32_bf16 v[48:51], v[140:143], v[196:199], v[48:51]
	v_mfma_f32_16x16x32_bf16 v[48:51], v[144:147], v[200:203], v[48:51]
	v_mfma_f32_16x16x32_bf16 v[44:47], v[148:151], v[196:199], v[44:47]
	v_mfma_f32_16x16x32_bf16 v[44:47], v[152:155], v[200:203], v[44:47]
	v_mfma_f32_16x16x32_bf16 v[16:19], v[156:159], v[196:199], v[16:19]
	v_mfma_f32_16x16x32_bf16 v[16:19], v[160:163], v[200:203], v[16:19]
	v_mfma_f32_16x16x32_bf16 v[12:15], v[164:167], v[196:199], v[12:15]
	v_mfma_f32_16x16x32_bf16 v[12:15], v[168:171], v[200:203], v[12:15]
	s_setprio 0
	s_barrier
	s_add_i32 s68, 0, 0x18000
	v_add_u32_e32 v5, s68, v3
	s_add_i32 s70, 0, 0x1c000
	ds_read_b128 v[140:143], v5
	ds_read_b128 v[144:147], v5 offset:1024
	ds_read_b128 v[148:151], v5 offset:2048
	ds_read_b128 v[152:155], v5 offset:3072
	v_add_u32_e32 v5, s70, v3
	ds_read_b128 v[156:159], v5
	ds_read_b128 v[160:163], v5 offset:1024
	ds_read_b128 v[164:167], v5 offset:2048
	ds_read_b128 v[168:171], v5 offset:3072
	s_add_u32 s98, s50, 0x80000
	s_addc_u32 s99, s51, 0
	s_mov_b64 s[100:101], s[50:51]
	s_mov_b32 m0, s49
	ds_read_b128 v[172:175], v246 offset:32768
	ds_read_b128 v[176:179], v246 offset:33792
	ds_read_b128 v[180:183], v246 offset:34816
	ds_read_b128 v[184:187], v246 offset:35840
	ds_read_b128 v[188:191], v246 offset:36864
	ds_read_b128 v[192:195], v246 offset:37888
	ds_read_b128 v[196:199], v246 offset:38912
	ds_read_b128 v[200:203], v246 offset:39936
	global_load_lds_dwordx4 v208, s[98:99]
	s_mov_b32 m0, s52
	s_nop 0
	global_load_lds_dwordx4 v212, s[98:99]
	s_waitcnt vmcnt(8)
	s_waitcnt lgkmcnt(0)
	s_setprio 1
	s_barrier
	v_mfma_f32_16x16x32_bf16 v[136:139], v[140:143], v[172:175], v[136:139]
	v_mfma_f32_16x16x32_bf16 v[136:139], v[144:147], v[176:179], v[136:139]
	v_mfma_f32_16x16x32_bf16 v[132:135], v[148:151], v[172:175], v[132:135]
	v_mfma_f32_16x16x32_bf16 v[132:135], v[152:155], v[176:179], v[132:135]
	v_mfma_f32_16x16x32_bf16 v[104:107], v[156:159], v[172:175], v[104:107]
	v_mfma_f32_16x16x32_bf16 v[104:107], v[160:163], v[176:179], v[104:107]
	v_mfma_f32_16x16x32_bf16 v[100:103], v[164:167], v[172:175], v[100:103]
	v_mfma_f32_16x16x32_bf16 v[100:103], v[168:171], v[176:179], v[100:103]
	v_mfma_f32_16x16x32_bf16 v[128:131], v[140:143], v[180:183], v[128:131]
	v_mfma_f32_16x16x32_bf16 v[128:131], v[144:147], v[184:187], v[128:131]
	v_mfma_f32_16x16x32_bf16 v[124:127], v[148:151], v[180:183], v[124:127]
	v_mfma_f32_16x16x32_bf16 v[124:127], v[152:155], v[184:187], v[124:127]
	v_mfma_f32_16x16x32_bf16 v[96:99], v[156:159], v[180:183], v[96:99]
	v_mfma_f32_16x16x32_bf16 v[96:99], v[160:163], v[184:187], v[96:99]
	v_mfma_f32_16x16x32_bf16 v[92:95], v[164:167], v[180:183], v[92:95]
	v_mfma_f32_16x16x32_bf16 v[92:95], v[168:171], v[184:187], v[92:95]
	v_mfma_f32_16x16x32_bf16 v[120:123], v[140:143], v[188:191], v[120:123]
	v_mfma_f32_16x16x32_bf16 v[120:123], v[144:147], v[192:195], v[120:123]
	v_mfma_f32_16x16x32_bf16 v[116:119], v[148:151], v[188:191], v[116:119]
	v_mfma_f32_16x16x32_bf16 v[116:119], v[152:155], v[192:195], v[116:119]
	v_mfma_f32_16x16x32_bf16 v[88:91], v[156:159], v[188:191], v[88:91]
	v_mfma_f32_16x16x32_bf16 v[88:91], v[160:163], v[192:195], v[88:91]
	v_mfma_f32_16x16x32_bf16 v[84:87], v[164:167], v[188:191], v[84:87]
	v_mfma_f32_16x16x32_bf16 v[84:87], v[168:171], v[192:195], v[84:87]
	v_mfma_f32_16x16x32_bf16 v[112:115], v[140:143], v[196:199], v[112:115]
	v_mfma_f32_16x16x32_bf16 v[112:115], v[144:147], v[200:203], v[112:115]
	v_mfma_f32_16x16x32_bf16 v[108:111], v[148:151], v[196:199], v[108:111]
	v_mfma_f32_16x16x32_bf16 v[108:111], v[152:155], v[200:203], v[108:111]
	v_mfma_f32_16x16x32_bf16 v[80:83], v[156:159], v[196:199], v[80:83]
	v_mfma_f32_16x16x32_bf16 v[80:83], v[160:163], v[200:203], v[80:83]
	v_mfma_f32_16x16x32_bf16 v[76:79], v[164:167], v[196:199], v[76:79]
	v_mfma_f32_16x16x32_bf16 v[76:79], v[168:171], v[200:203], v[76:79]
	s_setprio 0
	s_barrier
	s_add_i32 s50, s68, s46
	s_add_i32 m0, s50, 0xffffff80
	ds_read_b128 v[172:175], v246 offset:49152
	ds_read_b128 v[176:179], v246 offset:50176
	ds_read_b128 v[180:183], v246 offset:51200
	ds_read_b128 v[184:187], v246 offset:52224
	ds_read_b128 v[188:191], v246 offset:53248
	ds_read_b128 v[192:195], v246 offset:54272
	ds_read_b128 v[196:199], v246 offset:55296
	ds_read_b128 v[200:203], v246 offset:56320
	global_load_lds_dwordx4 v210, s[42:43] offset:128
	s_add_i32 m0, s50, 0x1f80
	s_add_i32 s50, s70, s46
	global_load_lds_dwordx4 v214, s[42:43] offset:128
	s_add_u32 s42, s42, 0x80080
	s_addc_u32 s43, s43, 0
	s_mov_b32 m0, s50
	s_nop 0
	global_load_lds_dwordx4 v210, s[42:43]
	s_add_i32 m0, s50, 0x2000
	s_nop 0
	global_load_lds_dwordx4 v214, s[42:43]
	s_add_i32 m0, s58, 0xffffff80
	s_nop 0
	global_load_lds_dwordx4 v208, s[100:101] offset:128
	s_add_i32 m0, s59, 0xffffff80
	s_nop 0
	global_load_lds_dwordx4 v212, s[100:101] offset:128
	s_waitcnt vmcnt(8)
	s_waitcnt lgkmcnt(0)
	s_setprio 1
	s_barrier
	v_mfma_f32_16x16x32_bf16 v[72:75], v[140:143], v[172:175], v[72:75]
	v_mfma_f32_16x16x32_bf16 v[72:75], v[144:147], v[176:179], v[72:75]
	v_mfma_f32_16x16x32_bf16 v[68:71], v[148:151], v[172:175], v[68:71]
	v_mfma_f32_16x16x32_bf16 v[68:71], v[152:155], v[176:179], v[68:71]
	v_mfma_f32_16x16x32_bf16 v[40:43], v[156:159], v[172:175], v[40:43]
	v_mfma_f32_16x16x32_bf16 v[40:43], v[160:163], v[176:179], v[40:43]
	v_mfma_f32_16x16x32_bf16 v[36:39], v[164:167], v[172:175], v[36:39]
	v_mfma_f32_16x16x32_bf16 v[36:39], v[168:171], v[176:179], v[36:39]
	v_mfma_f32_16x16x32_bf16 v[64:67], v[140:143], v[180:183], v[64:67]
	v_mfma_f32_16x16x32_bf16 v[64:67], v[144:147], v[184:187], v[64:67]
	v_mfma_f32_16x16x32_bf16 v[60:63], v[148:151], v[180:183], v[60:63]
	v_mfma_f32_16x16x32_bf16 v[60:63], v[152:155], v[184:187], v[60:63]
	v_mfma_f32_16x16x32_bf16 v[32:35], v[156:159], v[180:183], v[32:35]
	v_mfma_f32_16x16x32_bf16 v[32:35], v[160:163], v[184:187], v[32:35]
	v_mfma_f32_16x16x32_bf16 v[28:31], v[164:167], v[180:183], v[28:31]
	v_mfma_f32_16x16x32_bf16 v[28:31], v[168:171], v[184:187], v[28:31]
	v_mfma_f32_16x16x32_bf16 v[56:59], v[140:143], v[188:191], v[56:59]
	v_mfma_f32_16x16x32_bf16 v[56:59], v[144:147], v[192:195], v[56:59]
	v_mfma_f32_16x16x32_bf16 v[52:55], v[148:151], v[188:191], v[52:55]
	v_mfma_f32_16x16x32_bf16 v[52:55], v[152:155], v[192:195], v[52:55]
	v_mfma_f32_16x16x32_bf16 v[24:27], v[156:159], v[188:191], v[24:27]
	v_mfma_f32_16x16x32_bf16 v[24:27], v[160:163], v[192:195], v[24:27]
	v_mfma_f32_16x16x32_bf16 v[20:23], v[164:167], v[188:191], v[20:23]
	v_mfma_f32_16x16x32_bf16 v[20:23], v[168:171], v[192:195], v[20:23]
	v_mfma_f32_16x16x32_bf16 v[48:51], v[140:143], v[196:199], v[48:51]
	v_mfma_f32_16x16x32_bf16 v[48:51], v[144:147], v[200:203], v[48:51]
	v_mfma_f32_16x16x32_bf16 v[44:47], v[148:151], v[196:199], v[44:47]
	v_mfma_f32_16x16x32_bf16 v[44:47], v[152:155], v[200:203], v[44:47]
	v_mfma_f32_16x16x32_bf16 v[16:19], v[156:159], v[196:199], v[16:19]
	v_mfma_f32_16x16x32_bf16 v[16:19], v[160:163], v[200:203], v[16:19]
	v_mfma_f32_16x16x32_bf16 v[12:15], v[164:167], v[196:199], v[12:15]
	v_mfma_f32_16x16x32_bf16 v[12:15], v[168:171], v[200:203], v[12:15]
	s_setprio 0
	s_barrier
	s_add_i32 s67, s67, 2
	s_add_u32 s40, s40, 0x100
	s_addc_u32 s41, s41, 0
	s_add_u32 s65, s65, 0x100
	s_addc_u32 s66, s66, 0
	s_cmp_gt_u32 s67, 29
	s_cbranch_scc0 .LBB0_1032
	s_and_b64 vcc, exec, s[22:23]
	s_cbranch_vccz .LBB0_1035
	s_barrier

.LBB0_1203:
	ds_read_b128 v[132:135], v187
	ds_read_b128 v[136:139], v187 offset:1024
	ds_read_b128 v[140:143], v187 offset:2048
	ds_read_b128 v[144:147], v187 offset:3072
	ds_read_b128 v[148:151], v188
	ds_read_b128 v[152:155], v188 offset:1024
	ds_read_b128 v[172:175], v188 offset:2048
	ds_read_b128 v[176:179], v188 offset:3072
	s_add_u32 s0, s42, 0xfff00080
	s_addc_u32 s50, s43, -1
	s_cmp_eq_u32 s65, 60
	s_cselect_b32 s53, s25, s50
	s_cselect_b32 s52, s31, s0
	s_cselect_b32 s51, s23, s64
	s_cselect_b32 s50, s62, s63
	s_add_i32 m0, s41, 0xc000
	ds_read_b128 v[180:183], v189
	ds_read_b128 v[192:195], v189 offset:1024
	ds_read_b128 v[196:199], v189 offset:2048
	ds_read_b128 v[200:203], v189 offset:3072
	ds_read_b128 v[204:207], v189 offset:4096
	ds_read_b128 v[208:211], v189 offset:5120
	ds_read_b128 v[212:215], v189 offset:6144
	ds_read_b128 v[216:219], v189 offset:7168
	global_load_lds_dwordx4 v164, s[42:43]
	s_add_i32 m0, s41, 0xe000
	s_nop 0
	global_load_lds_dwordx4 v166, s[42:43]
	s_waitcnt vmcnt(8)
	s_waitcnt lgkmcnt(0)
	s_setprio 1
	s_barrier
	v_mfma_f32_16x16x32_bf16 v[128:131], v[132:135], v[180:183], v[128:131]
	v_mfma_f32_16x16x32_bf16 v[128:131], v[136:139], v[192:195], v[128:131]
	v_mfma_f32_16x16x32_bf16 v[124:127], v[140:143], v[180:183], v[124:127]
	v_mfma_f32_16x16x32_bf16 v[124:127], v[144:147], v[192:195], v[124:127]
	v_mfma_f32_16x16x32_bf16 v[120:123], v[148:151], v[180:183], v[120:123]
	v_mfma_f32_16x16x32_bf16 v[120:123], v[152:155], v[192:195], v[120:123]
	v_mfma_f32_16x16x32_bf16 v[116:119], v[172:175], v[180:183], v[116:119]
	v_mfma_f32_16x16x32_bf16 v[116:119], v[176:179], v[192:195], v[116:119]
	v_mfma_f32_16x16x32_bf16 v[112:115], v[132:135], v[196:199], v[112:115]
	v_mfma_f32_16x16x32_bf16 v[112:115], v[136:139], v[200:203], v[112:115]
	v_mfma_f32_16x16x32_bf16 v[108:111], v[140:143], v[196:199], v[108:111]
	v_mfma_f32_16x16x32_bf16 v[108:111], v[144:147], v[200:203], v[108:111]
	v_mfma_f32_16x16x32_bf16 v[104:107], v[148:151], v[196:199], v[104:107]
	v_mfma_f32_16x16x32_bf16 v[104:107], v[152:155], v[200:203], v[104:107]
	v_mfma_f32_16x16x32_bf16 v[100:103], v[172:175], v[196:199], v[100:103]
	v_mfma_f32_16x16x32_bf16 v[100:103], v[176:179], v[200:203], v[100:103]
	v_mfma_f32_16x16x32_bf16 v[96:99], v[132:135], v[204:207], v[96:99]
	v_mfma_f32_16x16x32_bf16 v[96:99], v[136:139], v[208:211], v[96:99]
	v_mfma_f32_16x16x32_bf16 v[92:95], v[140:143], v[204:207], v[92:95]
	v_mfma_f32_16x16x32_bf16 v[92:95], v[144:147], v[208:211], v[92:95]
	v_mfma_f32_16x16x32_bf16 v[88:91], v[148:151], v[204:207], v[88:91]
	v_mfma_f32_16x16x32_bf16 v[88:91], v[152:155], v[208:211], v[88:91]
	v_mfma_f32_16x16x32_bf16 v[84:87], v[172:175], v[204:207], v[84:87]
	v_mfma_f32_16x16x32_bf16 v[84:87], v[176:179], v[208:211], v[84:87]
	v_mfma_f32_16x16x32_bf16 v[80:83], v[132:135], v[212:215], v[80:83]
	v_mfma_f32_16x16x32_bf16 v[80:83], v[136:139], v[216:219], v[80:83]
	v_mfma_f32_16x16x32_bf16 v[76:79], v[140:143], v[212:215], v[76:79]
	v_mfma_f32_16x16x32_bf16 v[76:79], v[144:147], v[216:219], v[76:79]
	v_mfma_f32_16x16x32_bf16 v[72:75], v[148:151], v[212:215], v[72:75]
	v_mfma_f32_16x16x32_bf16 v[72:75], v[152:155], v[216:219], v[72:75]
	v_mfma_f32_16x16x32_bf16 v[68:71], v[172:175], v[212:215], v[68:71]
	v_mfma_f32_16x16x32_bf16 v[68:71], v[176:179], v[216:219], v[68:71]
	s_setprio 0
	s_barrier
	s_add_i32 s0, s59, s46
	s_mov_b32 m0, s0
	ds_read_b128 v[180:183], v189 offset:16384
	ds_read_b128 v[192:195], v189 offset:17408
	ds_read_b128 v[196:199], v189 offset:18432
	ds_read_b128 v[200:203], v189 offset:19456
	ds_read_b128 v[204:207], v189 offset:20480
	ds_read_b128 v[208:211], v189 offset:21504
	ds_read_b128 v[212:215], v189 offset:22528
	ds_read_b128 v[216:219], v189 offset:23552
	global_load_lds_dwordx4 v158, s[50:51]
	s_add_i32 m0, s0, 0x2000
	s_add_u32 s66, s50, 0x100000
	s_addc_u32 s67, s51, 0
	s_add_i32 s0, s60, s46
	global_load_lds_dwordx4 v162, s[50:51]
	s_mov_b32 m0, s0
	s_nop 0
	global_load_lds_dwordx4 v158, s[66:67]
	s_add_i32 m0, s0, 0x2000
	s_nop 0
	global_load_lds_dwordx4 v162, s[66:67]
	s_mov_b32 m0, s41
	s_nop 0
	global_load_lds_dwordx4 v156, s[52:53]
	s_mov_b32 m0, s47
	s_nop 0
	global_load_lds_dwordx4 v160, s[52:53]
	s_waitcnt vmcnt(8)
	s_waitcnt lgkmcnt(0)
	s_setprio 1
	s_barrier
	v_mfma_f32_16x16x32_bf16 v[64:67], v[132:135], v[180:183], v[64:67]
	v_mfma_f32_16x16x32_bf16 v[64:67], v[136:139], v[192:195], v[64:67]
	v_mfma_f32_16x16x32_bf16 v[60:63], v[140:143], v[180:183], v[60:63]
	v_mfma_f32_16x16x32_bf16 v[60:63], v[144:147], v[192:195], v[60:63]
	v_mfma_f32_16x16x32_bf16 v[56:59], v[148:151], v[180:183], v[56:59]
	v_mfma_f32_16x16x32_bf16 v[56:59], v[152:155], v[192:195], v[56:59]
	v_mfma_f32_16x16x32_bf16 v[52:55], v[172:175], v[180:183], v[52:55]
	v_mfma_f32_16x16x32_bf16 v[52:55], v[176:179], v[192:195], v[52:55]
	v_mfma_f32_16x16x32_bf16 v[48:51], v[132:135], v[196:199], v[48:51]
	v_mfma_f32_16x16x32_bf16 v[48:51], v[136:139], v[200:203], v[48:51]
	v_mfma_f32_16x16x32_bf16 v[44:47], v[140:143], v[196:199], v[44:47]
	v_mfma_f32_16x16x32_bf16 v[44:47], v[144:147], v[200:203], v[44:47]
	v_mfma_f32_16x16x32_bf16 v[40:43], v[148:151], v[196:199], v[40:43]
	v_mfma_f32_16x16x32_bf16 v[40:43], v[152:155], v[200:203], v[40:43]
	v_mfma_f32_16x16x32_bf16 v[36:39], v[172:175], v[196:199], v[36:39]
	v_mfma_f32_16x16x32_bf16 v[36:39], v[176:179], v[200:203], v[36:39]
	v_mfma_f32_16x16x32_bf16 v[32:35], v[132:135], v[204:207], v[32:35]
	v_mfma_f32_16x16x32_bf16 v[32:35], v[136:139], v[208:211], v[32:35]
	v_mfma_f32_16x16x32_bf16 v[28:31], v[140:143], v[204:207], v[28:31]
	v_mfma_f32_16x16x32_bf16 v[28:31], v[144:147], v[208:211], v[28:31]
	v_mfma_f32_16x16x32_bf16 v[24:27], v[148:151], v[204:207], v[24:27]
	v_mfma_f32_16x16x32_bf16 v[24:27], v[152:155], v[208:211], v[24:27]
	v_mfma_f32_16x16x32_bf16 v[20:23], v[172:175], v[204:207], v[20:23]
	v_mfma_f32_16x16x32_bf16 v[20:23], v[176:179], v[208:211], v[20:23]
	v_mfma_f32_16x16x32_bf16 v[16:19], v[132:135], v[212:215], v[16:19]
	v_mfma_f32_16x16x32_bf16 v[16:19], v[136:139], v[216:219], v[16:19]
	v_mfma_f32_16x16x32_bf16 v[12:15], v[140:143], v[212:215], v[12:15]
	v_mfma_f32_16x16x32_bf16 v[12:15], v[144:147], v[216:219], v[12:15]
	v_mfma_f32_16x16x32_bf16 v[8:11], v[148:151], v[212:215], v[8:11]
	v_mfma_f32_16x16x32_bf16 v[8:11], v[152:155], v[216:219], v[8:11]
	v_mfma_f32_16x16x32_bf16 v[4:7], v[172:175], v[212:215], v[4:7]
	v_mfma_f32_16x16x32_bf16 v[4:7], v[176:179], v[216:219], v[4:7]
	s_setprio 0
	s_barrier
	s_add_i32 s0, 0, 0x18000
	s_add_i32 s66, 0, 0x1c000
	v_add_u32_e32 v144, s0, v3
	v_add_u32_e32 v176, s66, v3
	ds_read_b128 v[132:135], v144
	ds_read_b128 v[136:139], v144 offset:1024
	ds_read_b128 v[140:143], v144 offset:2048
	ds_read_b128 v[144:147], v144 offset:3072
	ds_read_b128 v[148:151], v176
	ds_read_b128 v[152:155], v176 offset:1024
	ds_read_b128 v[172:175], v176 offset:2048
	ds_read_b128 v[176:179], v176 offset:3072
	s_add_u32 s98, s52, 0x100000
	s_addc_u32 s99, s53, 0
	s_mov_b32 m0, s48
	ds_read_b128 v[180:183], v189 offset:32768
	ds_read_b128 v[192:195], v189 offset:33792
	ds_read_b128 v[196:199], v189 offset:34816
	ds_read_b128 v[200:203], v189 offset:35840
	ds_read_b128 v[204:207], v189 offset:36864
	ds_read_b128 v[208:211], v189 offset:37888
	ds_read_b128 v[212:215], v189 offset:38912
	ds_read_b128 v[216:219], v189 offset:39936
	global_load_lds_dwordx4 v156, s[98:99]
	s_mov_b32 m0, s49
	s_nop 0
	global_load_lds_dwordx4 v160, s[98:99]
	s_waitcnt vmcnt(8)
	s_waitcnt lgkmcnt(0)
	s_setprio 1
	s_barrier
	v_mfma_f32_16x16x32_bf16 v[128:131], v[132:135], v[180:183], v[128:131]
	v_mfma_f32_16x16x32_bf16 v[128:131], v[136:139], v[192:195], v[128:131]
	v_mfma_f32_16x16x32_bf16 v[124:127], v[140:143], v[180:183], v[124:127]
	v_mfma_f32_16x16x32_bf16 v[124:127], v[144:147], v[192:195], v[124:127]
	v_mfma_f32_16x16x32_bf16 v[120:123], v[148:151], v[180:183], v[120:123]
	v_mfma_f32_16x16x32_bf16 v[120:123], v[152:155], v[192:195], v[120:123]
	v_mfma_f32_16x16x32_bf16 v[116:119], v[172:175], v[180:183], v[116:119]
	v_mfma_f32_16x16x32_bf16 v[116:119], v[176:179], v[192:195], v[116:119]
	v_mfma_f32_16x16x32_bf16 v[112:115], v[132:135], v[196:199], v[112:115]
	v_mfma_f32_16x16x32_bf16 v[112:115], v[136:139], v[200:203], v[112:115]
	v_mfma_f32_16x16x32_bf16 v[108:111], v[140:143], v[196:199], v[108:111]
	v_mfma_f32_16x16x32_bf16 v[108:111], v[144:147], v[200:203], v[108:111]
	v_mfma_f32_16x16x32_bf16 v[104:107], v[148:151], v[196:199], v[104:107]
	v_mfma_f32_16x16x32_bf16 v[104:107], v[152:155], v[200:203], v[104:107]
	v_mfma_f32_16x16x32_bf16 v[100:103], v[172:175], v[196:199], v[100:103]
	v_mfma_f32_16x16x32_bf16 v[100:103], v[176:179], v[200:203], v[100:103]
	v_mfma_f32_16x16x32_bf16 v[96:99], v[132:135], v[204:207], v[96:99]
	v_mfma_f32_16x16x32_bf16 v[96:99], v[136:139], v[208:211], v[96:99]
	v_mfma_f32_16x16x32_bf16 v[92:95], v[140:143], v[204:207], v[92:95]
	v_mfma_f32_16x16x32_bf16 v[92:95], v[144:147], v[208:211], v[92:95]
	v_mfma_f32_16x16x32_bf16 v[88:91], v[148:151], v[204:207], v[88:91]
	v_mfma_f32_16x16x32_bf16 v[88:91], v[152:155], v[208:211], v[88:91]
	v_mfma_f32_16x16x32_bf16 v[84:87], v[172:175], v[204:207], v[84:87]
	v_mfma_f32_16x16x32_bf16 v[84:87], v[176:179], v[208:211], v[84:87]
	v_mfma_f32_16x16x32_bf16 v[80:83], v[132:135], v[212:215], v[80:83]
	v_mfma_f32_16x16x32_bf16 v[80:83], v[136:139], v[216:219], v[80:83]
	v_mfma_f32_16x16x32_bf16 v[76:79], v[140:143], v[212:215], v[76:79]
	v_mfma_f32_16x16x32_bf16 v[76:79], v[144:147], v[216:219], v[76:79]
	v_mfma_f32_16x16x32_bf16 v[72:75], v[148:151], v[212:215], v[72:75]
	v_mfma_f32_16x16x32_bf16 v[72:75], v[152:155], v[216:219], v[72:75]
	v_mfma_f32_16x16x32_bf16 v[68:71], v[172:175], v[212:215], v[68:71]
	v_mfma_f32_16x16x32_bf16 v[68:71], v[176:179], v[216:219], v[68:71]
	s_setprio 0
	s_barrier
	s_add_i32 s0, s0, s46
	s_add_i32 m0, s0, 0xffffff80
	ds_read_b128 v[180:183], v189 offset:49152
	ds_read_b128 v[192:195], v189 offset:50176
	ds_read_b128 v[196:199], v189 offset:51200
	ds_read_b128 v[200:203], v189 offset:52224
	ds_read_b128 v[204:207], v189 offset:53248
	ds_read_b128 v[208:211], v189 offset:54272
	ds_read_b128 v[212:215], v189 offset:55296
	ds_read_b128 v[216:219], v189 offset:56320
	global_load_lds_dwordx4 v158, s[50:51] offset:128
	s_add_i32 m0, s0, 0x1f80
	s_add_i32 s0, s66, s46
	global_load_lds_dwordx4 v162, s[50:51] offset:128
	s_add_u32 s50, s50, 0x100080
	s_addc_u32 s51, s51, 0
	s_mov_b32 m0, s0
	s_nop 0
	global_load_lds_dwordx4 v158, s[50:51]
	s_add_i32 m0, s0, 0x2000
	s_nop 0
	global_load_lds_dwordx4 v162, s[50:51]
	s_add_i32 m0, s57, 0xffffff80
	s_nop 0
	global_load_lds_dwordx4 v156, s[52:53] offset:128
	s_add_i32 m0, s58, 0xffffff80
	s_nop 0
	global_load_lds_dwordx4 v160, s[52:53] offset:128
	s_waitcnt vmcnt(8)
	s_waitcnt lgkmcnt(0)
	s_setprio 1
	s_barrier
	v_mfma_f32_16x16x32_bf16 v[64:67], v[132:135], v[180:183], v[64:67]
	v_mfma_f32_16x16x32_bf16 v[64:67], v[136:139], v[192:195], v[64:67]
	v_mfma_f32_16x16x32_bf16 v[60:63], v[140:143], v[180:183], v[60:63]
	v_mfma_f32_16x16x32_bf16 v[60:63], v[144:147], v[192:195], v[60:63]
	v_mfma_f32_16x16x32_bf16 v[56:59], v[148:151], v[180:183], v[56:59]
	v_mfma_f32_16x16x32_bf16 v[56:59], v[152:155], v[192:195], v[56:59]
	v_mfma_f32_16x16x32_bf16 v[52:55], v[172:175], v[180:183], v[52:55]
	v_mfma_f32_16x16x32_bf16 v[52:55], v[176:179], v[192:195], v[52:55]
	v_mfma_f32_16x16x32_bf16 v[48:51], v[132:135], v[196:199], v[48:51]
	v_mfma_f32_16x16x32_bf16 v[48:51], v[136:139], v[200:203], v[48:51]
	v_mfma_f32_16x16x32_bf16 v[44:47], v[140:143], v[196:199], v[44:47]
	v_mfma_f32_16x16x32_bf16 v[44:47], v[144:147], v[200:203], v[44:47]
	v_mfma_f32_16x16x32_bf16 v[40:43], v[148:151], v[196:199], v[40:43]
	v_mfma_f32_16x16x32_bf16 v[40:43], v[152:155], v[200:203], v[40:43]
	v_mfma_f32_16x16x32_bf16 v[36:39], v[172:175], v[196:199], v[36:39]
	v_mfma_f32_16x16x32_bf16 v[36:39], v[176:179], v[200:203], v[36:39]
	v_mfma_f32_16x16x32_bf16 v[32:35], v[132:135], v[204:207], v[32:35]
	v_mfma_f32_16x16x32_bf16 v[32:35], v[136:139], v[208:211], v[32:35]
	v_mfma_f32_16x16x32_bf16 v[28:31], v[140:143], v[204:207], v[28:31]
	v_mfma_f32_16x16x32_bf16 v[28:31], v[144:147], v[208:211], v[28:31]
	v_mfma_f32_16x16x32_bf16 v[24:27], v[148:151], v[204:207], v[24:27]
	v_mfma_f32_16x16x32_bf16 v[24:27], v[152:155], v[208:211], v[24:27]
	v_mfma_f32_16x16x32_bf16 v[20:23], v[172:175], v[204:207], v[20:23]
	v_mfma_f32_16x16x32_bf16 v[20:23], v[176:179], v[208:211], v[20:23]
	v_mfma_f32_16x16x32_bf16 v[16:19], v[132:135], v[212:215], v[16:19]
	v_mfma_f32_16x16x32_bf16 v[16:19], v[136:139], v[216:219], v[16:19]
	v_mfma_f32_16x16x32_bf16 v[12:15], v[140:143], v[212:215], v[12:15]
	v_mfma_f32_16x16x32_bf16 v[12:15], v[144:147], v[216:219], v[12:15]
	v_mfma_f32_16x16x32_bf16 v[8:11], v[148:151], v[212:215], v[8:11]
	v_mfma_f32_16x16x32_bf16 v[8:11], v[152:155], v[216:219], v[8:11]
	v_mfma_f32_16x16x32_bf16 v[4:7], v[172:175], v[212:215], v[4:7]
	v_mfma_f32_16x16x32_bf16 v[4:7], v[176:179], v[216:219], v[4:7]
	s_setprio 0
	s_barrier
	s_add_i32 s65, s65, 2
	s_add_u32 s42, s42, 0x100
	s_addc_u32 s43, s43, 0
	s_add_u32 s63, s63, 0x100
	s_addc_u32 s64, s64, 0
	s_cmp_gt_u32 s65, 61
	s_cbranch_scc0 .LBB0_1203
	s_and_b64 vcc, exec, s[20:21]
	s_cbranch_vccz .LBB0_1206
	s_barrier

.LBB0_1288:
	ds_read_b128 v[154:157], v150
	ds_read_b128 v[158:161], v150 offset:1024
	ds_read_b128 v[162:165], v150 offset:2048
	ds_read_b128 v[166:169], v150 offset:3072
	ds_read_b128 v[170:173], v151
	ds_read_b128 v[174:177], v151 offset:1024
	ds_read_b128 v[178:181], v151 offset:2048
	ds_read_b128 v[182:185], v151 offset:3072
	s_add_u32 s0, s42, 0xfff00080
	s_addc_u32 s50, s43, -1
	s_cmp_eq_u32 s70, 12
	s_cselect_b32 s53, s29, s50
	s_cselect_b32 s52, s28, s0
	s_cselect_b32 s51, s5, s41
	s_cselect_b32 s50, s4, s31
	s_add_i32 m0, s17, 0xc000
	ds_read_b128 v[186:189], v152
	ds_read_b128 v[190:193], v152 offset:1024
	ds_read_b128 v[194:197], v152 offset:2048
	ds_read_b128 v[198:201], v152 offset:3072
	ds_read_b128 v[202:205], v152 offset:4096
	ds_read_b128 v[206:209], v152 offset:5120
	ds_read_b128 v[210:213], v152 offset:6144
	ds_read_b128 v[214:217], v152 offset:7168
	global_load_lds_dwordx4 v142, s[42:43]
	s_add_i32 m0, s17, 0xe000
	s_nop 0
	global_load_lds_dwordx4 v144, s[42:43]
	s_waitcnt vmcnt(8)
	s_waitcnt lgkmcnt(0)
	s_setprio 1
	s_barrier
	v_mfma_f32_16x16x32_bf16 v[128:131], v[154:157], v[186:189], v[128:131]
	v_mfma_f32_16x16x32_bf16 v[128:131], v[158:161], v[190:193], v[128:131]
	v_mfma_f32_16x16x32_bf16 v[124:127], v[162:165], v[186:189], v[124:127]
	v_mfma_f32_16x16x32_bf16 v[124:127], v[166:169], v[190:193], v[124:127]
	v_mfma_f32_16x16x32_bf16 v[112:115], v[170:173], v[186:189], v[112:115]
	v_mfma_f32_16x16x32_bf16 v[112:115], v[174:177], v[190:193], v[112:115]
	v_mfma_f32_16x16x32_bf16 v[108:111], v[178:181], v[186:189], v[108:111]
	v_mfma_f32_16x16x32_bf16 v[108:111], v[182:185], v[190:193], v[108:111]
	v_mfma_f32_16x16x32_bf16 v[120:123], v[154:157], v[194:197], v[120:123]
	v_mfma_f32_16x16x32_bf16 v[120:123], v[158:161], v[198:201], v[120:123]
	v_mfma_f32_16x16x32_bf16 v[116:119], v[162:165], v[194:197], v[116:119]
	v_mfma_f32_16x16x32_bf16 v[116:119], v[166:169], v[198:201], v[116:119]
	v_mfma_f32_16x16x32_bf16 v[96:99], v[170:173], v[194:197], v[96:99]
	v_mfma_f32_16x16x32_bf16 v[96:99], v[174:177], v[198:201], v[96:99]
	v_mfma_f32_16x16x32_bf16 v[92:95], v[178:181], v[194:197], v[92:95]
	v_mfma_f32_16x16x32_bf16 v[92:95], v[182:185], v[198:201], v[92:95]
	v_mfma_f32_16x16x32_bf16 v[104:107], v[154:157], v[202:205], v[104:107]
	v_mfma_f32_16x16x32_bf16 v[104:107], v[158:161], v[206:209], v[104:107]
	v_mfma_f32_16x16x32_bf16 v[100:103], v[162:165], v[202:205], v[100:103]
	v_mfma_f32_16x16x32_bf16 v[100:103], v[166:169], v[206:209], v[100:103]
	v_mfma_f32_16x16x32_bf16 v[80:83], v[170:173], v[202:205], v[80:83]
	v_mfma_f32_16x16x32_bf16 v[80:83], v[174:177], v[206:209], v[80:83]
	v_mfma_f32_16x16x32_bf16 v[76:79], v[178:181], v[202:205], v[76:79]
	v_mfma_f32_16x16x32_bf16 v[76:79], v[182:185], v[206:209], v[76:79]
	v_mfma_f32_16x16x32_bf16 v[88:91], v[154:157], v[210:213], v[88:91]
	v_mfma_f32_16x16x32_bf16 v[88:91], v[158:161], v[214:217], v[88:91]
	v_mfma_f32_16x16x32_bf16 v[84:87], v[162:165], v[210:213], v[84:87]
	v_mfma_f32_16x16x32_bf16 v[84:87], v[166:169], v[214:217], v[84:87]
	v_mfma_f32_16x16x32_bf16 v[72:75], v[170:173], v[210:213], v[72:75]
	v_mfma_f32_16x16x32_bf16 v[72:75], v[174:177], v[214:217], v[72:75]
	v_mfma_f32_16x16x32_bf16 v[68:71], v[178:181], v[210:213], v[68:71]
	v_mfma_f32_16x16x32_bf16 v[68:71], v[182:185], v[214:217], v[68:71]
	s_setprio 0
	s_barrier
	s_add_i32 s0, s60, s46
	s_mov_b32 m0, s0
	ds_read_b128 v[186:189], v152 offset:16384
	ds_read_b128 v[190:193], v152 offset:17408
	ds_read_b128 v[194:197], v152 offset:18432
	ds_read_b128 v[198:201], v152 offset:19456
	ds_read_b128 v[202:205], v152 offset:20480
	ds_read_b128 v[206:209], v152 offset:21504
	ds_read_b128 v[210:213], v152 offset:22528
	ds_read_b128 v[214:217], v152 offset:23552
	global_load_lds_dwordx4 v136, s[50:51]
	s_add_i32 m0, s0, 0x2000
	s_add_u32 s72, s50, 0x100000
	s_addc_u32 s73, s51, 0
	s_add_i32 s0, s61, s46
	global_load_lds_dwordx4 v132, s[50:51]
	s_mov_b32 m0, s0
	s_nop 0
	global_load_lds_dwordx4 v136, s[72:73]
	s_add_i32 m0, s0, 0x2000
	s_nop 0
	global_load_lds_dwordx4 v132, s[72:73]
	s_mov_b32 m0, s17
	s_nop 0
	global_load_lds_dwordx4 v138, s[52:53]
	s_mov_b32 m0, s47
	s_nop 0
	global_load_lds_dwordx4 v134, s[52:53]
	s_waitcnt vmcnt(8)
	s_waitcnt lgkmcnt(0)
	s_setprio 1
	s_barrier
	v_mfma_f32_16x16x32_bf16 v[64:67], v[154:157], v[186:189], v[64:67]
	v_mfma_f32_16x16x32_bf16 v[64:67], v[158:161], v[190:193], v[64:67]
	v_mfma_f32_16x16x32_bf16 v[60:63], v[162:165], v[186:189], v[60:63]
	v_mfma_f32_16x16x32_bf16 v[60:63], v[166:169], v[190:193], v[60:63]
	v_mfma_f32_16x16x32_bf16 v[48:51], v[170:173], v[186:189], v[48:51]
	v_mfma_f32_16x16x32_bf16 v[48:51], v[174:177], v[190:193], v[48:51]
	v_mfma_f32_16x16x32_bf16 v[44:47], v[178:181], v[186:189], v[44:47]
	v_mfma_f32_16x16x32_bf16 v[44:47], v[182:185], v[190:193], v[44:47]
	v_mfma_f32_16x16x32_bf16 v[56:59], v[154:157], v[194:197], v[56:59]
	v_mfma_f32_16x16x32_bf16 v[56:59], v[158:161], v[198:201], v[56:59]
	v_mfma_f32_16x16x32_bf16 v[52:55], v[162:165], v[194:197], v[52:55]
	v_mfma_f32_16x16x32_bf16 v[52:55], v[166:169], v[198:201], v[52:55]
	v_mfma_f32_16x16x32_bf16 v[32:35], v[170:173], v[194:197], v[32:35]
	v_mfma_f32_16x16x32_bf16 v[32:35], v[174:177], v[198:201], v[32:35]
	v_mfma_f32_16x16x32_bf16 v[28:31], v[178:181], v[194:197], v[28:31]
	v_mfma_f32_16x16x32_bf16 v[28:31], v[182:185], v[198:201], v[28:31]
	v_mfma_f32_16x16x32_bf16 v[40:43], v[154:157], v[202:205], v[40:43]
	v_mfma_f32_16x16x32_bf16 v[40:43], v[158:161], v[206:209], v[40:43]
	v_mfma_f32_16x16x32_bf16 v[36:39], v[162:165], v[202:205], v[36:39]
	v_mfma_f32_16x16x32_bf16 v[36:39], v[166:169], v[206:209], v[36:39]
	v_mfma_f32_16x16x32_bf16 v[16:19], v[170:173], v[202:205], v[16:19]
	v_mfma_f32_16x16x32_bf16 v[16:19], v[174:177], v[206:209], v[16:19]
	v_mfma_f32_16x16x32_bf16 v[12:15], v[178:181], v[202:205], v[12:15]
	v_mfma_f32_16x16x32_bf16 v[12:15], v[182:185], v[206:209], v[12:15]
	v_mfma_f32_16x16x32_bf16 v[24:27], v[154:157], v[210:213], v[24:27]
	v_mfma_f32_16x16x32_bf16 v[24:27], v[158:161], v[214:217], v[24:27]
	v_mfma_f32_16x16x32_bf16 v[20:23], v[162:165], v[210:213], v[20:23]
	v_mfma_f32_16x16x32_bf16 v[20:23], v[166:169], v[214:217], v[20:23]
	v_mfma_f32_16x16x32_bf16 v[8:11], v[170:173], v[210:213], v[8:11]
	v_mfma_f32_16x16x32_bf16 v[8:11], v[174:177], v[214:217], v[8:11]
	v_mfma_f32_16x16x32_bf16 v[4:7], v[178:181], v[210:213], v[4:7]
	v_mfma_f32_16x16x32_bf16 v[4:7], v[182:185], v[214:217], v[4:7]
	s_setprio 0
	s_barrier
	s_add_i32 s0, 0, 0x18000
	v_add_u32_e32 v140, s0, v3
	s_add_i32 s71, 0, 0x1c000
	ds_read_b128 v[154:157], v140
	ds_read_b128 v[158:161], v140 offset:1024
	ds_read_b128 v[162:165], v140 offset:2048
	ds_read_b128 v[166:169], v140 offset:3072
	v_add_u32_e32 v140, s71, v3
	ds_read_b128 v[170:173], v140
	ds_read_b128 v[174:177], v140 offset:1024
	ds_read_b128 v[178:181], v140 offset:2048
	ds_read_b128 v[182:185], v140 offset:3072
	s_add_u32 s98, s52, 0x100000
	s_addc_u32 s99, s53, 0
	s_mov_b32 m0, s48
	ds_read_b128 v[186:189], v152 offset:32768
	ds_read_b128 v[190:193], v152 offset:33792
	ds_read_b128 v[194:197], v152 offset:34816
	ds_read_b128 v[198:201], v152 offset:35840
	ds_read_b128 v[202:205], v152 offset:36864
	ds_read_b128 v[206:209], v152 offset:37888
	ds_read_b128 v[210:213], v152 offset:38912
	ds_read_b128 v[214:217], v152 offset:39936
	global_load_lds_dwordx4 v138, s[98:99]
	s_mov_b32 m0, s49
	s_nop 0
	global_load_lds_dwordx4 v134, s[98:99]
	s_waitcnt vmcnt(8)
	s_waitcnt lgkmcnt(0)
	s_setprio 1
	s_barrier
	v_mfma_f32_16x16x32_bf16 v[128:131], v[154:157], v[186:189], v[128:131]
	v_mfma_f32_16x16x32_bf16 v[128:131], v[158:161], v[190:193], v[128:131]
	v_mfma_f32_16x16x32_bf16 v[124:127], v[162:165], v[186:189], v[124:127]
	v_mfma_f32_16x16x32_bf16 v[124:127], v[166:169], v[190:193], v[124:127]
	v_mfma_f32_16x16x32_bf16 v[112:115], v[170:173], v[186:189], v[112:115]
	v_mfma_f32_16x16x32_bf16 v[112:115], v[174:177], v[190:193], v[112:115]
	v_mfma_f32_16x16x32_bf16 v[108:111], v[178:181], v[186:189], v[108:111]
	v_mfma_f32_16x16x32_bf16 v[108:111], v[182:185], v[190:193], v[108:111]
	v_mfma_f32_16x16x32_bf16 v[120:123], v[154:157], v[194:197], v[120:123]
	v_mfma_f32_16x16x32_bf16 v[120:123], v[158:161], v[198:201], v[120:123]
	v_mfma_f32_16x16x32_bf16 v[116:119], v[162:165], v[194:197], v[116:119]
	v_mfma_f32_16x16x32_bf16 v[116:119], v[166:169], v[198:201], v[116:119]
	v_mfma_f32_16x16x32_bf16 v[96:99], v[170:173], v[194:197], v[96:99]
	v_mfma_f32_16x16x32_bf16 v[96:99], v[174:177], v[198:201], v[96:99]
	v_mfma_f32_16x16x32_bf16 v[92:95], v[178:181], v[194:197], v[92:95]
	v_mfma_f32_16x16x32_bf16 v[92:95], v[182:185], v[198:201], v[92:95]
	v_mfma_f32_16x16x32_bf16 v[104:107], v[154:157], v[202:205], v[104:107]
	v_mfma_f32_16x16x32_bf16 v[104:107], v[158:161], v[206:209], v[104:107]
	v_mfma_f32_16x16x32_bf16 v[100:103], v[162:165], v[202:205], v[100:103]
	v_mfma_f32_16x16x32_bf16 v[100:103], v[166:169], v[206:209], v[100:103]
	v_mfma_f32_16x16x32_bf16 v[80:83], v[170:173], v[202:205], v[80:83]
	v_mfma_f32_16x16x32_bf16 v[80:83], v[174:177], v[206:209], v[80:83]
	v_mfma_f32_16x16x32_bf16 v[76:79], v[178:181], v[202:205], v[76:79]
	v_mfma_f32_16x16x32_bf16 v[76:79], v[182:185], v[206:209], v[76:79]
	v_mfma_f32_16x16x32_bf16 v[88:91], v[154:157], v[210:213], v[88:91]
	v_mfma_f32_16x16x32_bf16 v[88:91], v[158:161], v[214:217], v[88:91]
	v_mfma_f32_16x16x32_bf16 v[84:87], v[162:165], v[210:213], v[84:87]
	v_mfma_f32_16x16x32_bf16 v[84:87], v[166:169], v[214:217], v[84:87]
	v_mfma_f32_16x16x32_bf16 v[72:75], v[170:173], v[210:213], v[72:75]
	v_mfma_f32_16x16x32_bf16 v[72:75], v[174:177], v[214:217], v[72:75]
	v_mfma_f32_16x16x32_bf16 v[68:71], v[178:181], v[210:213], v[68:71]
	v_mfma_f32_16x16x32_bf16 v[68:71], v[182:185], v[214:217], v[68:71]
	s_setprio 0
	s_barrier
	s_add_i32 s0, s0, s46
	s_add_i32 m0, s0, 0xffffff80
	ds_read_b128 v[186:189], v152 offset:49152
	ds_read_b128 v[190:193], v152 offset:50176
	ds_read_b128 v[194:197], v152 offset:51200
	ds_read_b128 v[198:201], v152 offset:52224
	ds_read_b128 v[202:205], v152 offset:53248
	ds_read_b128 v[206:209], v152 offset:54272
	ds_read_b128 v[210:213], v152 offset:55296
	ds_read_b128 v[214:217], v152 offset:56320
	global_load_lds_dwordx4 v136, s[50:51] offset:128
	s_add_i32 m0, s0, 0x1f80
	s_add_i32 s0, s71, s46
	global_load_lds_dwordx4 v132, s[50:51] offset:128
	s_add_u32 s50, s50, 0x100080
	s_addc_u32 s51, s51, 0
	s_mov_b32 m0, s0
	s_nop 0
	global_load_lds_dwordx4 v136, s[50:51]
	s_add_i32 m0, s0, 0x2000
	s_nop 0
	global_load_lds_dwordx4 v132, s[50:51]
	s_add_i32 m0, s58, 0xffffff80
	s_nop 0
	global_load_lds_dwordx4 v138, s[52:53] offset:128
	s_add_i32 m0, s59, 0xffffff80
	s_nop 0
	global_load_lds_dwordx4 v134, s[52:53] offset:128
	s_waitcnt vmcnt(8)
	s_waitcnt lgkmcnt(0)
	s_setprio 1
	s_barrier
	v_mfma_f32_16x16x32_bf16 v[64:67], v[154:157], v[186:189], v[64:67]
	v_mfma_f32_16x16x32_bf16 v[64:67], v[158:161], v[190:193], v[64:67]
	v_mfma_f32_16x16x32_bf16 v[60:63], v[162:165], v[186:189], v[60:63]
	v_mfma_f32_16x16x32_bf16 v[60:63], v[166:169], v[190:193], v[60:63]
	v_mfma_f32_16x16x32_bf16 v[48:51], v[170:173], v[186:189], v[48:51]
	v_mfma_f32_16x16x32_bf16 v[48:51], v[174:177], v[190:193], v[48:51]
	v_mfma_f32_16x16x32_bf16 v[44:47], v[178:181], v[186:189], v[44:47]
	v_mfma_f32_16x16x32_bf16 v[44:47], v[182:185], v[190:193], v[44:47]
	v_mfma_f32_16x16x32_bf16 v[56:59], v[154:157], v[194:197], v[56:59]
	v_mfma_f32_16x16x32_bf16 v[56:59], v[158:161], v[198:201], v[56:59]
	v_mfma_f32_16x16x32_bf16 v[52:55], v[162:165], v[194:197], v[52:55]
	v_mfma_f32_16x16x32_bf16 v[52:55], v[166:169], v[198:201], v[52:55]
	v_mfma_f32_16x16x32_bf16 v[32:35], v[170:173], v[194:197], v[32:35]
	v_mfma_f32_16x16x32_bf16 v[32:35], v[174:177], v[198:201], v[32:35]
	v_mfma_f32_16x16x32_bf16 v[28:31], v[178:181], v[194:197], v[28:31]
	v_mfma_f32_16x16x32_bf16 v[28:31], v[182:185], v[198:201], v[28:31]
	v_mfma_f32_16x16x32_bf16 v[40:43], v[154:157], v[202:205], v[40:43]
	v_mfma_f32_16x16x32_bf16 v[40:43], v[158:161], v[206:209], v[40:43]
	v_mfma_f32_16x16x32_bf16 v[36:39], v[162:165], v[202:205], v[36:39]
	v_mfma_f32_16x16x32_bf16 v[36:39], v[166:169], v[206:209], v[36:39]
	v_mfma_f32_16x16x32_bf16 v[16:19], v[170:173], v[202:205], v[16:19]
	v_mfma_f32_16x16x32_bf16 v[16:19], v[174:177], v[206:209], v[16:19]
	v_mfma_f32_16x16x32_bf16 v[12:15], v[178:181], v[202:205], v[12:15]
	v_mfma_f32_16x16x32_bf16 v[12:15], v[182:185], v[206:209], v[12:15]
	v_mfma_f32_16x16x32_bf16 v[24:27], v[154:157], v[210:213], v[24:27]
	v_mfma_f32_16x16x32_bf16 v[24:27], v[158:161], v[214:217], v[24:27]
	v_mfma_f32_16x16x32_bf16 v[20:23], v[162:165], v[210:213], v[20:23]
	v_mfma_f32_16x16x32_bf16 v[20:23], v[166:169], v[214:217], v[20:23]
	v_mfma_f32_16x16x32_bf16 v[8:11], v[170:173], v[210:213], v[8:11]
	v_mfma_f32_16x16x32_bf16 v[8:11], v[174:177], v[214:217], v[8:11]
	v_mfma_f32_16x16x32_bf16 v[4:7], v[178:181], v[210:213], v[4:7]
	v_mfma_f32_16x16x32_bf16 v[4:7], v[182:185], v[214:217], v[4:7]
	s_setprio 0
	s_barrier
	s_add_i32 s70, s70, 2
	s_add_u32 s42, s42, 0x100
	s_addc_u32 s43, s43, 0
	s_add_u32 s31, s31, 0x100
	s_addc_u32 s41, s41, 0
	s_cmp_gt_u32 s70, 13
	s_cbranch_scc0 .LBB0_1288
	s_and_b64 vcc, exec, s[14:15]
	s_cbranch_vccz .LBB0_1291
	s_barrier

.LBB0_1415:
	ds_read_b128 v[132:135], v187
	ds_read_b128 v[136:139], v187 offset:1024
	ds_read_b128 v[140:143], v187 offset:2048
	ds_read_b128 v[144:147], v187 offset:3072
	ds_read_b128 v[148:151], v188
	ds_read_b128 v[152:155], v188 offset:1024
	ds_read_b128 v[172:175], v188 offset:2048
	ds_read_b128 v[176:179], v188 offset:3072
	s_add_u32 s0, s42, 0xfffe0080
	s_addc_u32 s50, s43, -1
	s_cmp_eq_u32 s64, 4
	s_cselect_b32 s53, s25, s50
	s_cselect_b32 s52, s31, s0
	s_cselect_b32 s51, s23, s63
	s_cselect_b32 s50, s61, s62
	s_add_i32 m0, s41, 0xc000
	ds_read_b128 v[180:183], v189
	ds_read_b128 v[192:195], v189 offset:1024
	ds_read_b128 v[196:199], v189 offset:2048
	ds_read_b128 v[200:203], v189 offset:3072
	ds_read_b128 v[204:207], v189 offset:4096
	ds_read_b128 v[208:211], v189 offset:5120
	ds_read_b128 v[212:215], v189 offset:6144
	ds_read_b128 v[216:219], v189 offset:7168
	global_load_lds_dwordx4 v164, s[42:43]
	s_add_i32 m0, s41, 0xe000
	s_nop 0
	global_load_lds_dwordx4 v166, s[42:43]
	s_waitcnt vmcnt(8)
	s_waitcnt lgkmcnt(0)
	s_setprio 1
	s_barrier
	v_mfma_f32_16x16x32_bf16 v[128:131], v[132:135], v[180:183], v[128:131]
	v_mfma_f32_16x16x32_bf16 v[128:131], v[136:139], v[192:195], v[128:131]
	v_mfma_f32_16x16x32_bf16 v[124:127], v[140:143], v[180:183], v[124:127]
	v_mfma_f32_16x16x32_bf16 v[124:127], v[144:147], v[192:195], v[124:127]
	v_mfma_f32_16x16x32_bf16 v[120:123], v[148:151], v[180:183], v[120:123]
	v_mfma_f32_16x16x32_bf16 v[120:123], v[152:155], v[192:195], v[120:123]
	v_mfma_f32_16x16x32_bf16 v[116:119], v[172:175], v[180:183], v[116:119]
	v_mfma_f32_16x16x32_bf16 v[116:119], v[176:179], v[192:195], v[116:119]
	v_mfma_f32_16x16x32_bf16 v[112:115], v[132:135], v[196:199], v[112:115]
	v_mfma_f32_16x16x32_bf16 v[112:115], v[136:139], v[200:203], v[112:115]
	v_mfma_f32_16x16x32_bf16 v[108:111], v[140:143], v[196:199], v[108:111]
	v_mfma_f32_16x16x32_bf16 v[108:111], v[144:147], v[200:203], v[108:111]
	v_mfma_f32_16x16x32_bf16 v[104:107], v[148:151], v[196:199], v[104:107]
	v_mfma_f32_16x16x32_bf16 v[104:107], v[152:155], v[200:203], v[104:107]
	v_mfma_f32_16x16x32_bf16 v[100:103], v[172:175], v[196:199], v[100:103]
	v_mfma_f32_16x16x32_bf16 v[100:103], v[176:179], v[200:203], v[100:103]
	v_mfma_f32_16x16x32_bf16 v[96:99], v[132:135], v[204:207], v[96:99]
	v_mfma_f32_16x16x32_bf16 v[96:99], v[136:139], v[208:211], v[96:99]
	v_mfma_f32_16x16x32_bf16 v[92:95], v[140:143], v[204:207], v[92:95]
	v_mfma_f32_16x16x32_bf16 v[92:95], v[144:147], v[208:211], v[92:95]
	v_mfma_f32_16x16x32_bf16 v[88:91], v[148:151], v[204:207], v[88:91]
	v_mfma_f32_16x16x32_bf16 v[88:91], v[152:155], v[208:211], v[88:91]
	v_mfma_f32_16x16x32_bf16 v[84:87], v[172:175], v[204:207], v[84:87]
	v_mfma_f32_16x16x32_bf16 v[84:87], v[176:179], v[208:211], v[84:87]
	v_mfma_f32_16x16x32_bf16 v[80:83], v[132:135], v[212:215], v[80:83]
	v_mfma_f32_16x16x32_bf16 v[80:83], v[136:139], v[216:219], v[80:83]
	v_mfma_f32_16x16x32_bf16 v[76:79], v[140:143], v[212:215], v[76:79]
	v_mfma_f32_16x16x32_bf16 v[76:79], v[144:147], v[216:219], v[76:79]
	v_mfma_f32_16x16x32_bf16 v[72:75], v[148:151], v[212:215], v[72:75]
	v_mfma_f32_16x16x32_bf16 v[72:75], v[152:155], v[216:219], v[72:75]
	v_mfma_f32_16x16x32_bf16 v[68:71], v[172:175], v[212:215], v[68:71]
	v_mfma_f32_16x16x32_bf16 v[68:71], v[176:179], v[216:219], v[68:71]
	s_setprio 0
	s_barrier
	s_add_i32 s0, s58, s45
	s_mov_b32 m0, s0
	ds_read_b128 v[180:183], v189 offset:16384
	ds_read_b128 v[192:195], v189 offset:17408
	ds_read_b128 v[196:199], v189 offset:18432
	ds_read_b128 v[200:203], v189 offset:19456
	ds_read_b128 v[204:207], v189 offset:20480
	ds_read_b128 v[208:211], v189 offset:21504
	ds_read_b128 v[212:215], v189 offset:22528
	ds_read_b128 v[216:219], v189 offset:23552
	global_load_lds_dwordx4 v158, s[50:51]
	s_add_i32 m0, s0, 0x2000
	s_add_u32 s66, s50, 0x20000
	s_addc_u32 s67, s51, 0
	s_add_i32 s0, s59, s45
	global_load_lds_dwordx4 v162, s[50:51]
	s_mov_b32 m0, s0
	s_nop 0
	global_load_lds_dwordx4 v158, s[66:67]
	s_add_i32 m0, s0, 0x2000
	s_nop 0
	global_load_lds_dwordx4 v162, s[66:67]
	s_mov_b32 m0, s41
	s_nop 0
	global_load_lds_dwordx4 v156, s[52:53]
	s_mov_b32 m0, s46
	s_nop 0
	global_load_lds_dwordx4 v160, s[52:53]
	s_waitcnt vmcnt(8)
	s_waitcnt lgkmcnt(0)
	s_setprio 1
	s_barrier
	v_mfma_f32_16x16x32_bf16 v[64:67], v[132:135], v[180:183], v[64:67]
	v_mfma_f32_16x16x32_bf16 v[64:67], v[136:139], v[192:195], v[64:67]
	v_mfma_f32_16x16x32_bf16 v[60:63], v[140:143], v[180:183], v[60:63]
	v_mfma_f32_16x16x32_bf16 v[60:63], v[144:147], v[192:195], v[60:63]
	v_mfma_f32_16x16x32_bf16 v[56:59], v[148:151], v[180:183], v[56:59]
	v_mfma_f32_16x16x32_bf16 v[56:59], v[152:155], v[192:195], v[56:59]
	v_mfma_f32_16x16x32_bf16 v[52:55], v[172:175], v[180:183], v[52:55]
	v_mfma_f32_16x16x32_bf16 v[52:55], v[176:179], v[192:195], v[52:55]
	v_mfma_f32_16x16x32_bf16 v[48:51], v[132:135], v[196:199], v[48:51]
	v_mfma_f32_16x16x32_bf16 v[48:51], v[136:139], v[200:203], v[48:51]
	v_mfma_f32_16x16x32_bf16 v[44:47], v[140:143], v[196:199], v[44:47]
	v_mfma_f32_16x16x32_bf16 v[44:47], v[144:147], v[200:203], v[44:47]
	v_mfma_f32_16x16x32_bf16 v[40:43], v[148:151], v[196:199], v[40:43]
	v_mfma_f32_16x16x32_bf16 v[40:43], v[152:155], v[200:203], v[40:43]
	v_mfma_f32_16x16x32_bf16 v[36:39], v[172:175], v[196:199], v[36:39]
	v_mfma_f32_16x16x32_bf16 v[36:39], v[176:179], v[200:203], v[36:39]
	v_mfma_f32_16x16x32_bf16 v[32:35], v[132:135], v[204:207], v[32:35]
	v_mfma_f32_16x16x32_bf16 v[32:35], v[136:139], v[208:211], v[32:35]
	v_mfma_f32_16x16x32_bf16 v[28:31], v[140:143], v[204:207], v[28:31]
	v_mfma_f32_16x16x32_bf16 v[28:31], v[144:147], v[208:211], v[28:31]
	v_mfma_f32_16x16x32_bf16 v[24:27], v[148:151], v[204:207], v[24:27]
	v_mfma_f32_16x16x32_bf16 v[24:27], v[152:155], v[208:211], v[24:27]
	v_mfma_f32_16x16x32_bf16 v[20:23], v[172:175], v[204:207], v[20:23]
	v_mfma_f32_16x16x32_bf16 v[20:23], v[176:179], v[208:211], v[20:23]
	v_mfma_f32_16x16x32_bf16 v[16:19], v[132:135], v[212:215], v[16:19]
	v_mfma_f32_16x16x32_bf16 v[16:19], v[136:139], v[216:219], v[16:19]
	v_mfma_f32_16x16x32_bf16 v[12:15], v[140:143], v[212:215], v[12:15]
	v_mfma_f32_16x16x32_bf16 v[12:15], v[144:147], v[216:219], v[12:15]
	v_mfma_f32_16x16x32_bf16 v[8:11], v[148:151], v[212:215], v[8:11]
	v_mfma_f32_16x16x32_bf16 v[8:11], v[152:155], v[216:219], v[8:11]
	v_mfma_f32_16x16x32_bf16 v[4:7], v[172:175], v[212:215], v[4:7]
	v_mfma_f32_16x16x32_bf16 v[4:7], v[176:179], v[216:219], v[4:7]
	s_setprio 0
	s_barrier
	s_add_i32 s0, 0, 0x18000
	s_add_i32 s65, 0, 0x1c000
	v_add_u32_e32 v144, s0, v3
	v_add_u32_e32 v176, s65, v3
	ds_read_b128 v[132:135], v144
	ds_read_b128 v[136:139], v144 offset:1024
	ds_read_b128 v[140:143], v144 offset:2048
	ds_read_b128 v[144:147], v144 offset:3072
	ds_read_b128 v[148:151], v176
	ds_read_b128 v[152:155], v176 offset:1024
	ds_read_b128 v[172:175], v176 offset:2048
	ds_read_b128 v[176:179], v176 offset:3072
	s_add_u32 s98, s52, 0x20000
	s_addc_u32 s99, s53, 0
	s_mov_b32 m0, s47
	ds_read_b128 v[180:183], v189 offset:32768
	ds_read_b128 v[192:195], v189 offset:33792
	ds_read_b128 v[196:199], v189 offset:34816
	ds_read_b128 v[200:203], v189 offset:35840
	ds_read_b128 v[204:207], v189 offset:36864
	ds_read_b128 v[208:211], v189 offset:37888
	ds_read_b128 v[212:215], v189 offset:38912
	ds_read_b128 v[216:219], v189 offset:39936
	global_load_lds_dwordx4 v156, s[98:99]
	s_mov_b32 m0, s48
	s_nop 0
	global_load_lds_dwordx4 v160, s[98:99]
	s_waitcnt vmcnt(8)
	s_waitcnt lgkmcnt(0)
	s_setprio 1
	s_barrier
	v_mfma_f32_16x16x32_bf16 v[128:131], v[132:135], v[180:183], v[128:131]
	v_mfma_f32_16x16x32_bf16 v[128:131], v[136:139], v[192:195], v[128:131]
	v_mfma_f32_16x16x32_bf16 v[124:127], v[140:143], v[180:183], v[124:127]
	v_mfma_f32_16x16x32_bf16 v[124:127], v[144:147], v[192:195], v[124:127]
	v_mfma_f32_16x16x32_bf16 v[120:123], v[148:151], v[180:183], v[120:123]
	v_mfma_f32_16x16x32_bf16 v[120:123], v[152:155], v[192:195], v[120:123]
	v_mfma_f32_16x16x32_bf16 v[116:119], v[172:175], v[180:183], v[116:119]
	v_mfma_f32_16x16x32_bf16 v[116:119], v[176:179], v[192:195], v[116:119]
	v_mfma_f32_16x16x32_bf16 v[112:115], v[132:135], v[196:199], v[112:115]
	v_mfma_f32_16x16x32_bf16 v[112:115], v[136:139], v[200:203], v[112:115]
	v_mfma_f32_16x16x32_bf16 v[108:111], v[140:143], v[196:199], v[108:111]
	v_mfma_f32_16x16x32_bf16 v[108:111], v[144:147], v[200:203], v[108:111]
	v_mfma_f32_16x16x32_bf16 v[104:107], v[148:151], v[196:199], v[104:107]
	v_mfma_f32_16x16x32_bf16 v[104:107], v[152:155], v[200:203], v[104:107]
	v_mfma_f32_16x16x32_bf16 v[100:103], v[172:175], v[196:199], v[100:103]
	v_mfma_f32_16x16x32_bf16 v[100:103], v[176:179], v[200:203], v[100:103]
	v_mfma_f32_16x16x32_bf16 v[96:99], v[132:135], v[204:207], v[96:99]
	v_mfma_f32_16x16x32_bf16 v[96:99], v[136:139], v[208:211], v[96:99]
	v_mfma_f32_16x16x32_bf16 v[92:95], v[140:143], v[204:207], v[92:95]
	v_mfma_f32_16x16x32_bf16 v[92:95], v[144:147], v[208:211], v[92:95]
	v_mfma_f32_16x16x32_bf16 v[88:91], v[148:151], v[204:207], v[88:91]
	v_mfma_f32_16x16x32_bf16 v[88:91], v[152:155], v[208:211], v[88:91]
	v_mfma_f32_16x16x32_bf16 v[84:87], v[172:175], v[204:207], v[84:87]
	v_mfma_f32_16x16x32_bf16 v[84:87], v[176:179], v[208:211], v[84:87]
	v_mfma_f32_16x16x32_bf16 v[80:83], v[132:135], v[212:215], v[80:83]
	v_mfma_f32_16x16x32_bf16 v[80:83], v[136:139], v[216:219], v[80:83]
	v_mfma_f32_16x16x32_bf16 v[76:79], v[140:143], v[212:215], v[76:79]
	v_mfma_f32_16x16x32_bf16 v[76:79], v[144:147], v[216:219], v[76:79]
	v_mfma_f32_16x16x32_bf16 v[72:75], v[148:151], v[212:215], v[72:75]
	v_mfma_f32_16x16x32_bf16 v[72:75], v[152:155], v[216:219], v[72:75]
	v_mfma_f32_16x16x32_bf16 v[68:71], v[172:175], v[212:215], v[68:71]
	v_mfma_f32_16x16x32_bf16 v[68:71], v[176:179], v[216:219], v[68:71]
	s_setprio 0
	s_barrier
	s_add_i32 s0, s0, s45
	s_add_i32 m0, s0, 0xffffff80
	ds_read_b128 v[180:183], v189 offset:49152
	ds_read_b128 v[192:195], v189 offset:50176
	ds_read_b128 v[196:199], v189 offset:51200
	ds_read_b128 v[200:203], v189 offset:52224
	ds_read_b128 v[204:207], v189 offset:53248
	ds_read_b128 v[208:211], v189 offset:54272
	ds_read_b128 v[212:215], v189 offset:55296
	ds_read_b128 v[216:219], v189 offset:56320
	global_load_lds_dwordx4 v158, s[50:51] offset:128
	s_add_i32 m0, s0, 0x1f80
	s_add_i32 s0, s65, s45
	global_load_lds_dwordx4 v162, s[50:51] offset:128
	s_add_u32 s50, s50, 0x20080
	s_addc_u32 s51, s51, 0
	s_mov_b32 m0, s0
	s_nop 0
	global_load_lds_dwordx4 v158, s[50:51]
	s_add_i32 m0, s0, 0x2000
	s_nop 0
	global_load_lds_dwordx4 v162, s[50:51]
	s_add_i32 m0, s56, 0xffffff80
	s_nop 0
	global_load_lds_dwordx4 v156, s[52:53] offset:128
	s_add_i32 m0, s57, 0xffffff80
	s_nop 0
	global_load_lds_dwordx4 v160, s[52:53] offset:128
	s_waitcnt vmcnt(8)
	s_waitcnt lgkmcnt(0)
	s_setprio 1
	s_barrier
	v_mfma_f32_16x16x32_bf16 v[64:67], v[132:135], v[180:183], v[64:67]
	v_mfma_f32_16x16x32_bf16 v[64:67], v[136:139], v[192:195], v[64:67]
	v_mfma_f32_16x16x32_bf16 v[60:63], v[140:143], v[180:183], v[60:63]
	v_mfma_f32_16x16x32_bf16 v[60:63], v[144:147], v[192:195], v[60:63]
	v_mfma_f32_16x16x32_bf16 v[56:59], v[148:151], v[180:183], v[56:59]
	v_mfma_f32_16x16x32_bf16 v[56:59], v[152:155], v[192:195], v[56:59]
	v_mfma_f32_16x16x32_bf16 v[52:55], v[172:175], v[180:183], v[52:55]
	v_mfma_f32_16x16x32_bf16 v[52:55], v[176:179], v[192:195], v[52:55]
	v_mfma_f32_16x16x32_bf16 v[48:51], v[132:135], v[196:199], v[48:51]
	v_mfma_f32_16x16x32_bf16 v[48:51], v[136:139], v[200:203], v[48:51]
	v_mfma_f32_16x16x32_bf16 v[44:47], v[140:143], v[196:199], v[44:47]
	v_mfma_f32_16x16x32_bf16 v[44:47], v[144:147], v[200:203], v[44:47]
	v_mfma_f32_16x16x32_bf16 v[40:43], v[148:151], v[196:199], v[40:43]
	v_mfma_f32_16x16x32_bf16 v[40:43], v[152:155], v[200:203], v[40:43]
	v_mfma_f32_16x16x32_bf16 v[36:39], v[172:175], v[196:199], v[36:39]
	v_mfma_f32_16x16x32_bf16 v[36:39], v[176:179], v[200:203], v[36:39]
	v_mfma_f32_16x16x32_bf16 v[32:35], v[132:135], v[204:207], v[32:35]
	v_mfma_f32_16x16x32_bf16 v[32:35], v[136:139], v[208:211], v[32:35]
	v_mfma_f32_16x16x32_bf16 v[28:31], v[140:143], v[204:207], v[28:31]
	v_mfma_f32_16x16x32_bf16 v[28:31], v[144:147], v[208:211], v[28:31]
	v_mfma_f32_16x16x32_bf16 v[24:27], v[148:151], v[204:207], v[24:27]
	v_mfma_f32_16x16x32_bf16 v[24:27], v[152:155], v[208:211], v[24:27]
	v_mfma_f32_16x16x32_bf16 v[20:23], v[172:175], v[204:207], v[20:23]
	v_mfma_f32_16x16x32_bf16 v[20:23], v[176:179], v[208:211], v[20:23]
	v_mfma_f32_16x16x32_bf16 v[16:19], v[132:135], v[212:215], v[16:19]
	v_mfma_f32_16x16x32_bf16 v[16:19], v[136:139], v[216:219], v[16:19]
	v_mfma_f32_16x16x32_bf16 v[12:15], v[140:143], v[212:215], v[12:15]
	v_mfma_f32_16x16x32_bf16 v[12:15], v[144:147], v[216:219], v[12:15]
	v_mfma_f32_16x16x32_bf16 v[8:11], v[148:151], v[212:215], v[8:11]
	v_mfma_f32_16x16x32_bf16 v[8:11], v[152:155], v[216:219], v[8:11]
	v_mfma_f32_16x16x32_bf16 v[4:7], v[172:175], v[212:215], v[4:7]
	v_mfma_f32_16x16x32_bf16 v[4:7], v[176:179], v[216:219], v[4:7]
	s_setprio 0
	s_barrier
	s_add_i32 s64, s64, 2
	s_add_u32 s42, s42, 0x100
	s_addc_u32 s43, s43, 0
	s_add_u32 s62, s62, 0x100
	s_addc_u32 s63, s63, 0
	s_cmp_gt_u32 s64, 5
	s_cbranch_scc0 .LBB0_1415
	s_and_b64 vcc, exec, s[16:17]
	s_cbranch_vccz .LBB0_1418
	s_barrier

.LBB0_1503:
	ds_read_b128 v[132:135], v159
	ds_read_b128 v[164:167], v159 offset:1024
	ds_read_b128 v[168:171], v159 offset:2048
	ds_read_b128 v[172:175], v159 offset:3072
	ds_read_b128 v[176:179], v160
	ds_read_b128 v[180:183], v160 offset:1024
	ds_read_b128 v[184:187], v160 offset:2048
	ds_read_b128 v[188:191], v160 offset:3072
	s_add_u32 s0, s54, 0xfff00080
	s_addc_u32 s56, s55, -1
	s_cmp_eq_u32 s75, 60
	s_cselect_b32 s59, s31, s56
	s_cselect_b32 s58, s71, s0
	s_cselect_b32 s57, s29, s74
	s_cselect_b32 s56, s72, s73
	s_add_i32 m0, s48, 0xc000
	ds_read_b128 v[192:195], v161
	ds_read_b128 v[196:199], v161 offset:1024
	ds_read_b128 v[200:203], v161 offset:2048
	ds_read_b128 v[204:207], v161 offset:3072
	ds_read_b128 v[208:211], v161 offset:4096
	ds_read_b128 v[212:215], v161 offset:5120
	ds_read_b128 v[216:219], v161 offset:6144
	ds_read_b128 v[220:223], v161 offset:7168
	global_load_lds_dwordx4 v148, s[54:55]
	s_add_i32 m0, s48, 0xe000
	s_nop 0
	global_load_lds_dwordx4 v150, s[54:55]
	s_waitcnt vmcnt(8)
	s_waitcnt lgkmcnt(0)
	s_setprio 1
	s_barrier
	v_mfma_f32_16x16x32_bf16 v[136:139], v[132:135], v[192:195], v[136:139]
	v_mfma_f32_16x16x32_bf16 v[136:139], v[164:167], v[196:199], v[136:139]
	v_mfma_f32_16x16x32_bf16 v[128:131], v[168:171], v[192:195], v[128:131]
	v_mfma_f32_16x16x32_bf16 v[128:131], v[172:175], v[196:199], v[128:131]
	v_mfma_f32_16x16x32_bf16 v[124:127], v[176:179], v[192:195], v[124:127]
	v_mfma_f32_16x16x32_bf16 v[124:127], v[180:183], v[196:199], v[124:127]
	v_mfma_f32_16x16x32_bf16 v[120:123], v[184:187], v[192:195], v[120:123]
	v_mfma_f32_16x16x32_bf16 v[120:123], v[188:191], v[196:199], v[120:123]
	v_mfma_f32_16x16x32_bf16 v[116:119], v[132:135], v[200:203], v[116:119]
	v_mfma_f32_16x16x32_bf16 v[116:119], v[164:167], v[204:207], v[116:119]
	v_mfma_f32_16x16x32_bf16 v[112:115], v[168:171], v[200:203], v[112:115]
	v_mfma_f32_16x16x32_bf16 v[112:115], v[172:175], v[204:207], v[112:115]
	v_mfma_f32_16x16x32_bf16 v[108:111], v[176:179], v[200:203], v[108:111]
	v_mfma_f32_16x16x32_bf16 v[108:111], v[180:183], v[204:207], v[108:111]
	v_mfma_f32_16x16x32_bf16 v[104:107], v[184:187], v[200:203], v[104:107]
	v_mfma_f32_16x16x32_bf16 v[104:107], v[188:191], v[204:207], v[104:107]
	v_mfma_f32_16x16x32_bf16 v[100:103], v[132:135], v[208:211], v[100:103]
	v_mfma_f32_16x16x32_bf16 v[100:103], v[164:167], v[212:215], v[100:103]
	v_mfma_f32_16x16x32_bf16 v[96:99], v[168:171], v[208:211], v[96:99]
	v_mfma_f32_16x16x32_bf16 v[96:99], v[172:175], v[212:215], v[96:99]
	v_mfma_f32_16x16x32_bf16 v[92:95], v[176:179], v[208:211], v[92:95]
	v_mfma_f32_16x16x32_bf16 v[92:95], v[180:183], v[212:215], v[92:95]
	v_mfma_f32_16x16x32_bf16 v[88:91], v[184:187], v[208:211], v[88:91]
	v_mfma_f32_16x16x32_bf16 v[88:91], v[188:191], v[212:215], v[88:91]
	v_mfma_f32_16x16x32_bf16 v[84:87], v[132:135], v[216:219], v[84:87]
	v_mfma_f32_16x16x32_bf16 v[84:87], v[164:167], v[220:223], v[84:87]
	v_mfma_f32_16x16x32_bf16 v[80:83], v[168:171], v[216:219], v[80:83]
	v_mfma_f32_16x16x32_bf16 v[80:83], v[172:175], v[220:223], v[80:83]
	v_mfma_f32_16x16x32_bf16 v[76:79], v[176:179], v[216:219], v[76:79]
	v_mfma_f32_16x16x32_bf16 v[76:79], v[180:183], v[220:223], v[76:79]
	v_mfma_f32_16x16x32_bf16 v[72:75], v[184:187], v[216:219], v[72:75]
	v_mfma_f32_16x16x32_bf16 v[72:75], v[188:191], v[220:223], v[72:75]
	s_setprio 0
	s_barrier
	s_add_i32 s0, s65, s47
	s_mov_b32 m0, s0
	ds_read_b128 v[192:195], v161 offset:16384
	ds_read_b128 v[196:199], v161 offset:17408
	ds_read_b128 v[200:203], v161 offset:18432
	ds_read_b128 v[204:207], v161 offset:19456
	ds_read_b128 v[208:211], v161 offset:20480
	ds_read_b128 v[212:215], v161 offset:21504
	ds_read_b128 v[216:219], v161 offset:22528
	ds_read_b128 v[220:223], v161 offset:23552
	global_load_lds_dwordx4 v142, s[56:57]
	s_add_i32 m0, s0, 0x2000
	s_add_u32 s76, s56, 0x100000
	s_addc_u32 s77, s57, 0
	s_add_i32 s0, s66, s47
	global_load_lds_dwordx4 v146, s[56:57]
	s_mov_b32 m0, s0
	s_nop 0
	global_load_lds_dwordx4 v142, s[76:77]
	s_add_i32 m0, s0, 0x2000
	s_nop 0
	global_load_lds_dwordx4 v146, s[76:77]
	s_mov_b32 m0, s48
	s_nop 0
	global_load_lds_dwordx4 v140, s[58:59]
	s_mov_b32 m0, s49
	s_nop 0
	global_load_lds_dwordx4 v144, s[58:59]
	s_waitcnt vmcnt(8)
	s_waitcnt lgkmcnt(0)
	s_setprio 1
	s_barrier
	v_mfma_f32_16x16x32_bf16 v[68:71], v[132:135], v[192:195], v[68:71]
	v_mfma_f32_16x16x32_bf16 v[68:71], v[164:167], v[196:199], v[68:71]
	v_mfma_f32_16x16x32_bf16 v[64:67], v[168:171], v[192:195], v[64:67]
	v_mfma_f32_16x16x32_bf16 v[64:67], v[172:175], v[196:199], v[64:67]
	v_mfma_f32_16x16x32_bf16 v[60:63], v[176:179], v[192:195], v[60:63]
	v_mfma_f32_16x16x32_bf16 v[60:63], v[180:183], v[196:199], v[60:63]
	v_mfma_f32_16x16x32_bf16 v[56:59], v[184:187], v[192:195], v[56:59]
	v_mfma_f32_16x16x32_bf16 v[56:59], v[188:191], v[196:199], v[56:59]
	v_mfma_f32_16x16x32_bf16 v[52:55], v[132:135], v[200:203], v[52:55]
	v_mfma_f32_16x16x32_bf16 v[52:55], v[164:167], v[204:207], v[52:55]
	v_mfma_f32_16x16x32_bf16 v[48:51], v[168:171], v[200:203], v[48:51]
	v_mfma_f32_16x16x32_bf16 v[48:51], v[172:175], v[204:207], v[48:51]
	v_mfma_f32_16x16x32_bf16 v[44:47], v[176:179], v[200:203], v[44:47]
	v_mfma_f32_16x16x32_bf16 v[44:47], v[180:183], v[204:207], v[44:47]
	v_mfma_f32_16x16x32_bf16 v[40:43], v[184:187], v[200:203], v[40:43]
	v_mfma_f32_16x16x32_bf16 v[40:43], v[188:191], v[204:207], v[40:43]
	v_mfma_f32_16x16x32_bf16 v[36:39], v[132:135], v[208:211], v[36:39]
	v_mfma_f32_16x16x32_bf16 v[36:39], v[164:167], v[212:215], v[36:39]
	v_mfma_f32_16x16x32_bf16 v[32:35], v[168:171], v[208:211], v[32:35]
	v_mfma_f32_16x16x32_bf16 v[32:35], v[172:175], v[212:215], v[32:35]
	v_mfma_f32_16x16x32_bf16 v[28:31], v[176:179], v[208:211], v[28:31]
	v_mfma_f32_16x16x32_bf16 v[28:31], v[180:183], v[212:215], v[28:31]
	v_mfma_f32_16x16x32_bf16 v[24:27], v[184:187], v[208:211], v[24:27]
	v_mfma_f32_16x16x32_bf16 v[24:27], v[188:191], v[212:215], v[24:27]
	v_mfma_f32_16x16x32_bf16 v[20:23], v[132:135], v[216:219], v[20:23]
	v_mfma_f32_16x16x32_bf16 v[20:23], v[164:167], v[220:223], v[20:23]
	v_mfma_f32_16x16x32_bf16 v[16:19], v[168:171], v[216:219], v[16:19]
	v_mfma_f32_16x16x32_bf16 v[16:19], v[172:175], v[220:223], v[16:19]
	v_mfma_f32_16x16x32_bf16 v[12:15], v[176:179], v[216:219], v[12:15]
	v_mfma_f32_16x16x32_bf16 v[12:15], v[180:183], v[220:223], v[12:15]
	v_mfma_f32_16x16x32_bf16 v[8:11], v[184:187], v[216:219], v[8:11]
	v_mfma_f32_16x16x32_bf16 v[8:11], v[188:191], v[220:223], v[8:11]
	s_setprio 0
	s_barrier
	s_add_i32 s0, 0, 0x18000
	s_add_i32 s76, 0, 0x1c000
	v_add_u32_e32 v172, s0, v156
	v_add_u32_e32 v188, s76, v156
	ds_read_b128 v[132:135], v172
	ds_read_b128 v[164:167], v172 offset:1024
	ds_read_b128 v[168:171], v172 offset:2048
	ds_read_b128 v[172:175], v172 offset:3072
	ds_read_b128 v[176:179], v188
	ds_read_b128 v[180:183], v188 offset:1024
	ds_read_b128 v[184:187], v188 offset:2048
	ds_read_b128 v[188:191], v188 offset:3072
	s_add_u32 s98, s58, 0x100000
	s_addc_u32 s99, s59, 0
	s_mov_b32 m0, s51
	ds_read_b128 v[192:195], v161 offset:32768
	ds_read_b128 v[196:199], v161 offset:33792
	ds_read_b128 v[200:203], v161 offset:34816
	ds_read_b128 v[204:207], v161 offset:35840
	ds_read_b128 v[208:211], v161 offset:36864
	ds_read_b128 v[212:215], v161 offset:37888
	ds_read_b128 v[216:219], v161 offset:38912
	ds_read_b128 v[220:223], v161 offset:39936
	global_load_lds_dwordx4 v140, s[98:99]
	s_mov_b32 m0, s53
	s_nop 0
	global_load_lds_dwordx4 v144, s[98:99]
	s_waitcnt vmcnt(8)
	s_waitcnt lgkmcnt(0)
	s_setprio 1
	s_barrier
	v_mfma_f32_16x16x32_bf16 v[136:139], v[132:135], v[192:195], v[136:139]
	v_mfma_f32_16x16x32_bf16 v[136:139], v[164:167], v[196:199], v[136:139]
	v_mfma_f32_16x16x32_bf16 v[128:131], v[168:171], v[192:195], v[128:131]
	v_mfma_f32_16x16x32_bf16 v[128:131], v[172:175], v[196:199], v[128:131]
	v_mfma_f32_16x16x32_bf16 v[124:127], v[176:179], v[192:195], v[124:127]
	v_mfma_f32_16x16x32_bf16 v[124:127], v[180:183], v[196:199], v[124:127]
	v_mfma_f32_16x16x32_bf16 v[120:123], v[184:187], v[192:195], v[120:123]
	v_mfma_f32_16x16x32_bf16 v[120:123], v[188:191], v[196:199], v[120:123]
	v_mfma_f32_16x16x32_bf16 v[116:119], v[132:135], v[200:203], v[116:119]
	v_mfma_f32_16x16x32_bf16 v[116:119], v[164:167], v[204:207], v[116:119]
	v_mfma_f32_16x16x32_bf16 v[112:115], v[168:171], v[200:203], v[112:115]
	v_mfma_f32_16x16x32_bf16 v[112:115], v[172:175], v[204:207], v[112:115]
	v_mfma_f32_16x16x32_bf16 v[108:111], v[176:179], v[200:203], v[108:111]
	v_mfma_f32_16x16x32_bf16 v[108:111], v[180:183], v[204:207], v[108:111]
	v_mfma_f32_16x16x32_bf16 v[104:107], v[184:187], v[200:203], v[104:107]
	v_mfma_f32_16x16x32_bf16 v[104:107], v[188:191], v[204:207], v[104:107]
	v_mfma_f32_16x16x32_bf16 v[100:103], v[132:135], v[208:211], v[100:103]
	v_mfma_f32_16x16x32_bf16 v[100:103], v[164:167], v[212:215], v[100:103]
	v_mfma_f32_16x16x32_bf16 v[96:99], v[168:171], v[208:211], v[96:99]
	v_mfma_f32_16x16x32_bf16 v[96:99], v[172:175], v[212:215], v[96:99]
	v_mfma_f32_16x16x32_bf16 v[92:95], v[176:179], v[208:211], v[92:95]
	v_mfma_f32_16x16x32_bf16 v[92:95], v[180:183], v[212:215], v[92:95]
	v_mfma_f32_16x16x32_bf16 v[88:91], v[184:187], v[208:211], v[88:91]
	v_mfma_f32_16x16x32_bf16 v[88:91], v[188:191], v[212:215], v[88:91]
	v_mfma_f32_16x16x32_bf16 v[84:87], v[132:135], v[216:219], v[84:87]
	v_mfma_f32_16x16x32_bf16 v[84:87], v[164:167], v[220:223], v[84:87]
	v_mfma_f32_16x16x32_bf16 v[80:83], v[168:171], v[216:219], v[80:83]
	v_mfma_f32_16x16x32_bf16 v[80:83], v[172:175], v[220:223], v[80:83]
	v_mfma_f32_16x16x32_bf16 v[76:79], v[176:179], v[216:219], v[76:79]
	v_mfma_f32_16x16x32_bf16 v[76:79], v[180:183], v[220:223], v[76:79]
	v_mfma_f32_16x16x32_bf16 v[72:75], v[184:187], v[216:219], v[72:75]
	v_mfma_f32_16x16x32_bf16 v[72:75], v[188:191], v[220:223], v[72:75]
	s_setprio 0
	s_barrier
	s_add_i32 s0, s0, s47
	s_add_i32 m0, s0, 0xffffff80
	ds_read_b128 v[192:195], v161 offset:49152
	ds_read_b128 v[196:199], v161 offset:50176
	ds_read_b128 v[200:203], v161 offset:51200
	ds_read_b128 v[204:207], v161 offset:52224
	ds_read_b128 v[208:211], v161 offset:53248
	ds_read_b128 v[212:215], v161 offset:54272
	ds_read_b128 v[216:219], v161 offset:55296
	ds_read_b128 v[220:223], v161 offset:56320
	global_load_lds_dwordx4 v142, s[56:57] offset:128
	s_add_i32 m0, s0, 0x1f80
	s_add_i32 s0, s76, s47
	global_load_lds_dwordx4 v146, s[56:57] offset:128
	s_add_u32 s56, s56, 0x100080
	s_addc_u32 s57, s57, 0
	s_mov_b32 m0, s0
	s_nop 0
	global_load_lds_dwordx4 v142, s[56:57]
	s_add_i32 m0, s0, 0x2000
	s_nop 0
	global_load_lds_dwordx4 v146, s[56:57]
	s_add_i32 m0, s62, 0xffffff80
	s_nop 0
	global_load_lds_dwordx4 v140, s[58:59] offset:128
	s_add_i32 m0, s63, 0xffffff80
	s_nop 0
	global_load_lds_dwordx4 v144, s[58:59] offset:128
	s_waitcnt vmcnt(8)
	s_waitcnt lgkmcnt(0)
	s_setprio 1
	s_barrier
	v_mfma_f32_16x16x32_bf16 v[68:71], v[132:135], v[192:195], v[68:71]
	v_mfma_f32_16x16x32_bf16 v[68:71], v[164:167], v[196:199], v[68:71]
	v_mfma_f32_16x16x32_bf16 v[64:67], v[168:171], v[192:195], v[64:67]
	v_mfma_f32_16x16x32_bf16 v[64:67], v[172:175], v[196:199], v[64:67]
	v_mfma_f32_16x16x32_bf16 v[60:63], v[176:179], v[192:195], v[60:63]
	v_mfma_f32_16x16x32_bf16 v[60:63], v[180:183], v[196:199], v[60:63]
	v_mfma_f32_16x16x32_bf16 v[56:59], v[184:187], v[192:195], v[56:59]
	v_mfma_f32_16x16x32_bf16 v[56:59], v[188:191], v[196:199], v[56:59]
	v_mfma_f32_16x16x32_bf16 v[52:55], v[132:135], v[200:203], v[52:55]
	v_mfma_f32_16x16x32_bf16 v[52:55], v[164:167], v[204:207], v[52:55]
	v_mfma_f32_16x16x32_bf16 v[48:51], v[168:171], v[200:203], v[48:51]
	v_mfma_f32_16x16x32_bf16 v[48:51], v[172:175], v[204:207], v[48:51]
	v_mfma_f32_16x16x32_bf16 v[44:47], v[176:179], v[200:203], v[44:47]
	v_mfma_f32_16x16x32_bf16 v[44:47], v[180:183], v[204:207], v[44:47]
	v_mfma_f32_16x16x32_bf16 v[40:43], v[184:187], v[200:203], v[40:43]
	v_mfma_f32_16x16x32_bf16 v[40:43], v[188:191], v[204:207], v[40:43]
	v_mfma_f32_16x16x32_bf16 v[36:39], v[132:135], v[208:211], v[36:39]
	v_mfma_f32_16x16x32_bf16 v[36:39], v[164:167], v[212:215], v[36:39]
	v_mfma_f32_16x16x32_bf16 v[32:35], v[168:171], v[208:211], v[32:35]
	v_mfma_f32_16x16x32_bf16 v[32:35], v[172:175], v[212:215], v[32:35]
	v_mfma_f32_16x16x32_bf16 v[28:31], v[176:179], v[208:211], v[28:31]
	v_mfma_f32_16x16x32_bf16 v[28:31], v[180:183], v[212:215], v[28:31]
	v_mfma_f32_16x16x32_bf16 v[24:27], v[184:187], v[208:211], v[24:27]
	v_mfma_f32_16x16x32_bf16 v[24:27], v[188:191], v[212:215], v[24:27]
	v_mfma_f32_16x16x32_bf16 v[20:23], v[132:135], v[216:219], v[20:23]
	v_mfma_f32_16x16x32_bf16 v[20:23], v[164:167], v[220:223], v[20:23]
	v_mfma_f32_16x16x32_bf16 v[16:19], v[168:171], v[216:219], v[16:19]
	v_mfma_f32_16x16x32_bf16 v[16:19], v[172:175], v[220:223], v[16:19]
	v_mfma_f32_16x16x32_bf16 v[12:15], v[176:179], v[216:219], v[12:15]
	v_mfma_f32_16x16x32_bf16 v[12:15], v[180:183], v[220:223], v[12:15]
	v_mfma_f32_16x16x32_bf16 v[8:11], v[184:187], v[216:219], v[8:11]
	v_mfma_f32_16x16x32_bf16 v[8:11], v[188:191], v[220:223], v[8:11]
	s_setprio 0
	s_barrier
	s_add_i32 s75, s75, 2
	s_add_u32 s54, s54, 0x100
	s_addc_u32 s55, s55, 0
	s_add_u32 s73, s73, 0x100
	s_addc_u32 s74, s74, 0
	s_cmp_gt_u32 s75, 61
	s_cbranch_scc0 .LBB0_1503
	s_and_b64 vcc, exec, s[26:27]
	s_cbranch_vccz .LBB0_1506
	s_barrier

.LBB0_1672:
	ds_read_b128 v[132:135], v193
	ds_read_b128 v[136:139], v193 offset:1024
	ds_read_b128 v[140:143], v193 offset:2048
	ds_read_b128 v[144:147], v193 offset:3072
	ds_read_b128 v[148:151], v194
	ds_read_b128 v[152:155], v194 offset:1024
	ds_read_b128 v[172:175], v194 offset:2048
	ds_read_b128 v[176:179], v194 offset:3072
	s_add_u32 s0, s30, 0xffd50080
	s_addc_u32 s42, s31, -1
	s_cmpk_eq_i32 s66, 0xa8
	s_cselect_b32 s51, s7, s42
	s_cselect_b32 s50, s6, s0
	s_cselect_b32 s43, s29, s65
	s_cselect_b32 s42, s28, s64
	s_add_i32 m0, s46, 0xc000
	ds_read_b128 v[180:183], v195
	ds_read_b128 v[198:201], v195 offset:1024
	ds_read_b128 v[202:205], v195 offset:2048
	ds_read_b128 v[206:209], v195 offset:3072
	ds_read_b128 v[210:213], v195 offset:4096
	ds_read_b128 v[214:217], v195 offset:5120
	ds_read_b128 v[218:221], v195 offset:6144
	ds_read_b128 v[222:225], v195 offset:7168
	global_load_lds_dwordx4 v164, s[30:31]
	s_add_i32 m0, s46, 0xe000
	s_nop 0
	global_load_lds_dwordx4 v166, s[30:31]
	s_waitcnt vmcnt(8)
	s_waitcnt lgkmcnt(0)
	s_setprio 1
	s_barrier
	v_mfma_f32_16x16x32_bf16 v[128:131], v[132:135], v[180:183], v[128:131]
	v_mfma_f32_16x16x32_bf16 v[128:131], v[136:139], v[198:201], v[128:131]
	v_mfma_f32_16x16x32_bf16 v[124:127], v[140:143], v[180:183], v[124:127]
	v_mfma_f32_16x16x32_bf16 v[124:127], v[144:147], v[198:201], v[124:127]
	v_mfma_f32_16x16x32_bf16 v[120:123], v[148:151], v[180:183], v[120:123]
	v_mfma_f32_16x16x32_bf16 v[120:123], v[152:155], v[198:201], v[120:123]
	v_mfma_f32_16x16x32_bf16 v[116:119], v[172:175], v[180:183], v[116:119]
	v_mfma_f32_16x16x32_bf16 v[116:119], v[176:179], v[198:201], v[116:119]
	v_mfma_f32_16x16x32_bf16 v[112:115], v[132:135], v[202:205], v[112:115]
	v_mfma_f32_16x16x32_bf16 v[112:115], v[136:139], v[206:209], v[112:115]
	v_mfma_f32_16x16x32_bf16 v[108:111], v[140:143], v[202:205], v[108:111]
	v_mfma_f32_16x16x32_bf16 v[108:111], v[144:147], v[206:209], v[108:111]
	v_mfma_f32_16x16x32_bf16 v[104:107], v[148:151], v[202:205], v[104:107]
	v_mfma_f32_16x16x32_bf16 v[104:107], v[152:155], v[206:209], v[104:107]
	v_mfma_f32_16x16x32_bf16 v[100:103], v[172:175], v[202:205], v[100:103]
	v_mfma_f32_16x16x32_bf16 v[100:103], v[176:179], v[206:209], v[100:103]
	v_mfma_f32_16x16x32_bf16 v[96:99], v[132:135], v[210:213], v[96:99]
	v_mfma_f32_16x16x32_bf16 v[96:99], v[136:139], v[214:217], v[96:99]
	v_mfma_f32_16x16x32_bf16 v[92:95], v[140:143], v[210:213], v[92:95]
	v_mfma_f32_16x16x32_bf16 v[92:95], v[144:147], v[214:217], v[92:95]
	v_mfma_f32_16x16x32_bf16 v[88:91], v[148:151], v[210:213], v[88:91]
	v_mfma_f32_16x16x32_bf16 v[88:91], v[152:155], v[214:217], v[88:91]
	v_mfma_f32_16x16x32_bf16 v[84:87], v[172:175], v[210:213], v[84:87]
	v_mfma_f32_16x16x32_bf16 v[84:87], v[176:179], v[214:217], v[84:87]
	v_mfma_f32_16x16x32_bf16 v[80:83], v[132:135], v[218:221], v[80:83]
	v_mfma_f32_16x16x32_bf16 v[80:83], v[136:139], v[222:225], v[80:83]
	v_mfma_f32_16x16x32_bf16 v[76:79], v[140:143], v[218:221], v[76:79]
	v_mfma_f32_16x16x32_bf16 v[76:79], v[144:147], v[222:225], v[76:79]
	v_mfma_f32_16x16x32_bf16 v[72:75], v[148:151], v[218:221], v[72:75]
	v_mfma_f32_16x16x32_bf16 v[72:75], v[152:155], v[222:225], v[72:75]
	v_mfma_f32_16x16x32_bf16 v[68:71], v[172:175], v[218:221], v[68:71]
	v_mfma_f32_16x16x32_bf16 v[68:71], v[176:179], v[222:225], v[68:71]
	s_setprio 0
	s_barrier
	s_add_i32 s0, s57, s45
	s_mov_b32 m0, s0
	ds_read_b128 v[180:183], v195 offset:16384
	ds_read_b128 v[198:201], v195 offset:17408
	ds_read_b128 v[202:205], v195 offset:18432
	ds_read_b128 v[206:209], v195 offset:19456
	ds_read_b128 v[210:213], v195 offset:20480
	ds_read_b128 v[214:217], v195 offset:21504
	ds_read_b128 v[218:221], v195 offset:22528
	ds_read_b128 v[222:225], v195 offset:23552
	global_load_lds_dwordx4 v158, s[42:43]
	s_add_i32 m0, s0, 0x2000
	s_add_u32 s70, s42, 0x2b0000
	s_addc_u32 s71, s43, 0
	s_add_i32 s0, s58, s45
	global_load_lds_dwordx4 v162, s[42:43]
	s_mov_b32 m0, s0
	s_nop 0
	global_load_lds_dwordx4 v158, s[70:71]
	s_add_i32 m0, s0, 0x2000
	s_nop 0
	global_load_lds_dwordx4 v162, s[70:71]
	s_mov_b32 m0, s46
	s_nop 0
	global_load_lds_dwordx4 v156, s[50:51]
	s_mov_b32 m0, s47
	s_nop 0
	global_load_lds_dwordx4 v160, s[50:51]
	s_waitcnt vmcnt(8)
	s_waitcnt lgkmcnt(0)
	s_setprio 1
	s_barrier
	v_mfma_f32_16x16x32_bf16 v[64:67], v[132:135], v[180:183], v[64:67]
	v_mfma_f32_16x16x32_bf16 v[64:67], v[136:139], v[198:201], v[64:67]
	v_mfma_f32_16x16x32_bf16 v[60:63], v[140:143], v[180:183], v[60:63]
	v_mfma_f32_16x16x32_bf16 v[60:63], v[144:147], v[198:201], v[60:63]
	v_mfma_f32_16x16x32_bf16 v[56:59], v[148:151], v[180:183], v[56:59]
	v_mfma_f32_16x16x32_bf16 v[56:59], v[152:155], v[198:201], v[56:59]
	v_mfma_f32_16x16x32_bf16 v[52:55], v[172:175], v[180:183], v[52:55]
	v_mfma_f32_16x16x32_bf16 v[52:55], v[176:179], v[198:201], v[52:55]
	v_mfma_f32_16x16x32_bf16 v[48:51], v[132:135], v[202:205], v[48:51]
	v_mfma_f32_16x16x32_bf16 v[48:51], v[136:139], v[206:209], v[48:51]
	v_mfma_f32_16x16x32_bf16 v[44:47], v[140:143], v[202:205], v[44:47]
	v_mfma_f32_16x16x32_bf16 v[44:47], v[144:147], v[206:209], v[44:47]
	v_mfma_f32_16x16x32_bf16 v[40:43], v[148:151], v[202:205], v[40:43]
	v_mfma_f32_16x16x32_bf16 v[40:43], v[152:155], v[206:209], v[40:43]
	v_mfma_f32_16x16x32_bf16 v[36:39], v[172:175], v[202:205], v[36:39]
	v_mfma_f32_16x16x32_bf16 v[36:39], v[176:179], v[206:209], v[36:39]
	v_mfma_f32_16x16x32_bf16 v[32:35], v[132:135], v[210:213], v[32:35]
	v_mfma_f32_16x16x32_bf16 v[32:35], v[136:139], v[214:217], v[32:35]
	v_mfma_f32_16x16x32_bf16 v[28:31], v[140:143], v[210:213], v[28:31]
	v_mfma_f32_16x16x32_bf16 v[28:31], v[144:147], v[214:217], v[28:31]
	v_mfma_f32_16x16x32_bf16 v[24:27], v[148:151], v[210:213], v[24:27]
	v_mfma_f32_16x16x32_bf16 v[24:27], v[152:155], v[214:217], v[24:27]
	v_mfma_f32_16x16x32_bf16 v[20:23], v[172:175], v[210:213], v[20:23]
	v_mfma_f32_16x16x32_bf16 v[20:23], v[176:179], v[214:217], v[20:23]
	v_mfma_f32_16x16x32_bf16 v[16:19], v[132:135], v[218:221], v[16:19]
	v_mfma_f32_16x16x32_bf16 v[16:19], v[136:139], v[222:225], v[16:19]
	v_mfma_f32_16x16x32_bf16 v[12:15], v[140:143], v[218:221], v[12:15]
	v_mfma_f32_16x16x32_bf16 v[12:15], v[144:147], v[222:225], v[12:15]
	v_mfma_f32_16x16x32_bf16 v[8:11], v[148:151], v[218:221], v[8:11]
	v_mfma_f32_16x16x32_bf16 v[8:11], v[152:155], v[222:225], v[8:11]
	v_mfma_f32_16x16x32_bf16 v[4:7], v[172:175], v[218:221], v[4:7]
	v_mfma_f32_16x16x32_bf16 v[4:7], v[176:179], v[222:225], v[4:7]
	s_setprio 0
	s_barrier
	s_add_i32 s0, 0, 0x18000
	s_add_i32 s67, 0, 0x1c000
	v_add_u32_e32 v144, s0, v191
	v_add_u32_e32 v176, s67, v191
	ds_read_b128 v[132:135], v144
	ds_read_b128 v[136:139], v144 offset:1024
	ds_read_b128 v[140:143], v144 offset:2048
	ds_read_b128 v[144:147], v144 offset:3072
	ds_read_b128 v[148:151], v176
	ds_read_b128 v[152:155], v176 offset:1024
	ds_read_b128 v[172:175], v176 offset:2048
	ds_read_b128 v[176:179], v176 offset:3072
	s_add_u32 s98, s50, 0x2b0000
	s_addc_u32 s99, s51, 0
	s_mov_b32 m0, s48
	ds_read_b128 v[180:183], v195 offset:32768
	ds_read_b128 v[198:201], v195 offset:33792
	ds_read_b128 v[202:205], v195 offset:34816
	ds_read_b128 v[206:209], v195 offset:35840
	ds_read_b128 v[210:213], v195 offset:36864
	ds_read_b128 v[214:217], v195 offset:37888
	ds_read_b128 v[218:221], v195 offset:38912
	ds_read_b128 v[222:225], v195 offset:39936
	global_load_lds_dwordx4 v156, s[98:99]
	s_mov_b32 m0, s49
	s_nop 0
	global_load_lds_dwordx4 v160, s[98:99]
	s_waitcnt vmcnt(8)
	s_waitcnt lgkmcnt(0)
	s_setprio 1
	s_barrier
	v_mfma_f32_16x16x32_bf16 v[128:131], v[132:135], v[180:183], v[128:131]
	v_mfma_f32_16x16x32_bf16 v[128:131], v[136:139], v[198:201], v[128:131]
	v_mfma_f32_16x16x32_bf16 v[124:127], v[140:143], v[180:183], v[124:127]
	v_mfma_f32_16x16x32_bf16 v[124:127], v[144:147], v[198:201], v[124:127]
	v_mfma_f32_16x16x32_bf16 v[120:123], v[148:151], v[180:183], v[120:123]
	v_mfma_f32_16x16x32_bf16 v[120:123], v[152:155], v[198:201], v[120:123]
	v_mfma_f32_16x16x32_bf16 v[116:119], v[172:175], v[180:183], v[116:119]
	v_mfma_f32_16x16x32_bf16 v[116:119], v[176:179], v[198:201], v[116:119]
	v_mfma_f32_16x16x32_bf16 v[112:115], v[132:135], v[202:205], v[112:115]
	v_mfma_f32_16x16x32_bf16 v[112:115], v[136:139], v[206:209], v[112:115]
	v_mfma_f32_16x16x32_bf16 v[108:111], v[140:143], v[202:205], v[108:111]
	v_mfma_f32_16x16x32_bf16 v[108:111], v[144:147], v[206:209], v[108:111]
	v_mfma_f32_16x16x32_bf16 v[104:107], v[148:151], v[202:205], v[104:107]
	v_mfma_f32_16x16x32_bf16 v[104:107], v[152:155], v[206:209], v[104:107]
	v_mfma_f32_16x16x32_bf16 v[100:103], v[172:175], v[202:205], v[100:103]
	v_mfma_f32_16x16x32_bf16 v[100:103], v[176:179], v[206:209], v[100:103]
	v_mfma_f32_16x16x32_bf16 v[96:99], v[132:135], v[210:213], v[96:99]
	v_mfma_f32_16x16x32_bf16 v[96:99], v[136:139], v[214:217], v[96:99]
	v_mfma_f32_16x16x32_bf16 v[92:95], v[140:143], v[210:213], v[92:95]
	v_mfma_f32_16x16x32_bf16 v[92:95], v[144:147], v[214:217], v[92:95]
	v_mfma_f32_16x16x32_bf16 v[88:91], v[148:151], v[210:213], v[88:91]
	v_mfma_f32_16x16x32_bf16 v[88:91], v[152:155], v[214:217], v[88:91]
	v_mfma_f32_16x16x32_bf16 v[84:87], v[172:175], v[210:213], v[84:87]
	v_mfma_f32_16x16x32_bf16 v[84:87], v[176:179], v[214:217], v[84:87]
	v_mfma_f32_16x16x32_bf16 v[80:83], v[132:135], v[218:221], v[80:83]
	v_mfma_f32_16x16x32_bf16 v[80:83], v[136:139], v[222:225], v[80:83]
	v_mfma_f32_16x16x32_bf16 v[76:79], v[140:143], v[218:221], v[76:79]
	v_mfma_f32_16x16x32_bf16 v[76:79], v[144:147], v[222:225], v[76:79]
	v_mfma_f32_16x16x32_bf16 v[72:75], v[148:151], v[218:221], v[72:75]
	v_mfma_f32_16x16x32_bf16 v[72:75], v[152:155], v[222:225], v[72:75]
	v_mfma_f32_16x16x32_bf16 v[68:71], v[172:175], v[218:221], v[68:71]
	v_mfma_f32_16x16x32_bf16 v[68:71], v[176:179], v[222:225], v[68:71]
	s_setprio 0
	s_barrier
	s_add_i32 s0, s0, s45
	s_add_i32 m0, s0, 0xffffff80
	ds_read_b128 v[180:183], v195 offset:49152
	ds_read_b128 v[198:201], v195 offset:50176
	ds_read_b128 v[202:205], v195 offset:51200
	ds_read_b128 v[206:209], v195 offset:52224
	ds_read_b128 v[210:213], v195 offset:53248
	ds_read_b128 v[214:217], v195 offset:54272
	ds_read_b128 v[218:221], v195 offset:55296
	ds_read_b128 v[222:225], v195 offset:56320
	global_load_lds_dwordx4 v158, s[42:43] offset:128
	s_add_i32 m0, s0, 0x1f80
	s_add_i32 s0, s67, s45
	global_load_lds_dwordx4 v162, s[42:43] offset:128
	s_add_u32 s42, s42, 0x2b0080
	s_addc_u32 s43, s43, 0
	s_mov_b32 m0, s0
	s_nop 0
	global_load_lds_dwordx4 v158, s[42:43]
	s_add_i32 m0, s0, 0x2000
	s_nop 0
	global_load_lds_dwordx4 v162, s[42:43]
	s_add_i32 m0, s55, 0xffffff80
	s_nop 0
	global_load_lds_dwordx4 v156, s[50:51] offset:128
	s_add_i32 m0, s56, 0xffffff80
	s_nop 0
	global_load_lds_dwordx4 v160, s[50:51] offset:128
	s_waitcnt vmcnt(8)
	s_waitcnt lgkmcnt(0)
	s_setprio 1
	s_barrier
	v_mfma_f32_16x16x32_bf16 v[64:67], v[132:135], v[180:183], v[64:67]
	v_mfma_f32_16x16x32_bf16 v[64:67], v[136:139], v[198:201], v[64:67]
	v_mfma_f32_16x16x32_bf16 v[60:63], v[140:143], v[180:183], v[60:63]
	v_mfma_f32_16x16x32_bf16 v[60:63], v[144:147], v[198:201], v[60:63]
	v_mfma_f32_16x16x32_bf16 v[56:59], v[148:151], v[180:183], v[56:59]
	v_mfma_f32_16x16x32_bf16 v[56:59], v[152:155], v[198:201], v[56:59]
	v_mfma_f32_16x16x32_bf16 v[52:55], v[172:175], v[180:183], v[52:55]
	v_mfma_f32_16x16x32_bf16 v[52:55], v[176:179], v[198:201], v[52:55]
	v_mfma_f32_16x16x32_bf16 v[48:51], v[132:135], v[202:205], v[48:51]
	v_mfma_f32_16x16x32_bf16 v[48:51], v[136:139], v[206:209], v[48:51]
	v_mfma_f32_16x16x32_bf16 v[44:47], v[140:143], v[202:205], v[44:47]
	v_mfma_f32_16x16x32_bf16 v[44:47], v[144:147], v[206:209], v[44:47]
	v_mfma_f32_16x16x32_bf16 v[40:43], v[148:151], v[202:205], v[40:43]
	v_mfma_f32_16x16x32_bf16 v[40:43], v[152:155], v[206:209], v[40:43]
	v_mfma_f32_16x16x32_bf16 v[36:39], v[172:175], v[202:205], v[36:39]
	v_mfma_f32_16x16x32_bf16 v[36:39], v[176:179], v[206:209], v[36:39]
	v_mfma_f32_16x16x32_bf16 v[32:35], v[132:135], v[210:213], v[32:35]
	v_mfma_f32_16x16x32_bf16 v[32:35], v[136:139], v[214:217], v[32:35]
	v_mfma_f32_16x16x32_bf16 v[28:31], v[140:143], v[210:213], v[28:31]
	v_mfma_f32_16x16x32_bf16 v[28:31], v[144:147], v[214:217], v[28:31]
	v_mfma_f32_16x16x32_bf16 v[24:27], v[148:151], v[210:213], v[24:27]
	v_mfma_f32_16x16x32_bf16 v[24:27], v[152:155], v[214:217], v[24:27]
	v_mfma_f32_16x16x32_bf16 v[20:23], v[172:175], v[210:213], v[20:23]
	v_mfma_f32_16x16x32_bf16 v[20:23], v[176:179], v[214:217], v[20:23]
	v_mfma_f32_16x16x32_bf16 v[16:19], v[132:135], v[218:221], v[16:19]
	v_mfma_f32_16x16x32_bf16 v[16:19], v[136:139], v[222:225], v[16:19]
	v_mfma_f32_16x16x32_bf16 v[12:15], v[140:143], v[218:221], v[12:15]
	v_mfma_f32_16x16x32_bf16 v[12:15], v[144:147], v[222:225], v[12:15]
	v_mfma_f32_16x16x32_bf16 v[8:11], v[148:151], v[218:221], v[8:11]
	v_mfma_f32_16x16x32_bf16 v[8:11], v[152:155], v[222:225], v[8:11]
	v_mfma_f32_16x16x32_bf16 v[4:7], v[172:175], v[218:221], v[4:7]
	v_mfma_f32_16x16x32_bf16 v[4:7], v[176:179], v[222:225], v[4:7]
	s_setprio 0
	s_barrier
	s_add_i32 s66, s66, 2
	s_add_u32 s30, s30, 0x100
	s_addc_u32 s31, s31, 0
	s_add_u32 s64, s64, 0x100
	s_addc_u32 s65, s65, 0
	s_cmpk_gt_u32 s66, 0xa9
	s_cbranch_scc0 .LBB0_1672
	s_and_b64 vcc, exec, s[24:25]
	s_cbranch_vccz .LBB0_1675
	s_barrier

.LBB0_1703:
	ds_read_b128 v[136:139], v196
	ds_read_b128 v[140:143], v196 offset:1024
	ds_read_b128 v[144:147], v196 offset:2048
	ds_read_b128 v[148:151], v196 offset:3072
	ds_read_b128 v[152:155], v197
	ds_read_b128 v[176:179], v197 offset:1024
	ds_read_b128 v[180:183], v197 offset:2048
	ds_read_b128 v[184:187], v197 offset:3072
	s_add_u32 s8, s6, 0x100
	s_addc_u32 s9, s7, 0
	s_add_u32 s0, s65, s6
	s_addc_u32 s40, s66, s7
	s_cmpk_eq_i32 s67, 0xa8
	s_cselect_b32 s43, s50, s40
	s_cselect_b32 s40, 0, s8
	s_cselect_b32 s42, s51, s0
	s_cselect_b32 s0, 0, s9
	s_add_u32 s40, s16, s40
	s_addc_u32 s41, s17, s0
	s_mov_b32 m0, s58
	v_lshl_add_u64 v[226:227], v[132:133], 0, s[6:7]
	ds_read_b128 v[188:191], v198
	ds_read_b128 v[192:195], v198 offset:1024
	ds_read_b128 v[202:205], v198 offset:2048
	ds_read_b128 v[206:209], v198 offset:3072
	ds_read_b128 v[210:213], v198 offset:4096
	ds_read_b128 v[214:217], v198 offset:5120
	ds_read_b128 v[218:221], v198 offset:6144
	ds_read_b128 v[222:225], v198 offset:7168
	global_load_lds_dwordx4 v[226:227], off
	v_lshl_add_u64 v[226:227], v[134:135], 0, s[6:7]
	s_mov_b32 m0, s59
	s_nop 0
	global_load_lds_dwordx4 v[226:227], off
	s_waitcnt vmcnt(8)
	s_waitcnt lgkmcnt(0)
	s_setprio 1
	s_barrier
	v_mfma_f32_16x16x32_bf16 v[128:131], v[136:139], v[188:191], v[128:131]
	v_mfma_f32_16x16x32_bf16 v[128:131], v[140:143], v[192:195], v[128:131]
	v_mfma_f32_16x16x32_bf16 v[124:127], v[144:147], v[188:191], v[124:127]
	v_mfma_f32_16x16x32_bf16 v[124:127], v[148:151], v[192:195], v[124:127]
	v_mfma_f32_16x16x32_bf16 v[120:123], v[152:155], v[188:191], v[120:123]
	v_mfma_f32_16x16x32_bf16 v[120:123], v[176:179], v[192:195], v[120:123]
	v_mfma_f32_16x16x32_bf16 v[116:119], v[180:183], v[188:191], v[116:119]
	v_mfma_f32_16x16x32_bf16 v[116:119], v[184:187], v[192:195], v[116:119]
	v_mfma_f32_16x16x32_bf16 v[112:115], v[136:139], v[202:205], v[112:115]
	v_mfma_f32_16x16x32_bf16 v[112:115], v[140:143], v[206:209], v[112:115]
	v_mfma_f32_16x16x32_bf16 v[108:111], v[144:147], v[202:205], v[108:111]
	v_mfma_f32_16x16x32_bf16 v[108:111], v[148:151], v[206:209], v[108:111]
	v_mfma_f32_16x16x32_bf16 v[104:107], v[152:155], v[202:205], v[104:107]
	v_mfma_f32_16x16x32_bf16 v[104:107], v[176:179], v[206:209], v[104:107]
	v_mfma_f32_16x16x32_bf16 v[100:103], v[180:183], v[202:205], v[100:103]
	v_mfma_f32_16x16x32_bf16 v[100:103], v[184:187], v[206:209], v[100:103]
	v_mfma_f32_16x16x32_bf16 v[96:99], v[136:139], v[210:213], v[96:99]
	v_mfma_f32_16x16x32_bf16 v[96:99], v[140:143], v[214:217], v[96:99]
	v_mfma_f32_16x16x32_bf16 v[92:95], v[144:147], v[210:213], v[92:95]
	v_mfma_f32_16x16x32_bf16 v[92:95], v[148:151], v[214:217], v[92:95]
	v_mfma_f32_16x16x32_bf16 v[88:91], v[152:155], v[210:213], v[88:91]
	v_mfma_f32_16x16x32_bf16 v[88:91], v[176:179], v[214:217], v[88:91]
	v_mfma_f32_16x16x32_bf16 v[84:87], v[180:183], v[210:213], v[84:87]
	v_mfma_f32_16x16x32_bf16 v[84:87], v[184:187], v[214:217], v[84:87]
	v_mfma_f32_16x16x32_bf16 v[80:83], v[136:139], v[218:221], v[80:83]
	v_mfma_f32_16x16x32_bf16 v[80:83], v[140:143], v[222:225], v[80:83]
	v_mfma_f32_16x16x32_bf16 v[76:79], v[144:147], v[218:221], v[76:79]
	v_mfma_f32_16x16x32_bf16 v[76:79], v[148:151], v[222:225], v[76:79]
	v_mfma_f32_16x16x32_bf16 v[72:75], v[152:155], v[218:221], v[72:75]
	v_mfma_f32_16x16x32_bf16 v[72:75], v[176:179], v[222:225], v[72:75]
	v_mfma_f32_16x16x32_bf16 v[68:71], v[180:183], v[218:221], v[68:71]
	v_mfma_f32_16x16x32_bf16 v[68:71], v[184:187], v[222:225], v[68:71]
	s_setprio 0
	s_barrier
	s_mov_b32 m0, s60
	v_lshl_add_u64 v[226:227], s[40:41], 0, v[158:159]
	s_add_u32 s6, s40, 0x2b0000
	ds_read_b128 v[188:191], v198 offset:16384
	ds_read_b128 v[192:195], v198 offset:17408
	ds_read_b128 v[202:205], v198 offset:18432
	ds_read_b128 v[206:209], v198 offset:19456
	ds_read_b128 v[210:213], v198 offset:20480
	ds_read_b128 v[214:217], v198 offset:21504
	ds_read_b128 v[218:221], v198 offset:22528
	ds_read_b128 v[222:225], v198 offset:23552
	global_load_lds_dwordx4 v[226:227], off
	v_lshl_add_u64 v[228:229], s[40:41], 0, v[162:163]
	s_mov_b32 m0, s61
	s_addc_u32 s7, s41, 0
	global_load_lds_dwordx4 v[228:229], off
	v_lshl_add_u64 v[230:231], s[6:7], 0, v[158:159]
	s_mov_b32 m0, s62
	v_lshl_add_u64 v[232:233], s[42:43], 0, v[160:161]
	global_load_lds_dwordx4 v[230:231], off
	v_lshl_add_u64 v[230:231], s[6:7], 0, v[162:163]
	s_mov_b32 m0, s63
	s_nop 0
	global_load_lds_dwordx4 v[230:231], off
	v_lshl_add_u64 v[230:231], s[42:43], 0, v[156:157]
	s_mov_b32 m0, s46
	s_nop 0
	global_load_lds_dwordx4 v[230:231], off
	s_mov_b32 m0, s47
	s_nop 0
	global_load_lds_dwordx4 v[232:233], off
	s_waitcnt vmcnt(8)
	s_waitcnt lgkmcnt(0)
	s_setprio 1
	s_barrier
	v_mfma_f32_16x16x32_bf16 v[64:67], v[136:139], v[188:191], v[64:67]
	v_mfma_f32_16x16x32_bf16 v[64:67], v[140:143], v[192:195], v[64:67]
	v_mfma_f32_16x16x32_bf16 v[60:63], v[144:147], v[188:191], v[60:63]
	v_mfma_f32_16x16x32_bf16 v[60:63], v[148:151], v[192:195], v[60:63]
	v_mfma_f32_16x16x32_bf16 v[56:59], v[152:155], v[188:191], v[56:59]
	v_mfma_f32_16x16x32_bf16 v[56:59], v[176:179], v[192:195], v[56:59]
	v_mfma_f32_16x16x32_bf16 v[52:55], v[180:183], v[188:191], v[52:55]
	v_mfma_f32_16x16x32_bf16 v[52:55], v[184:187], v[192:195], v[52:55]
	v_mfma_f32_16x16x32_bf16 v[48:51], v[136:139], v[202:205], v[48:51]
	v_mfma_f32_16x16x32_bf16 v[48:51], v[140:143], v[206:209], v[48:51]
	v_mfma_f32_16x16x32_bf16 v[44:47], v[144:147], v[202:205], v[44:47]
	v_mfma_f32_16x16x32_bf16 v[44:47], v[148:151], v[206:209], v[44:47]
	v_mfma_f32_16x16x32_bf16 v[40:43], v[152:155], v[202:205], v[40:43]
	v_mfma_f32_16x16x32_bf16 v[40:43], v[176:179], v[206:209], v[40:43]
	v_mfma_f32_16x16x32_bf16 v[36:39], v[180:183], v[202:205], v[36:39]
	v_mfma_f32_16x16x32_bf16 v[36:39], v[184:187], v[206:209], v[36:39]
	v_mfma_f32_16x16x32_bf16 v[32:35], v[136:139], v[210:213], v[32:35]
	v_mfma_f32_16x16x32_bf16 v[32:35], v[140:143], v[214:217], v[32:35]
	v_mfma_f32_16x16x32_bf16 v[28:31], v[144:147], v[210:213], v[28:31]
	v_mfma_f32_16x16x32_bf16 v[28:31], v[148:151], v[214:217], v[28:31]
	v_mfma_f32_16x16x32_bf16 v[24:27], v[152:155], v[210:213], v[24:27]
	v_mfma_f32_16x16x32_bf16 v[24:27], v[176:179], v[214:217], v[24:27]
	v_mfma_f32_16x16x32_bf16 v[20:23], v[180:183], v[210:213], v[20:23]
	v_mfma_f32_16x16x32_bf16 v[20:23], v[184:187], v[214:217], v[20:23]
	v_mfma_f32_16x16x32_bf16 v[16:19], v[136:139], v[218:221], v[16:19]
	v_mfma_f32_16x16x32_bf16 v[16:19], v[140:143], v[222:225], v[16:19]
	v_mfma_f32_16x16x32_bf16 v[12:15], v[144:147], v[218:221], v[12:15]
	v_mfma_f32_16x16x32_bf16 v[12:15], v[148:151], v[222:225], v[12:15]
	v_mfma_f32_16x16x32_bf16 v[8:11], v[152:155], v[218:221], v[8:11]
	v_mfma_f32_16x16x32_bf16 v[8:11], v[176:179], v[222:225], v[8:11]
	v_mfma_f32_16x16x32_bf16 v[4:7], v[180:183], v[218:221], v[4:7]
	v_mfma_f32_16x16x32_bf16 v[4:7], v[184:187], v[222:225], v[4:7]
	s_setprio 0
	s_barrier
	s_add_i32 s0, 0, 0x18000
	s_add_i32 s68, 0, 0x1c000
	v_add_u32_e32 v148, s0, v3
	v_add_u32_e32 v170, s68, v3
	ds_read_b128 v[136:139], v148
	ds_read_b128 v[140:143], v148 offset:1024
	ds_read_b128 v[144:147], v148 offset:2048
	ds_read_b128 v[148:151], v148 offset:3072
	ds_read_b128 v[152:155], v170
	ds_read_b128 v[176:179], v170 offset:1024
	ds_read_b128 v[180:183], v170 offset:2048
	ds_read_b128 v[184:187], v170 offset:3072
	s_add_u32 s6, s42, 0x2b0000
	s_addc_u32 s7, s43, 0
	s_mov_b32 m0, s48
	v_lshl_add_u64 v[234:235], s[6:7], 0, v[156:157]
	ds_read_b128 v[188:191], v198 offset:32768
	ds_read_b128 v[192:195], v198 offset:33792
	ds_read_b128 v[202:205], v198 offset:34816
	ds_read_b128 v[206:209], v198 offset:35840
	ds_read_b128 v[210:213], v198 offset:36864
	ds_read_b128 v[214:217], v198 offset:37888
	ds_read_b128 v[218:221], v198 offset:38912
	ds_read_b128 v[222:225], v198 offset:39936
	global_load_lds_dwordx4 v[234:235], off
	v_lshl_add_u64 v[234:235], s[6:7], 0, v[160:161]
	s_mov_b32 m0, s49
	s_nop 0
	global_load_lds_dwordx4 v[234:235], off
	s_waitcnt vmcnt(8)
	s_waitcnt lgkmcnt(0)
	s_setprio 1
	s_barrier
	v_mfma_f32_16x16x32_bf16 v[128:131], v[136:139], v[188:191], v[128:131]
	v_mfma_f32_16x16x32_bf16 v[128:131], v[140:143], v[192:195], v[128:131]
	v_mfma_f32_16x16x32_bf16 v[124:127], v[144:147], v[188:191], v[124:127]
	v_mfma_f32_16x16x32_bf16 v[124:127], v[148:151], v[192:195], v[124:127]
	v_mfma_f32_16x16x32_bf16 v[120:123], v[152:155], v[188:191], v[120:123]
	v_mfma_f32_16x16x32_bf16 v[120:123], v[176:179], v[192:195], v[120:123]
	v_mfma_f32_16x16x32_bf16 v[116:119], v[180:183], v[188:191], v[116:119]
	v_mfma_f32_16x16x32_bf16 v[116:119], v[184:187], v[192:195], v[116:119]
	v_mfma_f32_16x16x32_bf16 v[112:115], v[136:139], v[202:205], v[112:115]
	v_mfma_f32_16x16x32_bf16 v[112:115], v[140:143], v[206:209], v[112:115]
	v_mfma_f32_16x16x32_bf16 v[108:111], v[144:147], v[202:205], v[108:111]
	v_mfma_f32_16x16x32_bf16 v[108:111], v[148:151], v[206:209], v[108:111]
	v_mfma_f32_16x16x32_bf16 v[104:107], v[152:155], v[202:205], v[104:107]
	v_mfma_f32_16x16x32_bf16 v[104:107], v[176:179], v[206:209], v[104:107]
	v_mfma_f32_16x16x32_bf16 v[100:103], v[180:183], v[202:205], v[100:103]
	v_mfma_f32_16x16x32_bf16 v[100:103], v[184:187], v[206:209], v[100:103]
	v_mfma_f32_16x16x32_bf16 v[96:99], v[136:139], v[210:213], v[96:99]
	v_mfma_f32_16x16x32_bf16 v[96:99], v[140:143], v[214:217], v[96:99]
	v_mfma_f32_16x16x32_bf16 v[92:95], v[144:147], v[210:213], v[92:95]
	v_mfma_f32_16x16x32_bf16 v[92:95], v[148:151], v[214:217], v[92:95]
	v_mfma_f32_16x16x32_bf16 v[88:91], v[152:155], v[210:213], v[88:91]
	v_mfma_f32_16x16x32_bf16 v[88:91], v[176:179], v[214:217], v[88:91]
	v_mfma_f32_16x16x32_bf16 v[84:87], v[180:183], v[210:213], v[84:87]
	v_mfma_f32_16x16x32_bf16 v[84:87], v[184:187], v[214:217], v[84:87]
	v_mfma_f32_16x16x32_bf16 v[80:83], v[136:139], v[218:221], v[80:83]
	v_mfma_f32_16x16x32_bf16 v[80:83], v[140:143], v[222:225], v[80:83]
	v_mfma_f32_16x16x32_bf16 v[76:79], v[144:147], v[218:221], v[76:79]
	v_mfma_f32_16x16x32_bf16 v[76:79], v[148:151], v[222:225], v[76:79]
	v_mfma_f32_16x16x32_bf16 v[72:75], v[152:155], v[218:221], v[72:75]
	v_mfma_f32_16x16x32_bf16 v[72:75], v[176:179], v[222:225], v[72:75]
	v_mfma_f32_16x16x32_bf16 v[68:71], v[180:183], v[218:221], v[68:71]
	v_mfma_f32_16x16x32_bf16 v[68:71], v[184:187], v[222:225], v[68:71]
	s_setprio 0
	s_barrier
	s_add_i32 s0, s0, s45
	v_lshl_add_u64 v[226:227], v[226:227], 0, s[28:29]
	s_mov_b32 m0, s0
	ds_read_b128 v[188:191], v198 offset:49152
	ds_read_b128 v[192:195], v198 offset:50176
	ds_read_b128 v[202:205], v198 offset:51200
	ds_read_b128 v[206:209], v198 offset:52224
	ds_read_b128 v[210:213], v198 offset:53248
	ds_read_b128 v[214:217], v198 offset:54272
	ds_read_b128 v[218:221], v198 offset:55296
	ds_read_b128 v[222:225], v198 offset:56320
	global_load_lds_dwordx4 v[226:227], off
	s_add_i32 m0, s0, 0x2000
	s_add_u32 s6, s40, 0x2b0080
	v_lshl_add_u64 v[226:227], v[228:229], 0, s[28:29]
	s_addc_u32 s7, s41, 0
	s_add_i32 s0, s68, s45
	global_load_lds_dwordx4 v[226:227], off
	v_lshl_add_u64 v[226:227], s[6:7], 0, v[158:159]
	s_mov_b32 m0, s0
	s_nop 0
	global_load_lds_dwordx4 v[226:227], off
	v_lshl_add_u64 v[226:227], s[6:7], 0, v[162:163]
	s_add_i32 m0, s0, 0x2000
	s_nop 0
	global_load_lds_dwordx4 v[226:227], off
	v_lshl_add_u64 v[226:227], v[230:231], 0, s[28:29]
	s_mov_b32 m0, s54
	s_nop 0
	global_load_lds_dwordx4 v[226:227], off
	v_lshl_add_u64 v[226:227], v[232:233], 0, s[28:29]
	s_mov_b32 m0, s55
	s_nop 0
	global_load_lds_dwordx4 v[226:227], off
	s_waitcnt vmcnt(8)
	s_waitcnt lgkmcnt(0)
	s_setprio 1
	s_barrier
	v_mfma_f32_16x16x32_bf16 v[64:67], v[136:139], v[188:191], v[64:67]
	v_mfma_f32_16x16x32_bf16 v[64:67], v[140:143], v[192:195], v[64:67]
	v_mfma_f32_16x16x32_bf16 v[60:63], v[144:147], v[188:191], v[60:63]
	v_mfma_f32_16x16x32_bf16 v[60:63], v[148:151], v[192:195], v[60:63]
	v_mfma_f32_16x16x32_bf16 v[56:59], v[152:155], v[188:191], v[56:59]
	v_mfma_f32_16x16x32_bf16 v[56:59], v[176:179], v[192:195], v[56:59]
	v_mfma_f32_16x16x32_bf16 v[52:55], v[180:183], v[188:191], v[52:55]
	v_mfma_f32_16x16x32_bf16 v[52:55], v[184:187], v[192:195], v[52:55]
	v_mfma_f32_16x16x32_bf16 v[48:51], v[136:139], v[202:205], v[48:51]
	v_mfma_f32_16x16x32_bf16 v[48:51], v[140:143], v[206:209], v[48:51]
	v_mfma_f32_16x16x32_bf16 v[44:47], v[144:147], v[202:205], v[44:47]
	v_mfma_f32_16x16x32_bf16 v[44:47], v[148:151], v[206:209], v[44:47]
	v_mfma_f32_16x16x32_bf16 v[40:43], v[152:155], v[202:205], v[40:43]
	v_mfma_f32_16x16x32_bf16 v[40:43], v[176:179], v[206:209], v[40:43]
	v_mfma_f32_16x16x32_bf16 v[36:39], v[180:183], v[202:205], v[36:39]
	v_mfma_f32_16x16x32_bf16 v[36:39], v[184:187], v[206:209], v[36:39]
	v_mfma_f32_16x16x32_bf16 v[32:35], v[136:139], v[210:213], v[32:35]
	v_mfma_f32_16x16x32_bf16 v[32:35], v[140:143], v[214:217], v[32:35]
	v_mfma_f32_16x16x32_bf16 v[28:31], v[144:147], v[210:213], v[28:31]
	v_mfma_f32_16x16x32_bf16 v[28:31], v[148:151], v[214:217], v[28:31]
	v_mfma_f32_16x16x32_bf16 v[24:27], v[152:155], v[210:213], v[24:27]
	v_mfma_f32_16x16x32_bf16 v[24:27], v[176:179], v[214:217], v[24:27]
	v_mfma_f32_16x16x32_bf16 v[20:23], v[180:183], v[210:213], v[20:23]
	v_mfma_f32_16x16x32_bf16 v[20:23], v[184:187], v[214:217], v[20:23]
	v_mfma_f32_16x16x32_bf16 v[16:19], v[136:139], v[218:221], v[16:19]
	v_mfma_f32_16x16x32_bf16 v[16:19], v[140:143], v[222:225], v[16:19]
	v_mfma_f32_16x16x32_bf16 v[12:15], v[144:147], v[218:221], v[12:15]
	v_mfma_f32_16x16x32_bf16 v[12:15], v[148:151], v[222:225], v[12:15]
	v_mfma_f32_16x16x32_bf16 v[8:11], v[152:155], v[218:221], v[8:11]
	v_mfma_f32_16x16x32_bf16 v[8:11], v[176:179], v[222:225], v[8:11]
	v_mfma_f32_16x16x32_bf16 v[4:7], v[180:183], v[218:221], v[4:7]
	v_mfma_f32_16x16x32_bf16 v[4:7], v[184:187], v[222:225], v[4:7]
	s_setprio 0
	s_barrier
	s_add_i32 s67, s67, 2
	s_cmpk_gt_u32 s67, 0xa9
	s_mov_b64 s[6:7], s[8:9]
	s_cbranch_scc0 .LBB0_1703
	s_and_b64 vcc, exec, s[30:31]
	s_cbranch_vccz .LBB0_1706
	s_barrier
